# nt hint also on the once-read x loads (P0), gelu-gate row loads (LRU pass 2) and gate loads of the GateA/GateB epilogues; on top of v28
# baseline (speedup 1.0000x reference)
; __device__ __forceinline__ unsigned cvt_pk_bf16(float lo, float hi) { unsigned r; asm volatile("v_cvt_pk_bf16_f32 %0, %1, %2" : "=v"(r) : "v"(lo), "v"(hi)); return r; }
; __global__ void __launch_bounds__(512, 2) fwd_mega(Args a) {
;     ...
;     for (int row = gw; row < M; row += NGW) {
;         const f32x4* xr = (const f32x4*)(a.x + (size_t)row * D) + lane; float s = 0.f;
; #pragma unroll
;         for (int j = 0; j < 4; ++j) { const f32x4 v = xr[64 * j]; s += (v[0] * v[0] + v[1] * v[1]) + (v[2] * v[2] + v[3] * v[3]);
;             u32x2 o; o.x = cvt_pk_bf16(v[0], v[1]); o.y = cvt_pk_bf16(v[2], v[3]); *((u32x2*)(XB + (size_t)row * D) + lane + 64 * j) = o; }
;         s = wave_sum(s); if (lane < 16) SS[(size_t)row * 16 + lane] = lane == 0 ? s : 0.f;
;     }
.LBB0_74:
	v_lshl_add_u64 v[20:21], s[64:65], 0, v[2:3]
	v_add_co_u32_e64 v32, s[4:5], s7, v20
	s_waitcnt lgkmcnt(0)
	global_load_dwordx4 v[16:19], v[4:5], off offset:-3072 nt
	v_addc_co_u32_e64 v33, s[4:5], 0, v21, s[4:5]
	s_waitcnt vmcnt(0)
	v_cvt_pk_bf16_f32 v20, v16, v17
	v_cvt_pk_bf16_f32 v21, v18, v19
	global_store_dwordx2 v[32:33], v[20:21], off sc1
	global_load_dwordx4 v[20:23], v[4:5], off offset:-2048 nt
	s_waitcnt vmcnt(0)
	v_cvt_pk_bf16_f32 v24, v20, v21
	v_cvt_pk_bf16_f32 v25, v22, v23
	global_store_dwordx2 v[32:33], v[24:25], off offset:512 sc1
	global_load_dwordx4 v[24:27], v[4:5], off offset:-1024 nt
	s_waitcnt vmcnt(0)
	v_cvt_pk_bf16_f32 v28, v24, v25
	v_cvt_pk_bf16_f32 v29, v26, v27
	global_store_dwordx2 v[32:33], v[28:29], off offset:1024 sc1
	global_load_dwordx4 v[28:31], v[4:5], off nt
	v_cmp_lt_i32_e64 s[4:5], v9, v8
	v_mul_f32_e32 v17, v17, v17
	v_mul_f32_e32 v19, v19, v19
	v_fmac_f32_e32 v17, v16, v16
	v_fmac_f32_e32 v19, v18, v18
	v_add_f32_e32 v16, v17, v19
	v_cndmask_b32_e64 v15, v7, v9, s[4:5]
	v_mul_f32_e32 v17, v21, v21
	v_mul_f32_e32 v18, v23, v23
	v_fmac_f32_e32 v17, v20, v20
	v_fmac_f32_e32 v18, v22, v22
	v_add_f32_e32 v17, v17, v18
	v_add_f32_e32 v16, v16, v17
	v_mul_f32_e32 v17, v25, v25
	v_mul_f32_e32 v18, v27, v27
	v_fmac_f32_e32 v17, v24, v24
	v_fmac_f32_e32 v18, v26, v26
	v_add_f32_e32 v17, v17, v18
	v_add_f32_e32 v16, v16, v17
	s_waitcnt vmcnt(0)
	v_mul_f32_e32 v17, v29, v29
	v_mul_f32_e32 v18, v31, v31
	v_fmac_f32_e32 v17, v28, v28
	v_fmac_f32_e32 v18, v30, v30
	v_add_f32_e32 v17, v17, v18
	v_lshlrev_b32_e32 v15, 2, v15
	v_add_f32_e32 v16, v16, v17
	ds_bpermute_b32 v15, v15, v16
	v_cmp_lt_i32_e64 s[4:5], v10, v8
	v_cvt_pk_bf16_f32 v18, v28, v29
	v_cvt_pk_bf16_f32 v19, v30, v31
	global_store_dwordx2 v[32:33], v[18:19], off offset:1536 sc1
	s_waitcnt lgkmcnt(0)
	v_add_f32_e32 v15, v16, v15
	v_cndmask_b32_e64 v17, v7, v10, s[4:5]
	v_lshlrev_b32_e32 v17, 2, v17
	ds_bpermute_b32 v16, v17, v15
	v_cmp_lt_i32_e64 s[4:5], v11, v8
	s_waitcnt lgkmcnt(0)
	v_add_f32_e32 v15, v15, v16
	v_cndmask_b32_e64 v17, v7, v11, s[4:5]
	v_lshlrev_b32_e32 v17, 2, v17
	ds_bpermute_b32 v16, v17, v15
	v_cmp_lt_i32_e64 s[4:5], v12, v8
	s_waitcnt lgkmcnt(0)
	v_add_f32_e32 v15, v15, v16
	v_cndmask_b32_e64 v17, v7, v12, s[4:5]
	v_lshlrev_b32_e32 v17, 2, v17
	ds_bpermute_b32 v16, v17, v15
	v_cmp_lt_i32_e64 s[4:5], v13, v8
	s_waitcnt lgkmcnt(0)
	v_add_f32_e32 v15, v15, v16
	v_cndmask_b32_e64 v17, v7, v13, s[4:5]
	v_lshlrev_b32_e32 v17, 2, v17
	ds_bpermute_b32 v16, v17, v15
	v_cmp_lt_i32_e64 s[4:5], v14, v8
	s_waitcnt lgkmcnt(0)
	v_add_f32_e32 v15, v15, v16
	v_cndmask_b32_e64 v17, v7, v14, s[4:5]
	v_lshlrev_b32_e32 v16, 2, v17
	ds_bpermute_b32 v16, v16, v15
	s_and_saveexec_b64 s[4:5], vcc
	s_cbranch_execz .LBB0_73
	s_waitcnt lgkmcnt(0)
	v_add_f32_e32 v15, v15, v16
	v_lshl_add_u64 v[18:19], s[64:65], 0, v[0:1]
	v_cndmask_b32_e64 v15, 0, v15, s[0:1]
	global_store_dword v[18:19], v15, off sc1
	s_branch .LBB0_73

; #define LAS __attribute__((address_space(3)))
; __device__ __forceinline__ unsigned cvt_pk_bf16(float lo, float hi) { unsigned r; asm volatile("v_cvt_pk_bf16_f32 %0, %1, %2" : "=v"(r) : "v"(lo), "v"(hi)); return r; }
; __device__ __forceinline__ float bflo(unsigned w) { return __uint_as_float(w << 16); }
; __device__ __forceinline__ float bfhi(unsigned w) { return __uint_as_float(w & 0xffff0000u); }
; template <int PASS> __device__ __forceinline__ void lru_wave_item(LAS unsigned char* lds, LAS unsigned char* vw, int b, int c, int h, const MixP& p, int lane, float (&Hrun)[8], bool cont) {
;     ...
;     for (int st = 0; st < CT / 16; ++st) {
;         const int s0 = c * CT + 16 * st;
;         u32x4 ur[7];
;         {
;             const int sb = s0 + 4 * fq - 3;
; #pragma unroll
;             for (int r = 0; r < 7; ++r) ur[r] = *(const u32x4*)(ub + (size_t)max(sb + r, 0) * P1W);
;         }
;         if (s0 == 0 && fq == 0) {
; #pragma unroll
;             for (int r = 0; r < 3; ++r) ur[r] = (u32x4){0u, 0u, 0u, 0u};
;         }
; #pragma unroll
;         for (int jj = 0; jj < 4; ++jj) {
;             f32x2 o[4] = {bv[0], bv[1], bv[2], bv[3]};
; #pragma unroll
;             for (int k = 0; k < 4; ++k) { const u32x4 uk = ur[jj + k];
;                 o[0] = wv[k][0] * (f32x2){bflo(uk.x), bfhi(uk.x)} + o[0]; o[1] = wv[k][1] * (f32x2){bflo(uk.y), bfhi(uk.y)} + o[1];
;                 o[2] = wv[k][2] * (f32x2){bflo(uk.z), bfhi(uk.z)} + o[2]; o[3] = wv[k][3] * (f32x2){bflo(uk.w), bfhi(uk.w)} + o[3]; }
;             { u32x4 w; w.x = cvt_pk_bf16(o[0].x, o[0].y); w.y = cvt_pk_bf16(o[1].x, o[1].y); w.z = cvt_pk_bf16(o[2].x, o[2].y); w.w = cvt_pk_bf16(o[3].x, o[3].y);
;               *(LAS u32x4*)(vw + (4 * fq + jj) * WROW + cg * 16) = w; }
;     ...
;                 const u32x4 g = *(const u32x4*)(p.P2 + row * P2W + h * 128 + cg * 8);
.LBB0_818:
	s_or_b32 s22, s19, s11
	v_add_u32_e32 v0, s22, v224
	v_max_i32_e32 v2, 0, v0
	v_mad_u64_u32 v[2:3], s[20:21], v2, s82, v[182:183]
	global_load_dwordx4 v[74:77], v[2:3], off offset:1024
	v_max_i32_e32 v2, -1, v0
	v_add_u32_e32 v2, 1, v2
	v_mad_u64_u32 v[2:3], s[20:21], v2, s82, v[182:183]
	global_load_dwordx4 v[78:81], v[2:3], off offset:1024
	v_or_b32_e32 v2, 2, v0
	v_max_i32_e32 v2, 0, v2
	v_mad_u64_u32 v[2:3], s[20:21], v2, s82, v[182:183]
	global_load_dwordx4 v[82:85], v[2:3], off offset:1024
	v_or_b32_e32 v2, s22, v223
	v_max_i32_e32 v2, 0, v2
	v_mad_u64_u32 v[2:3], s[20:21], v2, s82, v[182:183]
	global_load_dwordx4 v[70:73], v[2:3], off offset:1024
	v_max_i32_e32 v2, -4, v0
	v_add_u32_e32 v2, 4, v2
	v_mad_u64_u32 v[2:3], s[20:21], v2, s82, v[182:183]
	global_load_dwordx4 v[66:69], v[2:3], off offset:1024
	v_max_i32_e32 v2, -5, v0
	v_add_u32_e32 v2, 5, v2
	v_mad_u64_u32 v[2:3], s[20:21], v2, s82, v[182:183]
	global_load_dwordx4 v[6:9], v[2:3], off offset:1024
	v_max_i32_e32 v0, -6, v0
	v_add_u32_e32 v0, 6, v0
	v_mad_u64_u32 v[2:3], s[20:21], v0, s82, v[182:183]
	global_load_dwordx4 v[2:5], v[2:3], off offset:1024
	s_cmp_eq_u32 s22, 0
	s_cselect_b64 s[20:21], -1, 0
	s_and_b64 s[20:21], s[20:21], s[4:5]
	s_or_b32 s19, s19, s18
	s_and_b64 vcc, exec, s[12:13]
	s_mov_b64 s[12:13], 0
	v_or_b32_e32 v96, s19, v203
	v_mad_i64_i32 v[240:241], s[98:99], v96, s83, v[152:153]
	global_load_dwordx4 v[240:243], v[240:241], off nt
	v_or_b32_e32 v96, s19, v225
	v_mad_i64_i32 v[244:245], s[98:99], v96, s83, v[152:153]
	global_load_dwordx4 v[244:247], v[244:245], off nt
	v_or_b32_e32 v96, s19, v226
	v_mad_i64_i32 v[248:249], s[98:99], v96, s83, v[152:153]
	global_load_dwordx4 v[248:251], v[248:249], off nt
	v_or_b32_e32 v96, s19, v227
	v_mad_i64_i32 v[206:207], s[98:99], v96, s83, v[152:153]
	global_load_dwordx2 v[210:211], v[206:207], off offset:8 nt
	global_load_dwordx2 v[206:207], v[206:207], off nt
	s_add_i32 s100, s22, 16
	v_add_u32_e32 v96, s100, v224
	v_max_i32_e32 v97, 0, v96
	v_mad_u64_u32 v[98:99], s[98:99], v97, s82, v[182:183]
	global_load_dword v237, v[98:99], off offset:1024
	v_add_u32_e32 v97, 1, v96
	v_max_i32_e32 v97, 0, v97
	v_mad_u64_u32 v[98:99], s[98:99], v97, s82, v[182:183]
	global_load_dword v237, v[98:99], off offset:1024
	v_add_u32_e32 v97, 2, v96
	v_max_i32_e32 v97, 0, v97
	v_mad_u64_u32 v[98:99], s[98:99], v97, s82, v[182:183]
	global_load_dword v237, v[98:99], off offset:1024
	v_add_u32_e32 v97, 3, v96
	v_max_i32_e32 v97, 0, v97
	v_mad_u64_u32 v[98:99], s[98:99], v97, s82, v[182:183]
	global_load_dword v237, v[98:99], off offset:1024
	v_add_u32_e32 v97, 4, v96
	v_max_i32_e32 v97, 0, v97
	v_mad_u64_u32 v[98:99], s[98:99], v97, s82, v[182:183]
	global_load_dword v237, v[98:99], off offset:1024
	v_add_u32_e32 v97, 5, v96
	v_max_i32_e32 v97, 0, v97
	v_mad_u64_u32 v[98:99], s[98:99], v97, s82, v[182:183]
	global_load_dword v237, v[98:99], off offset:1024
	v_add_u32_e32 v97, 6, v96
	v_max_i32_e32 v97, 0, v97
	v_mad_u64_u32 v[98:99], s[98:99], v97, s82, v[182:183]
	global_load_dword v237, v[98:99], off offset:1024
	s_waitcnt vmcnt(18)
	v_cndmask_b32_e64 v0, v77, 0, s[20:21]
	v_cndmask_b32_e64 v77, v75, 0, s[20:21]
	v_cndmask_b32_e64 v75, v74, 0, s[20:21]
	v_cndmask_b32_e64 v86, v76, 0, s[20:21]
	v_lshlrev_b32_e32 v74, 16, v75
	s_waitcnt vmcnt(17)
	v_cndmask_b32_e64 v89, v79, 0, s[20:21]
	v_cndmask_b32_e64 v91, v78, 0, s[20:21]
	v_and_b32_e32 v75, 0xffff0000, v75
	v_lshlrev_b32_e32 v76, 16, v77
	v_and_b32_e32 v77, 0xffff0000, v77
	v_cndmask_b32_e64 v88, v81, 0, s[20:21]
	v_cndmask_b32_e64 v87, v80, 0, s[20:21]
	s_waitcnt vmcnt(16)
	v_cndmask_b32_e64 v102, v83, 0, s[20:21]
	v_cndmask_b32_e64 v98, v82, 0, s[20:21]
	s_waitcnt lgkmcnt(13)
	v_pk_fma_f32 v[74:75], v[26:27], v[74:75], v[58:59]
	v_pk_fma_f32 v[76:77], v[28:29], v[76:77], v[60:61]
	v_lshlrev_b32_e32 v78, 16, v86
	v_and_b32_e32 v79, 0xffff0000, v86
	v_lshlrev_b32_e32 v80, 16, v0
	v_and_b32_e32 v81, 0xffff0000, v0
	v_lshlrev_b32_e32 v90, 16, v91
	v_and_b32_e32 v91, 0xffff0000, v91
	v_lshlrev_b32_e32 v92, 16, v89
	v_and_b32_e32 v93, 0xffff0000, v89
	v_cndmask_b32_e64 v100, v85, 0, s[20:21]
	v_cndmask_b32_e64 v101, v84, 0, s[20:21]
	s_waitcnt lgkmcnt(12)
	v_pk_fma_f32 v[78:79], v[30:31], v[78:79], v[62:63]
	v_pk_fma_f32 v[80:81], v[32:33], v[80:81], v[64:65]
	v_pk_fma_f32 v[82:83], v[34:35], v[90:91], v[74:75]
	v_pk_fma_f32 v[84:85], v[36:37], v[92:93], v[76:77]
	v_lshlrev_b32_e32 v94, 16, v87
	v_and_b32_e32 v95, 0xffff0000, v87
	v_lshlrev_b32_e32 v96, 16, v88
	v_and_b32_e32 v97, 0xffff0000, v88
	v_lshlrev_b32_e32 v74, 16, v98
	v_and_b32_e32 v75, 0xffff0000, v98
	v_lshlrev_b32_e32 v76, 16, v102
	v_and_b32_e32 v77, 0xffff0000, v102
	v_pk_fma_f32 v[86:87], v[38:39], v[94:95], v[78:79]
	v_pk_fma_f32 v[88:89], v[40:41], v[96:97], v[80:81]
	v_pk_fma_f32 v[98:99], v[42:43], v[74:75], v[82:83]
	v_pk_fma_f32 v[84:85], v[44:45], v[76:77], v[84:85]
	v_lshlrev_b32_e32 v78, 16, v101
	v_and_b32_e32 v79, 0xffff0000, v101
	v_lshlrev_b32_e32 v80, 16, v100
	v_and_b32_e32 v81, 0xffff0000, v100
	s_waitcnt vmcnt(15)
	v_lshlrev_b32_e32 v82, 16, v70
	v_and_b32_e32 v83, 0xffff0000, v70
	v_lshlrev_b32_e32 v70, 16, v71
	v_and_b32_e32 v71, 0xffff0000, v71
	v_pk_fma_f32 v[86:87], v[46:47], v[78:79], v[86:87]
	v_pk_fma_f32 v[88:89], v[48:49], v[80:81], v[88:89]
	v_pk_fma_f32 v[100:101], v[52:53], v[70:71], v[84:85]
	v_lshlrev_b32_e32 v84, 16, v72
	v_and_b32_e32 v85, 0xffff0000, v72
	v_lshlrev_b32_e32 v72, 16, v73
	v_and_b32_e32 v73, 0xffff0000, v73
	v_pk_fma_f32 v[98:99], v[50:51], v[82:83], v[98:99]
	v_pk_fma_f32 v[102:103], v[54:55], v[84:85], v[86:87]
	v_pk_fma_f32 v[104:105], v[56:57], v[72:73], v[88:89]
	v_cvt_pk_bf16_f32 v86, v98, v99
	v_cvt_pk_bf16_f32 v87, v100, v101
	v_cvt_pk_bf16_f32 v88, v102, v103
	s_waitcnt vmcnt(14)
; #define LAS __attribute__((address_space(3)))
; __device__ __forceinline__ unsigned cvt_pk_bf16(float lo, float hi) { unsigned r; asm volatile("v_cvt_pk_bf16_f32 %0, %1, %2" : "=v"(r) : "v"(lo), "v"(hi)); return r; }
; __device__ __forceinline__ float bflo(unsigned w) { return __uint_as_float(w << 16); }
; __device__ __forceinline__ float bfhi(unsigned w) { return __uint_as_float(w & 0xffff0000u); }
; template <int PASS> __device__ __forceinline__ void lru_wave_item(LAS unsigned char* lds, LAS unsigned char* vw, int b, int c, int h, const MixP& p, int lane, float (&Hrun)[8], bool cont) {
;     ...
; #pragma unroll
;         for (int jj = 0; jj < 4; ++jj) {
;             f32x2 o[4] = {bv[0], bv[1], bv[2], bv[3]};
; #pragma unroll
;             for (int k = 0; k < 4; ++k) { const u32x4 uk = ur[jj + k];
;                 o[0] = wv[k][0] * (f32x2){bflo(uk.x), bfhi(uk.x)} + o[0]; o[1] = wv[k][1] * (f32x2){bflo(uk.y), bfhi(uk.y)} + o[1];
;                 o[2] = wv[k][2] * (f32x2){bflo(uk.z), bfhi(uk.z)} + o[2]; o[3] = wv[k][3] * (f32x2){bflo(uk.w), bfhi(uk.w)} + o[3]; }
;             { u32x4 w; w.x = cvt_pk_bf16(o[0].x, o[0].y); w.y = cvt_pk_bf16(o[1].x, o[1].y); w.z = cvt_pk_bf16(o[2].x, o[2].y); w.w = cvt_pk_bf16(o[3].x, o[3].y);
;               *(LAS u32x4*)(vw + (4 * fq + jj) * WROW + cg * 16) = w; }
;         }
;         f32x4 aR[8], aI[8];
;         bf16x8 af[4];
;         {
; #pragma unroll
;             for (int kk = 0; kk < 4; ++kk) af[kk] = *(const LAS bf16x8*)(vw + fr * WROW + kk * 64 + fq * 16);
; #pragma unroll
;             for (int n = 0; n < 8; ++n) {
;                 aR[n] = (f32x4){0.f, 0.f, 0.f, 0.f}; aI[n] = (f32x4){0.f, 0.f, 0.f, 0.f};
; #pragma unroll
;                 for (int kk = 0; kk < 4; ++kk) {
;                     const bf16x8 ba = *(const LAS bf16x8*)(lds + WA_OFF + (16 * n + fr) * WROW + kk * 64 + fq * 16);
;                     const bf16x8 bx = *(const LAS bf16x8*)(lds + WX_OFF + (16 * n + fr) * WROW + kk * 64 + fq * 16);
;                     aR[n] = __builtin_amdgcn_mfma_f32_16x16x32_bf16(af[kk], ba, aR[n], 0, 0, 0);
;                     aI[n] = __builtin_amdgcn_mfma_f32_16x16x32_bf16(af[kk], bx, aI[n], 0, 0, 0);
;                 }
;             }
	v_lshlrev_b32_e32 v98, 16, v68
	v_cvt_pk_bf16_f32 v89, v104, v105
	ds_write_b128 v229, v[86:89]
	v_pk_fma_f32 v[86:87], v[26:27], v[90:91], v[58:59]
	v_pk_fma_f32 v[88:89], v[28:29], v[92:93], v[60:61]
	v_pk_fma_f32 v[90:91], v[30:31], v[94:95], v[62:63]
	v_pk_fma_f32 v[92:93], v[32:33], v[96:97], v[64:65]
	v_pk_fma_f32 v[86:87], v[34:35], v[74:75], v[86:87]
	v_pk_fma_f32 v[88:89], v[36:37], v[76:77], v[88:89]
	v_pk_fma_f32 v[90:91], v[38:39], v[78:79], v[90:91]
	v_pk_fma_f32 v[92:93], v[40:41], v[80:81], v[92:93]
	v_pk_fma_f32 v[86:87], v[42:43], v[82:83], v[86:87]
	v_pk_fma_f32 v[88:89], v[44:45], v[70:71], v[88:89]
	v_pk_fma_f32 v[90:91], v[46:47], v[84:85], v[90:91]
	v_pk_fma_f32 v[92:93], v[48:49], v[72:73], v[92:93]
	v_lshlrev_b32_e32 v94, 16, v66
	v_and_b32_e32 v95, 0xffff0000, v66
	v_lshlrev_b32_e32 v96, 16, v67
	v_and_b32_e32 v97, 0xffff0000, v67
	v_and_b32_e32 v99, 0xffff0000, v68
	v_lshlrev_b32_e32 v100, 16, v69
	v_and_b32_e32 v101, 0xffff0000, v69
	v_pk_fma_f32 v[86:87], v[50:51], v[94:95], v[86:87]
	v_pk_fma_f32 v[88:89], v[52:53], v[96:97], v[88:89]
	v_pk_fma_f32 v[90:91], v[54:55], v[98:99], v[90:91]
	v_pk_fma_f32 v[92:93], v[56:57], v[100:101], v[92:93]
	v_cvt_pk_bf16_f32 v66, v86, v87
	v_cvt_pk_bf16_f32 v67, v88, v89
	v_cvt_pk_bf16_f32 v68, v90, v91
	s_waitcnt vmcnt(13)
	v_lshlrev_b32_e32 v86, 16, v8
	v_cvt_pk_bf16_f32 v69, v92, v93
	ds_write_b128 v229, v[66:69] offset:272
	v_pk_fma_f32 v[66:67], v[26:27], v[74:75], v[58:59]
	v_pk_fma_f32 v[68:69], v[28:29], v[76:77], v[60:61]
	v_pk_fma_f32 v[74:75], v[30:31], v[78:79], v[62:63]
	v_pk_fma_f32 v[76:77], v[32:33], v[80:81], v[64:65]
	v_pk_fma_f32 v[66:67], v[34:35], v[82:83], v[66:67]
	v_pk_fma_f32 v[68:69], v[36:37], v[70:71], v[68:69]
	v_pk_fma_f32 v[74:75], v[38:39], v[84:85], v[74:75]
	v_pk_fma_f32 v[76:77], v[40:41], v[72:73], v[76:77]
	v_pk_fma_f32 v[66:67], v[42:43], v[94:95], v[66:67]
	v_pk_fma_f32 v[68:69], v[44:45], v[96:97], v[68:69]
	v_pk_fma_f32 v[74:75], v[46:47], v[98:99], v[74:75]
	v_pk_fma_f32 v[76:77], v[48:49], v[100:101], v[76:77]
	v_lshlrev_b32_e32 v78, 16, v6
	v_and_b32_e32 v79, 0xffff0000, v6
	v_lshlrev_b32_e32 v80, 16, v7
	v_and_b32_e32 v81, 0xffff0000, v7
	v_and_b32_e32 v87, 0xffff0000, v8
	v_lshlrev_b32_e32 v88, 16, v9
	v_and_b32_e32 v89, 0xffff0000, v9
	v_pk_fma_f32 v[66:67], v[50:51], v[78:79], v[66:67]
	v_pk_fma_f32 v[68:69], v[52:53], v[80:81], v[68:69]
	v_pk_fma_f32 v[74:75], v[54:55], v[86:87], v[74:75]
	v_pk_fma_f32 v[76:77], v[56:57], v[88:89], v[76:77]
	v_cvt_pk_bf16_f32 v6, v66, v67
	v_cvt_pk_bf16_f32 v7, v68, v69
	v_cvt_pk_bf16_f32 v8, v74, v75
	v_pk_fma_f32 v[66:67], v[30:31], v[84:85], v[62:63]
	v_cvt_pk_bf16_f32 v9, v76, v77
	ds_write_b128 v229, v[6:9] offset:544
	v_pk_fma_f32 v[6:7], v[26:27], v[82:83], v[58:59]
	v_pk_fma_f32 v[8:9], v[28:29], v[70:71], v[60:61]
	v_pk_fma_f32 v[68:69], v[32:33], v[72:73], v[64:65]
	v_pk_fma_f32 v[6:7], v[34:35], v[94:95], v[6:7]
	v_pk_fma_f32 v[8:9], v[36:37], v[96:97], v[8:9]
	v_pk_fma_f32 v[66:67], v[38:39], v[98:99], v[66:67]
	v_pk_fma_f32 v[68:69], v[40:41], v[100:101], v[68:69]
	v_pk_fma_f32 v[6:7], v[42:43], v[78:79], v[6:7]
	v_pk_fma_f32 v[8:9], v[44:45], v[80:81], v[8:9]
	v_pk_fma_f32 v[70:71], v[46:47], v[86:87], v[66:67]
	v_pk_fma_f32 v[66:67], v[48:49], v[88:89], v[68:69]
	s_waitcnt vmcnt(12)
	v_lshlrev_b32_e32 v68, 16, v2
	v_and_b32_e32 v69, 0xffff0000, v2
	v_lshlrev_b32_e32 v2, 16, v3
	v_and_b32_e32 v3, 0xffff0000, v3
	v_pk_fma_f32 v[6:7], v[50:51], v[68:69], v[6:7]
	v_pk_fma_f32 v[2:3], v[52:53], v[2:3], v[8:9]
	v_lshlrev_b32_e32 v8, 16, v4
	v_and_b32_e32 v9, 0xffff0000, v4
	v_lshlrev_b32_e32 v4, 16, v5
	v_and_b32_e32 v5, 0xffff0000, v5
	v_pk_fma_f32 v[8:9], v[54:55], v[8:9], v[70:71]
	v_pk_fma_f32 v[66:67], v[56:57], v[4:5], v[66:67]
	v_cvt_pk_bf16_f32 v4, v6, v7
	v_cvt_pk_bf16_f32 v5, v2, v3
	v_cvt_pk_bf16_f32 v6, v8, v9
	v_and_or_b32 v0, v213, 64, v202
	v_cvt_pk_bf16_f32 v7, v66, v67
	ds_write_b128 v229, v[4:7] offset:816
	ds_read_b128 v[118:121], v230
	ds_read_b128 v[90:93], v230 offset:64
	ds_read_b128 v[6:9], v230 offset:128
	ds_read_b128 v[2:5], v230 offset:192
	ds_read_b128 v[66:69], v231
	ds_read_b128 v[70:73], v231 offset:34816
	ds_read_b128 v[74:77], v231 offset:64
	ds_read_b128 v[78:81], v231 offset:34880
	s_waitcnt lgkmcnt(3)
	v_mfma_f32_16x16x32_bf16 v[66:69], v[118:121], v[66:69], 0
	v_lshlrev_b32_e32 v0, 2, v0
	s_waitcnt lgkmcnt(2)
	v_mfma_f32_16x16x32_bf16 v[70:73], v[118:121], v[70:73], 0
	s_waitcnt lgkmcnt(1)
	v_mfma_f32_16x16x32_bf16 v[66:69], v[90:93], v[74:77], v[66:69]
	s_waitcnt lgkmcnt(0)
	v_mfma_f32_16x16x32_bf16 v[70:73], v[90:93], v[78:81], v[70:73]
	ds_read_b128 v[74:77], v231 offset:128
	ds_read_b128 v[78:81], v231 offset:34944
	s_waitcnt lgkmcnt(1)
	v_mfma_f32_16x16x32_bf16 v[66:69], v[6:9], v[74:77], v[66:69]
	s_waitcnt lgkmcnt(0)
	v_mfma_f32_16x16x32_bf16 v[70:73], v[6:9], v[78:81], v[70:73]
	ds_read_b128 v[74:77], v231 offset:192
	ds_read_b128 v[78:81], v231 offset:35008
	s_waitcnt lgkmcnt(1)
	v_mfma_f32_16x16x32_bf16 v[134:137], v[2:5], v[74:77], v[66:69]
	s_waitcnt lgkmcnt(0)
	v_mfma_f32_16x16x32_bf16 v[130:133], v[2:5], v[78:81], v[70:73]
	s_nop 0
	ds_read_b128 v[66:69], v231 offset:4352
	s_nop 0
	ds_read_b128 v[70:73], v231 offset:39168
	ds_read_b128 v[74:77], v231 offset:4416
	ds_read_b128 v[78:81], v231 offset:39232
	v_add_f32_e32 v134, v158, v134
	s_waitcnt lgkmcnt(3)
	v_mfma_f32_16x16x32_bf16 v[66:69], v[118:121], v[66:69], 0
	v_add_f32_e32 v135, v158, v135
	v_mul_f32_e32 v134, 0xbfb8aa3b, v134
	v_mul_f32_e32 v135, 0xbfb8aa3b, v135
	s_waitcnt lgkmcnt(2)
	v_mfma_f32_16x16x32_bf16 v[70:73], v[118:121], v[70:73], 0
	v_exp_f32_e32 v134, v134
	v_exp_f32_e32 v135, v135
	v_add_f32_e32 v130, v160, v130
	s_waitcnt lgkmcnt(1)
; #define LAS __attribute__((address_space(3)))
; __device__ __forceinline__ float fsig2(float x) { return __builtin_amdgcn_rcpf(1.0f + __builtin_amdgcn_exp2f(-LOG2E * x)); }
; template <int PASS> __device__ __forceinline__ void lru_wave_item(LAS unsigned char* lds, LAS unsigned char* vw, int b, int c, int h, const MixP& p, int lane, float (&Hrun)[8], bool cont) {
;     ...
; #pragma unroll
;             for (int n = 0; n < 8; ++n) {
;                 aR[n] = (f32x4){0.f, 0.f, 0.f, 0.f}; aI[n] = (f32x4){0.f, 0.f, 0.f, 0.f};
; #pragma unroll
;                 for (int kk = 0; kk < 4; ++kk) {
;                     const bf16x8 ba = *(const LAS bf16x8*)(lds + WA_OFF + (16 * n + fr) * WROW + kk * 64 + fq * 16);
;                     const bf16x8 bx = *(const LAS bf16x8*)(lds + WX_OFF + (16 * n + fr) * WROW + kk * 64 + fq * 16);
;                     aR[n] = __builtin_amdgcn_mfma_f32_16x16x32_bf16(af[kk], ba, aR[n], 0, 0, 0);
;                     aI[n] = __builtin_amdgcn_mfma_f32_16x16x32_bf16(af[kk], bx, aI[n], 0, 0, 0);
;                 }
;             }
;         }
; #pragma unroll
;         for (int n = 0; n < 8; ++n) {
;             const f32x4 aVn = __builtin_amdgcn_mfma_f32_16x16x32_bf16(af[n >> 1], idf[n & 1], (f32x4){0.f, 0.f, 0.f, 0.f}, 0, 0, 0);
;             float av[4], bxv[4];
; #pragma unroll
;             for (int j = 0; j < 4; ++j) {
;                 const float r = fsig2(aR[n][j] + pba[n]), ig = fsig2(aI[n][j] + pbx[n]);
;                 const float a = __builtin_amdgcn_exp2f(r * pk8[n]), mult = __builtin_amdgcn_sqrtf(fmaxf(1.0f - a * a, 0.f));
;                 av[j] = a; bxv[j] = mult * ig * aVn[j];
;             }
	v_mfma_f32_16x16x32_bf16 v[66:69], v[90:93], v[74:77], v[66:69]
	v_add_f32_e32 v134, 1.0, v134
	v_add_f32_e32 v135, 1.0, v135
	v_rcp_f32_e32 v134, v134
	s_waitcnt lgkmcnt(0)
	v_mfma_f32_16x16x32_bf16 v[70:73], v[90:93], v[78:81], v[70:73]
	ds_read_b128 v[74:77], v231 offset:4480
	ds_read_b128 v[78:81], v231 offset:39296
	v_rcp_f32_e32 v135, v135
	v_mul_f32_e32 v134, v162, v134
	s_waitcnt lgkmcnt(1)
	v_mfma_f32_16x16x32_bf16 v[66:69], v[6:9], v[74:77], v[66:69]
	v_add_f32_e32 v131, v160, v131
	v_mul_f32_e32 v135, v162, v135
	v_mul_f32_e32 v130, 0xbfb8aa3b, v130
	s_waitcnt lgkmcnt(0)
	v_mfma_f32_16x16x32_bf16 v[70:73], v[6:9], v[78:81], v[70:73]
	ds_read_b128 v[74:77], v231 offset:4544
	ds_read_b128 v[78:81], v231 offset:39360
	v_exp_f32_e32 v236, v134
	v_mul_f32_e32 v131, 0xbfb8aa3b, v131
	s_waitcnt lgkmcnt(1)
	v_mfma_f32_16x16x32_bf16 v[126:129], v[2:5], v[74:77], v[66:69]
	v_exp_f32_e32 v130, v130
	v_exp_f32_e32 v131, v131
	v_fma_f32 v134, -v236, v236, 1.0
	s_waitcnt lgkmcnt(0)
	v_mfma_f32_16x16x32_bf16 v[122:125], v[2:5], v[78:81], v[70:73]
	ds_read_b128 v[66:69], v231 offset:8704
	s_nop 1
	ds_read_b128 v[70:73], v231 offset:43520
	ds_read_b128 v[74:77], v231 offset:8768
	ds_read_b128 v[78:81], v231 offset:43584
	v_add_f32_e32 v130, 1.0, v130
	s_waitcnt lgkmcnt(3)
	v_mfma_f32_16x16x32_bf16 v[66:69], v[118:121], v[66:69], 0
	v_max_f32_e32 v134, 0, v134
	v_add_f32_e32 v131, 1.0, v131
	v_rcp_f32_e32 v130, v130
	s_waitcnt lgkmcnt(2)
	v_mfma_f32_16x16x32_bf16 v[70:73], v[118:121], v[70:73], 0
	v_sqrt_f32_e32 v134, v134
	v_rcp_f32_e32 v131, v131
	v_add_f32_e32 v133, v160, v133
	s_waitcnt lgkmcnt(1)
	v_mfma_f32_16x16x32_bf16 v[66:69], v[90:93], v[74:77], v[66:69]
	v_mul_f32_e32 v133, 0xbfb8aa3b, v133
	v_exp_f32_e32 v133, v133
	v_add_f32_e32 v132, v160, v132
	s_waitcnt lgkmcnt(0)
	v_mfma_f32_16x16x32_bf16 v[70:73], v[90:93], v[78:81], v[70:73]
	ds_read_b128 v[74:77], v231 offset:8832
	ds_read_b128 v[78:81], v231 offset:43648
	v_mul_f32_e32 v132, 0xbfb8aa3b, v132
	v_exp_f32_e32 v132, v132
	s_waitcnt lgkmcnt(1)
	v_mfma_f32_16x16x32_bf16 v[66:69], v[6:9], v[74:77], v[66:69]
	v_add_f32_e32 v133, 1.0, v133
	v_add_f32_e32 v132, 1.0, v132
	v_rcp_f32_e32 v132, v132
	s_waitcnt lgkmcnt(0)
	v_mfma_f32_16x16x32_bf16 v[70:73], v[6:9], v[78:81], v[70:73]
	ds_read_b128 v[74:77], v231 offset:8896
	ds_read_b128 v[78:81], v231 offset:43712
	s_waitcnt lgkmcnt(1)
	v_mfma_f32_16x16x32_bf16 v[114:117], v[2:5], v[74:77], v[66:69]
	s_waitcnt lgkmcnt(0)
	v_mfma_f32_16x16x32_bf16 v[110:113], v[2:5], v[78:81], v[70:73]
	s_nop 0
	ds_read_b128 v[66:69], v232
	s_nop 0
	ds_read_b128 v[70:73], v232 offset:34816
	ds_read_b128 v[74:77], v232 offset:64
	ds_read_b128 v[78:81], v232 offset:34880
	s_waitcnt lgkmcnt(3)
	v_mfma_f32_16x16x32_bf16 v[66:69], v[118:121], v[66:69], 0
	s_waitcnt lgkmcnt(2)
	v_mfma_f32_16x16x32_bf16 v[70:73], v[118:121], v[70:73], 0
	s_waitcnt lgkmcnt(1)
	v_mfma_f32_16x16x32_bf16 v[66:69], v[90:93], v[74:77], v[66:69]
	s_waitcnt lgkmcnt(0)
	v_mfma_f32_16x16x32_bf16 v[70:73], v[90:93], v[78:81], v[70:73]
	ds_read_b128 v[74:77], v232 offset:128
	ds_read_b128 v[78:81], v232 offset:34944
	s_waitcnt lgkmcnt(1)
	v_mfma_f32_16x16x32_bf16 v[66:69], v[6:9], v[74:77], v[66:69]
	s_waitcnt lgkmcnt(0)
	v_mfma_f32_16x16x32_bf16 v[70:73], v[6:9], v[78:81], v[70:73]
	ds_read_b128 v[74:77], v232 offset:192
	ds_read_b128 v[78:81], v232 offset:35008
	s_waitcnt lgkmcnt(1)
	v_mfma_f32_16x16x32_bf16 v[106:109], v[2:5], v[74:77], v[66:69]
	s_waitcnt lgkmcnt(0)
	v_mfma_f32_16x16x32_bf16 v[102:105], v[2:5], v[78:81], v[70:73]
	s_nop 0
	ds_read_b128 v[66:69], v231 offset:17408
	s_nop 0
	ds_read_b128 v[70:73], v231 offset:52224
	ds_read_b128 v[74:77], v231 offset:17472
	ds_read_b128 v[78:81], v231 offset:52288
	s_waitcnt lgkmcnt(3)
	v_mfma_f32_16x16x32_bf16 v[66:69], v[118:121], v[66:69], 0
	s_waitcnt lgkmcnt(2)
	v_mfma_f32_16x16x32_bf16 v[70:73], v[118:121], v[70:73], 0
	s_waitcnt lgkmcnt(1)
	v_mfma_f32_16x16x32_bf16 v[66:69], v[90:93], v[74:77], v[66:69]
	s_waitcnt lgkmcnt(0)
	v_mfma_f32_16x16x32_bf16 v[70:73], v[90:93], v[78:81], v[70:73]
	ds_read_b128 v[74:77], v231 offset:17536
	ds_read_b128 v[78:81], v231 offset:52352
	s_waitcnt lgkmcnt(1)
	v_mfma_f32_16x16x32_bf16 v[66:69], v[6:9], v[74:77], v[66:69]
	s_waitcnt lgkmcnt(0)
	v_mfma_f32_16x16x32_bf16 v[70:73], v[6:9], v[78:81], v[70:73]
	ds_read_b128 v[74:77], v231 offset:17600
	ds_read_b128 v[78:81], v231 offset:52416
	s_waitcnt lgkmcnt(1)
	v_mfma_f32_16x16x32_bf16 v[98:101], v[2:5], v[74:77], v[66:69]
	s_waitcnt lgkmcnt(0)
	v_mfma_f32_16x16x32_bf16 v[94:97], v[2:5], v[78:81], v[70:73]
	s_nop 0
	ds_read_b128 v[66:69], v231 offset:21760
	s_nop 0
	ds_read_b128 v[70:73], v231 offset:56576
	ds_read_b128 v[74:77], v231 offset:21824
	ds_read_b128 v[78:81], v231 offset:56640
	s_waitcnt lgkmcnt(3)
	v_mfma_f32_16x16x32_bf16 v[66:69], v[118:121], v[66:69], 0
	s_waitcnt lgkmcnt(2)
	v_mfma_f32_16x16x32_bf16 v[70:73], v[118:121], v[70:73], 0
	s_waitcnt lgkmcnt(1)
	v_mfma_f32_16x16x32_bf16 v[66:69], v[90:93], v[74:77], v[66:69]
	s_waitcnt lgkmcnt(0)
	v_mfma_f32_16x16x32_bf16 v[70:73], v[90:93], v[78:81], v[70:73]
	ds_read_b128 v[74:77], v231 offset:21888
	ds_read_b128 v[78:81], v231 offset:56704
	s_waitcnt lgkmcnt(1)
	v_mfma_f32_16x16x32_bf16 v[66:69], v[6:9], v[74:77], v[66:69]
	s_waitcnt lgkmcnt(0)
	v_mfma_f32_16x16x32_bf16 v[70:73], v[6:9], v[78:81], v[70:73]
	ds_read_b128 v[74:77], v231 offset:21952
	ds_read_b128 v[78:81], v231 offset:56768
	s_waitcnt lgkmcnt(1)
	v_mfma_f32_16x16x32_bf16 v[86:89], v[2:5], v[74:77], v[66:69]
	s_waitcnt lgkmcnt(0)
; __device__ __forceinline__ float fsig2(float x) { return __builtin_amdgcn_rcpf(1.0f + __builtin_amdgcn_exp2f(-LOG2E * x)); }
; template <int PASS> __device__ __forceinline__ void lru_wave_item(LAS unsigned char* lds, LAS unsigned char* vw, int b, int c, int h, const MixP& p, int lane, float (&Hrun)[8], bool cont) {
;     ...
; #pragma unroll
;         for (int n = 0; n < 8; ++n) {
;             const f32x4 aVn = __builtin_amdgcn_mfma_f32_16x16x32_bf16(af[n >> 1], idf[n & 1], (f32x4){0.f, 0.f, 0.f, 0.f}, 0, 0, 0);
;             float av[4], bxv[4];
; #pragma unroll
;             for (int j = 0; j < 4; ++j) {
;                 const float r = fsig2(aR[n][j] + pba[n]), ig = fsig2(aI[n][j] + pbx[n]);
;                 const float a = __builtin_amdgcn_exp2f(r * pk8[n]), mult = __builtin_amdgcn_sqrtf(fmaxf(1.0f - a * a, 0.f));
;                 av[j] = a; bxv[j] = mult * ig * aVn[j];
;             }
;             const float H0 = bxv[0], H1 = av[1] * H0 + bxv[1], H2 = av[2] * H1 + bxv[2], H3 = av[3] * H2 + bxv[3];
;             const float A0 = av[0], A1 = av[1] * A0, A2 = av[2] * A1, A3 = av[3] * A2;
;             float At[4], Ht[4];
; #pragma unroll
;             for (int q = 0; q < 4; ++q) { At[q] = __shfl(A3, fr + 16 * q); Ht[q] = __shfl(H3, fr + 16 * q); }
;             const float c0 = Hrun[n], c1 = At[0] * c0 + Ht[0], c2 = At[1] * c1 + Ht[1], c3 = At[2] * c2 + Ht[2], c4 = At[3] * c3 + Ht[3];
	v_mfma_f32_16x16x32_bf16 v[82:85], v[2:5], v[78:81], v[70:73]
	s_nop 0
	ds_read_b128 v[66:69], v231 offset:26112
	s_nop 0
	ds_read_b128 v[70:73], v231 offset:60928
	ds_read_b128 v[74:77], v231 offset:26176
	ds_read_b128 v[78:81], v231 offset:60992
	v_add_f32_e32 v86, v171, v86
	s_waitcnt lgkmcnt(3)
	v_mfma_f32_16x16x32_bf16 v[66:69], v[118:121], v[66:69], 0
	v_add_f32_e32 v87, v171, v87
	v_mul_f32_e32 v86, 0xbfb8aa3b, v86
	v_mul_f32_e32 v87, 0xbfb8aa3b, v87
	s_waitcnt lgkmcnt(2)
	v_mfma_f32_16x16x32_bf16 v[70:73], v[118:121], v[70:73], 0
	v_exp_f32_e32 v86, v86
	v_exp_f32_e32 v87, v87
	v_add_f32_e32 v82, v173, v82
	s_waitcnt lgkmcnt(1)
	v_mfma_f32_16x16x32_bf16 v[66:69], v[90:93], v[74:77], v[66:69]
	v_add_f32_e32 v86, 1.0, v86
	v_add_f32_e32 v87, 1.0, v87
	v_rcp_f32_e32 v86, v86
	s_waitcnt lgkmcnt(0)
	v_mfma_f32_16x16x32_bf16 v[70:73], v[90:93], v[78:81], v[70:73]
	ds_read_b128 v[74:77], v231 offset:26240
	ds_read_b128 v[78:81], v231 offset:61056
	v_rcp_f32_e32 v87, v87
	v_mul_f32_e32 v86, v175, v86
	s_waitcnt lgkmcnt(1)
	v_mfma_f32_16x16x32_bf16 v[66:69], v[6:9], v[74:77], v[66:69]
	ds_read_b128 v[74:77], v231 offset:26304
	ds_read_b128 v[138:141], v231 offset:61120
	v_add_f32_e32 v83, v173, v83
	v_mul_f32_e32 v87, v175, v87
	s_waitcnt lgkmcnt(2)
	v_mfma_f32_16x16x32_bf16 v[70:73], v[6:9], v[78:81], v[70:73]
	v_mul_f32_e32 v82, 0xbfb8aa3b, v82
	v_mul_f32_e32 v83, 0xbfb8aa3b, v83
	v_exp_f32_e32 v82, v82
	s_waitcnt lgkmcnt(1)
	v_mfma_f32_16x16x32_bf16 v[78:81], v[2:5], v[74:77], v[66:69]
	v_exp_f32_e32 v83, v83
	v_add_f32_e32 v85, v173, v85
	v_add_f32_e32 v82, 1.0, v82
	s_waitcnt lgkmcnt(0)
	v_mfma_f32_16x16x32_bf16 v[74:77], v[2:5], v[138:141], v[70:73]
	ds_read_b128 v[66:69], v233
	s_nop 1
	ds_read_b128 v[70:73], v233 offset:34816
	ds_read_b128 v[138:141], v233 offset:64
	ds_read_b128 v[184:187], v233 offset:34880
	v_add_f32_e32 v83, 1.0, v83
	s_waitcnt lgkmcnt(3)
	v_mfma_f32_16x16x32_bf16 v[66:69], v[118:121], v[66:69], 0
	v_rcp_f32_e32 v82, v82
	v_rcp_f32_e32 v83, v83
	v_mul_f32_e32 v85, 0xbfb8aa3b, v85
	s_waitcnt lgkmcnt(2)
	v_mfma_f32_16x16x32_bf16 v[70:73], v[118:121], v[70:73], 0
	v_exp_f32_e32 v85, v85
	s_nop 0
	v_add_f32_e32 v85, 1.0, v85
	s_waitcnt lgkmcnt(1)
	v_mfma_f32_16x16x32_bf16 v[66:69], v[90:93], v[138:141], v[66:69]
	s_waitcnt lgkmcnt(0)
	v_mfma_f32_16x16x32_bf16 v[70:73], v[90:93], v[184:187], v[70:73]
	ds_read_b128 v[138:141], v233 offset:128
	ds_read_b128 v[184:187], v233 offset:34944
	s_waitcnt lgkmcnt(1)
	v_mfma_f32_16x16x32_bf16 v[66:69], v[6:9], v[138:141], v[66:69]
	s_waitcnt lgkmcnt(0)
	v_mfma_f32_16x16x32_bf16 v[138:141], v[6:9], v[184:187], v[70:73]
	s_nop 2
	ds_read_b128 v[70:73], v233 offset:192
	ds_read_b128 v[184:187], v233 offset:35008
	s_waitcnt lgkmcnt(1)
	v_mfma_f32_16x16x32_bf16 v[70:73], v[2:5], v[70:73], v[66:69]
	s_waitcnt lgkmcnt(0)
	v_mfma_f32_16x16x32_bf16 v[66:69], v[2:5], v[184:187], v[138:141]
	v_exp_f32_e32 v186, v135
	s_nop 0
	v_fma_f32 v135, -v186, v186, 1.0
	v_max_f32_e32 v135, 0, v135
	v_sqrt_f32_e32 v135, v135
	v_mfma_f32_16x16x32_bf16 v[138:141], v[118:121], v[18:21], 0
	s_nop 1
	v_add_f32_e32 v66, v179, v66
	v_add_f32_e32 v67, v179, v67
	v_pk_mul_f32 v[130:131], v[130:131], v[134:135]
	v_add_f32_e32 v134, v158, v136
	v_mul_f32_e32 v134, 0xbfb8aa3b, v134
	v_exp_f32_e32 v134, v134
	v_pk_mul_f32 v[130:131], v[130:131], v[138:139]
	v_rcp_f32_e32 v136, v133
	v_mul_f32_e32 v66, 0xbfb8aa3b, v66
	v_add_f32_e32 v134, 1.0, v134
	v_rcp_f32_e32 v134, v134
	v_mul_f32_e32 v67, 0xbfb8aa3b, v67
	v_exp_f32_e32 v66, v66
	v_exp_f32_e32 v67, v67
	v_mul_f32_e32 v134, v162, v134
	v_exp_f32_e32 v139, v134
	v_add_f32_e32 v134, v158, v137
	v_mul_f32_e32 v134, 0xbfb8aa3b, v134
	v_exp_f32_e32 v134, v134
	v_add_f32_e32 v66, 1.0, v66
	v_add_f32_e32 v67, 1.0, v67
	v_rcp_f32_e32 v66, v66
	v_add_f32_e32 v134, 1.0, v134
	v_rcp_f32_e32 v134, v134
	v_rcp_f32_e32 v67, v67
	v_add_f32_e32 v69, v179, v69
	v_mul_f32_e32 v69, 0xbfb8aa3b, v69
	v_mul_f32_e32 v133, v162, v134
	v_exp_f32_e32 v185, v133
	v_fma_f32 v133, v186, v130, v131
	v_fma_f32 v131, -v139, v139, 1.0
	v_max_f32_e32 v131, 0, v131
	v_sqrt_f32_e32 v138, v131
	v_fma_f32 v131, -v185, v185, 1.0
	v_max_f32_e32 v131, 0, v131
	v_sqrt_f32_e32 v184, v131
	v_pk_mul_f32 v[134:135], v[132:133], v[138:139]
	v_mul_f32_e32 v131, v186, v236
	v_fmac_f32_e32 v135, v134, v140
	v_mov_b32_e32 v137, v135
	v_pk_mul_f32 v[136:137], v[136:137], v[184:185]
	v_mul_f32_e32 v132, v139, v131
	v_fmac_f32_e32 v137, v136, v141
	v_mfma_f32_16x16x32_bf16 v[138:141], v[118:121], v[22:25], 0
	v_add_f32_e32 v118, v159, v126
	v_mul_f32_e32 v118, 0xbfb8aa3b, v118
	v_exp_f32_e32 v118, v118
	v_mul_f32_e32 v134, v185, v132
	ds_bpermute_b32 v188, v0, v134
	ds_bpermute_b32 v192, v0, v137
	v_add_f32_e32 v118, 1.0, v118
	v_rcp_f32_e32 v119, v118
	v_add_f32_e32 v118, v161, v122
	v_mul_f32_e32 v118, 0xbfb8aa3b, v118
	v_exp_f32_e32 v118, v118
	v_mul_f32_e32 v119, v163, v119
	v_exp_f32_e32 v136, v119
	v_add_f32_e32 v122, v161, v125
	v_add_f32_e32 v118, 1.0, v118
	v_rcp_f32_e32 v118, v118
	v_fma_f32 v119, -v136, v136, 1.0
	v_max_f32_e32 v119, 0, v119
	v_sqrt_f32_e32 v120, v119
	v_add_f32_e32 v119, v159, v127
	v_mul_f32_e32 v119, 0xbfb8aa3b, v119
	v_exp_f32_e32 v119, v119
	v_mul_f32_e32 v122, 0xbfb8aa3b, v122
	v_exp_f32_e32 v122, v122
	ds_bpermute_b32 v190, v0, v134 offset:64
	v_add_f32_e32 v119, 1.0, v119
	v_rcp_f32_e32 v121, v119
	v_add_f32_e32 v119, v161, v123
	v_mul_f32_e32 v119, 0xbfb8aa3b, v119
	v_exp_f32_e32 v119, v119
	v_mul_f32_e32 v121, v163, v121
	v_exp_f32_e32 v185, v121
	v_add_f32_e32 v122, 1.0, v122
	v_add_f32_e32 v119, 1.0, v119
	v_rcp_f32_e32 v119, v119
	v_fma_f32 v121, -v185, v185, 1.0
; __device__ __forceinline__ float fsig2(float x) { return __builtin_amdgcn_rcpf(1.0f + __builtin_amdgcn_exp2f(-LOG2E * x)); }
; template <int PASS> __device__ __forceinline__ void lru_wave_item(LAS unsigned char* lds, LAS unsigned char* vw, int b, int c, int h, const MixP& p, int lane, float (&Hrun)[8], bool cont) {
;     ...
;         for (int n = 0; n < 8; ++n) {
;             const f32x4 aVn = __builtin_amdgcn_mfma_f32_16x16x32_bf16(af[n >> 1], idf[n & 1], (f32x4){0.f, 0.f, 0.f, 0.f}, 0, 0, 0);
;             float av[4], bxv[4];
; #pragma unroll
;             for (int j = 0; j < 4; ++j) {
;                 const float r = fsig2(aR[n][j] + pba[n]), ig = fsig2(aI[n][j] + pbx[n]);
;                 const float a = __builtin_amdgcn_exp2f(r * pk8[n]), mult = __builtin_amdgcn_sqrtf(fmaxf(1.0f - a * a, 0.f));
;                 av[j] = a; bxv[j] = mult * ig * aVn[j];
;             }
;             const float H0 = bxv[0], H1 = av[1] * H0 + bxv[1], H2 = av[2] * H1 + bxv[2], H3 = av[3] * H2 + bxv[3];
;             const float A0 = av[0], A1 = av[1] * A0, A2 = av[2] * A1, A3 = av[3] * A2;
;             float At[4], Ht[4];
; #pragma unroll
;             for (int q = 0; q < 4; ++q) { At[q] = __shfl(A3, fr + 16 * q); Ht[q] = __shfl(H3, fr + 16 * q); }
;             const float c0 = Hrun[n], c1 = At[0] * c0 + Ht[0], c2 = At[1] * c1 + Ht[1], c3 = At[2] * c2 + Ht[2], c4 = At[3] * c3 + Ht[3];
;             Hrun[n] = c4;
;             if (PASS == 1) Arun[n] *= (At[0] * At[1]) * (At[2] * At[3]);
;             if (PASS == 2) {
;                 const float cin = fq == 0 ? c0 : (fq == 1 ? c1 : (fq == 2 ? c2 : c3));
;                 aR[n][0] = H0 + A0 * cin; aR[n][1] = H1 + A1 * cin; aR[n][2] = H2 + A2 * cin; aR[n][3] = H3 + A3 * cin;
;             }
	v_max_f32_e32 v121, 0, v121
	v_sqrt_f32_e32 v121, v121
	ds_bpermute_b32 v196, v0, v137 offset:64
	ds_bpermute_b32 v194, v0, v134 offset:128
	ds_bpermute_b32 v198, v0, v137 offset:128
	v_pk_mul_f32 v[118:119], v[118:119], v[120:121]
	v_add_f32_e32 v120, v159, v128
	v_mul_f32_e32 v120, 0xbfb8aa3b, v120
	v_exp_f32_e32 v120, v120
	v_pk_mul_f32 v[118:119], v[118:119], v[138:139]
	ds_bpermute_b32 v186, v0, v137 offset:192
	v_exp_f32_e32 v69, v69
	v_add_f32_e32 v120, 1.0, v120
	v_rcp_f32_e32 v121, v120
	v_add_f32_e32 v120, v161, v124
	v_mul_f32_e32 v120, 0xbfb8aa3b, v120
	v_exp_f32_e32 v120, v120
	v_mul_f32_e32 v121, v163, v121
	v_exp_f32_e32 v127, v121
	v_add_f32_e32 v121, v159, v129
	v_mul_f32_e32 v121, 0xbfb8aa3b, v121
	v_exp_f32_e32 v121, v121
	v_add_f32_e32 v120, 1.0, v120
	v_rcp_f32_e32 v120, v120
	v_rcp_f32_e32 v124, v122
	v_add_f32_e32 v121, 1.0, v121
	v_rcp_f32_e32 v121, v121
	v_add_f32_e32 v69, 1.0, v69
	ds_bpermute_b32 v184, v0, v134 offset:192
	v_mul_f32_e32 v121, v163, v121
	v_exp_f32_e32 v129, v121
	v_fma_f32 v121, v185, v118, v119
	v_fma_f32 v119, -v127, v127, 1.0
	v_max_f32_e32 v119, 0, v119
	v_sqrt_f32_e32 v126, v119
	v_fma_f32 v119, -v129, v129, 1.0
	v_max_f32_e32 v119, 0, v119
	v_sqrt_f32_e32 v128, v119
	v_pk_mul_f32 v[122:123], v[120:121], v[126:127]
	v_mul_f32_e32 v119, v185, v136
	v_fmac_f32_e32 v123, v122, v140
	v_mov_b32_e32 v125, v123
	v_pk_mul_f32 v[124:125], v[124:125], v[128:129]
	v_mul_f32_e32 v120, v127, v119
	v_fmac_f32_e32 v125, v124, v141
	v_mul_f32_e32 v122, v129, v120
	ds_bpermute_b32 v189, v0, v122
	ds_bpermute_b32 v193, v0, v125
	ds_bpermute_b32 v191, v0, v122 offset:64
	ds_bpermute_b32 v197, v0, v125 offset:64
	ds_bpermute_b32 v195, v0, v122 offset:128
	ds_bpermute_b32 v199, v0, v125 offset:128
	s_waitcnt lgkmcnt(4)
	v_pk_fma_f32 v[128:129], v[10:11], v[188:189], v[192:193]
	ds_bpermute_b32 v187, v0, v125 offset:192
	s_waitcnt lgkmcnt(3)
	v_pk_fma_f32 v[138:139], v[128:129], v[190:191], v[196:197]
	ds_bpermute_b32 v185, v0, v122 offset:192
	s_waitcnt lgkmcnt(2)
	v_pk_fma_f32 v[126:127], v[138:139], v[194:195], v[198:199]
	s_nop 0
	v_cndmask_b32_e64 v124, v126, v138, s[8:9]
	v_cndmask_b32_e64 v124, v124, v128, s[6:7]
	v_cndmask_b32_e64 v10, v124, v10, s[4:5]
	v_fmac_f32_e32 v130, v236, v10
	v_fmac_f32_e32 v133, v131, v10
	v_fmac_f32_e32 v135, v132, v10
	v_fmac_f32_e32 v137, v134, v10
	v_cndmask_b32_e64 v10, v127, v139, s[8:9]
	v_cndmask_b32_e64 v10, v10, v129, s[6:7]
	v_cndmask_b32_e64 v10, v10, v11, s[4:5]
	v_fmac_f32_e32 v118, v136, v10
	v_fmac_f32_e32 v121, v119, v10
	v_fmac_f32_e32 v123, v120, v10
	v_fmac_f32_e32 v125, v122, v10
	v_add_f32_e32 v10, v164, v114
	v_mul_f32_e32 v10, 0xbfb8aa3b, v10
	v_exp_f32_e32 v10, v10
	v_mfma_f32_16x16x32_bf16 v[138:141], v[90:93], v[18:21], 0
	v_add_f32_e32 v10, 1.0, v10
	v_rcp_f32_e32 v11, v10
	v_add_f32_e32 v10, v166, v110
	v_mul_f32_e32 v10, 0xbfb8aa3b, v10
	v_exp_f32_e32 v10, v10
	v_mul_f32_e32 v11, v168, v11
	v_exp_f32_e32 v119, v11
	v_add_f32_e32 v10, 1.0, v10
	v_rcp_f32_e32 v10, v10
	v_fma_f32 v11, -v119, v119, 1.0
	v_max_f32_e32 v11, 0, v11
	v_sqrt_f32_e32 v110, v11
	v_add_f32_e32 v11, v164, v115
	v_mul_f32_e32 v11, 0xbfb8aa3b, v11
	v_exp_f32_e32 v11, v11
	s_nop 0
	v_add_f32_e32 v11, 1.0, v11
	v_rcp_f32_e32 v114, v11
	v_add_f32_e32 v11, v166, v111
	v_mul_f32_e32 v11, 0xbfb8aa3b, v11
	v_exp_f32_e32 v11, v11
	v_mul_f32_e32 v111, v168, v114
	v_exp_f32_e32 v120, v111
	v_add_f32_e32 v11, 1.0, v11
	v_rcp_f32_e32 v11, v11
	v_fma_f32 v111, -v120, v120, 1.0
	v_max_f32_e32 v111, 0, v111
	v_sqrt_f32_e32 v111, v111
	s_nop 0
	v_pk_mul_f32 v[10:11], v[10:11], v[110:111]
	v_add_f32_e32 v110, v164, v116
	v_mul_f32_e32 v110, 0xbfb8aa3b, v110
	v_exp_f32_e32 v110, v110
	v_pk_mul_f32 v[10:11], v[10:11], v[138:139]
	v_add_f32_e32 v110, 1.0, v110
	v_rcp_f32_e32 v111, v110
	v_add_f32_e32 v110, v166, v112
	v_mul_f32_e32 v110, 0xbfb8aa3b, v110
	v_exp_f32_e32 v110, v110
	v_mul_f32_e32 v111, v168, v111
	v_exp_f32_e32 v129, v111
	v_add_f32_e32 v111, v164, v117
	v_mul_f32_e32 v111, 0xbfb8aa3b, v111
	v_exp_f32_e32 v111, v111
	v_add_f32_e32 v112, v166, v113
	v_mul_f32_e32 v112, 0xbfb8aa3b, v112
	v_exp_f32_e32 v112, v112
	v_add_f32_e32 v111, 1.0, v111
	v_rcp_f32_e32 v111, v111
	v_add_f32_e32 v110, 1.0, v110
	v_rcp_f32_e32 v110, v110
	v_add_f32_e32 v112, 1.0, v112
	v_mul_f32_e32 v111, v168, v111
	v_exp_f32_e32 v117, v111
	v_fma_f32 v111, v120, v10, v11
	v_fma_f32 v11, -v129, v129, 1.0
	v_max_f32_e32 v11, 0, v11
	v_sqrt_f32_e32 v128, v11
	v_fma_f32 v11, -v117, v117, 1.0
	v_max_f32_e32 v11, 0, v11
	v_rcp_f32_e32 v114, v112
	v_sqrt_f32_e32 v116, v11
	v_pk_mul_f32 v[112:113], v[110:111], v[128:129]
	v_mul_f32_e32 v11, v120, v119
	v_fmac_f32_e32 v113, v112, v140
	v_mov_b32_e32 v115, v113
	v_pk_mul_f32 v[114:115], v[114:115], v[116:117]
	v_mul_f32_e32 v110, v129, v11
	v_fmac_f32_e32 v115, v114, v141
	v_mfma_f32_16x16x32_bf16 v[138:141], v[90:93], v[22:25], 0
	v_add_f32_e32 v90, v165, v106
	v_mul_f32_e32 v90, 0xbfb8aa3b, v90
	v_exp_f32_e32 v90, v90
	v_mul_f32_e32 v112, v117, v110
	ds_bpermute_b32 v188, v0, v112
	ds_bpermute_b32 v190, v0, v115
	v_add_f32_e32 v90, 1.0, v90
	v_rcp_f32_e32 v91, v90
	v_add_f32_e32 v90, v167, v102
	v_mul_f32_e32 v90, 0xbfb8aa3b, v90
	v_exp_f32_e32 v90, v90
	v_mul_f32_e32 v91, v169, v91
	v_exp_f32_e32 v114, v91
	v_add_f32_e32 v102, v167, v105
	v_add_f32_e32 v90, 1.0, v90
	v_rcp_f32_e32 v90, v90
	v_fma_f32 v91, -v114, v114, 1.0
	v_max_f32_e32 v91, 0, v91
	v_sqrt_f32_e32 v92, v91
	v_add_f32_e32 v91, v165, v107
	v_mul_f32_e32 v91, 0xbfb8aa3b, v91
	v_exp_f32_e32 v91, v91
	v_mul_f32_e32 v102, 0xbfb8aa3b, v102
	v_exp_f32_e32 v102, v102
	ds_bpermute_b32 v192, v0, v112 offset:64
; __device__ __forceinline__ float fsig2(float x) { return __builtin_amdgcn_rcpf(1.0f + __builtin_amdgcn_exp2f(-LOG2E * x)); }
; template <int PASS> __device__ __forceinline__ void lru_wave_item(LAS unsigned char* lds, LAS unsigned char* vw, int b, int c, int h, const MixP& p, int lane, float (&Hrun)[8], bool cont) {
;     ...
;         for (int n = 0; n < 8; ++n) {
;             const f32x4 aVn = __builtin_amdgcn_mfma_f32_16x16x32_bf16(af[n >> 1], idf[n & 1], (f32x4){0.f, 0.f, 0.f, 0.f}, 0, 0, 0);
;             float av[4], bxv[4];
; #pragma unroll
;             for (int j = 0; j < 4; ++j) {
;                 const float r = fsig2(aR[n][j] + pba[n]), ig = fsig2(aI[n][j] + pbx[n]);
;                 const float a = __builtin_amdgcn_exp2f(r * pk8[n]), mult = __builtin_amdgcn_sqrtf(fmaxf(1.0f - a * a, 0.f));
;                 av[j] = a; bxv[j] = mult * ig * aVn[j];
;             }
;             const float H0 = bxv[0], H1 = av[1] * H0 + bxv[1], H2 = av[2] * H1 + bxv[2], H3 = av[3] * H2 + bxv[3];
;             const float A0 = av[0], A1 = av[1] * A0, A2 = av[2] * A1, A3 = av[3] * A2;
;             float At[4], Ht[4];
; #pragma unroll
;             for (int q = 0; q < 4; ++q) { At[q] = __shfl(A3, fr + 16 * q); Ht[q] = __shfl(H3, fr + 16 * q); }
;             const float c0 = Hrun[n], c1 = At[0] * c0 + Ht[0], c2 = At[1] * c1 + Ht[1], c3 = At[2] * c2 + Ht[2], c4 = At[3] * c3 + Ht[3];
;             Hrun[n] = c4;
;             if (PASS == 1) Arun[n] *= (At[0] * At[1]) * (At[2] * At[3]);
;             if (PASS == 2) {
;                 const float cin = fq == 0 ? c0 : (fq == 1 ? c1 : (fq == 2 ? c2 : c3));
;                 aR[n][0] = H0 + A0 * cin; aR[n][1] = H1 + A1 * cin; aR[n][2] = H2 + A2 * cin; aR[n][3] = H3 + A3 * cin;
;             }
	v_add_f32_e32 v91, 1.0, v91
	v_rcp_f32_e32 v93, v91
	v_add_f32_e32 v91, v167, v103
	v_mul_f32_e32 v91, 0xbfb8aa3b, v91
	v_exp_f32_e32 v91, v91
	v_mul_f32_e32 v93, v169, v93
	v_exp_f32_e32 v117, v93
	v_add_f32_e32 v102, 1.0, v102
	v_add_f32_e32 v91, 1.0, v91
	v_rcp_f32_e32 v91, v91
	v_fma_f32 v93, -v117, v117, 1.0
	v_max_f32_e32 v93, 0, v93
	v_sqrt_f32_e32 v93, v93
	ds_bpermute_b32 v194, v0, v115 offset:64
	ds_bpermute_b32 v196, v0, v112 offset:128
	ds_bpermute_b32 v198, v0, v115 offset:128
	v_pk_mul_f32 v[90:91], v[90:91], v[92:93]
	v_add_f32_e32 v92, v165, v108
	v_mul_f32_e32 v92, 0xbfb8aa3b, v92
	v_exp_f32_e32 v92, v92
	v_pk_mul_f32 v[90:91], v[90:91], v[138:139]
	ds_bpermute_b32 v128, v0, v115 offset:192
	ds_bpermute_b32 v116, v0, v112 offset:192
	v_add_f32_e32 v92, 1.0, v92
	v_rcp_f32_e32 v93, v92
	v_add_f32_e32 v92, v167, v104
	v_mul_f32_e32 v92, 0xbfb8aa3b, v92
	v_exp_f32_e32 v92, v92
	v_mul_f32_e32 v93, v169, v93
	v_exp_f32_e32 v107, v93
	v_add_f32_e32 v93, v165, v109
	v_mul_f32_e32 v93, 0xbfb8aa3b, v93
	v_exp_f32_e32 v93, v93
	v_add_f32_e32 v92, 1.0, v92
	v_rcp_f32_e32 v92, v92
	v_rcp_f32_e32 v104, v102
	v_add_f32_e32 v93, 1.0, v93
	v_rcp_f32_e32 v93, v93
	s_nop 0
	v_mul_f32_e32 v93, v169, v93
	v_exp_f32_e32 v109, v93
	v_fma_f32 v93, v117, v90, v91
	v_fma_f32 v91, -v107, v107, 1.0
	v_max_f32_e32 v91, 0, v91
	v_sqrt_f32_e32 v106, v91
	v_fma_f32 v91, -v109, v109, 1.0
	v_max_f32_e32 v91, 0, v91
	v_sqrt_f32_e32 v108, v91
	v_pk_mul_f32 v[102:103], v[92:93], v[106:107]
	v_mul_f32_e32 v91, v117, v114
	v_fmac_f32_e32 v103, v102, v140
	v_mov_b32_e32 v105, v103
	v_pk_mul_f32 v[104:105], v[104:105], v[108:109]
	v_mul_f32_e32 v92, v107, v91
	v_fmac_f32_e32 v105, v104, v141
	v_mul_f32_e32 v102, v109, v92
	ds_bpermute_b32 v189, v0, v102
	ds_bpermute_b32 v191, v0, v105
	ds_bpermute_b32 v193, v0, v102 offset:64
	ds_bpermute_b32 v195, v0, v105 offset:64
	ds_bpermute_b32 v197, v0, v102 offset:128
	ds_bpermute_b32 v199, v0, v105 offset:128
	s_waitcnt lgkmcnt(4)
	v_pk_fma_f32 v[108:109], v[12:13], v[188:189], v[190:191]
	ds_bpermute_b32 v129, v0, v105 offset:192
	s_waitcnt lgkmcnt(3)
	v_pk_fma_f32 v[138:139], v[108:109], v[192:193], v[194:195]
	ds_bpermute_b32 v117, v0, v102 offset:192
	s_waitcnt lgkmcnt(2)
	v_pk_fma_f32 v[106:107], v[138:139], v[196:197], v[198:199]
	s_nop 0
	v_cndmask_b32_e64 v104, v106, v138, s[8:9]
	v_cndmask_b32_e64 v104, v104, v108, s[6:7]
	v_cndmask_b32_e64 v12, v104, v12, s[4:5]
	v_fmac_f32_e32 v111, v11, v12
	v_cndmask_b32_e64 v11, v107, v139, s[8:9]
	v_cndmask_b32_e64 v11, v11, v109, s[6:7]
	v_cndmask_b32_e64 v11, v11, v13, s[4:5]
	v_fmac_f32_e32 v90, v114, v11
	v_fmac_f32_e32 v93, v91, v11
	v_fmac_f32_e32 v103, v92, v11
	v_fmac_f32_e32 v105, v102, v11
	v_add_f32_e32 v11, v170, v98
	v_mul_f32_e32 v11, 0xbfb8aa3b, v11
	v_exp_f32_e32 v11, v11
	v_fmac_f32_e32 v10, v119, v12
	v_fmac_f32_e32 v113, v110, v12
	v_fmac_f32_e32 v115, v112, v12
	v_add_f32_e32 v11, 1.0, v11
	v_rcp_f32_e32 v11, v11
	v_add_f32_e32 v12, v172, v94
	v_mul_f32_e32 v12, 0xbfb8aa3b, v12
	v_exp_f32_e32 v12, v12
	v_mul_f32_e32 v11, v174, v11
	v_exp_f32_e32 v11, v11
	v_mfma_f32_16x16x32_bf16 v[138:141], v[6:9], v[18:21], 0
	v_add_f32_e32 v12, 1.0, v12
	v_rcp_f32_e32 v12, v12
	v_fma_f32 v13, -v11, v11, 1.0
	v_max_f32_e32 v13, 0, v13
	v_sqrt_f32_e32 v94, v13
	v_add_f32_e32 v13, v170, v99
	v_mul_f32_e32 v13, 0xbfb8aa3b, v13
	v_exp_f32_e32 v13, v13
	v_mfma_f32_16x16x32_bf16 v[6:9], v[6:9], v[22:25], 0
	v_add_f32_e32 v13, 1.0, v13
	v_rcp_f32_e32 v91, v13
	v_add_f32_e32 v13, v172, v95
	v_mul_f32_e32 v13, 0xbfb8aa3b, v13
	v_exp_f32_e32 v13, v13
	v_mul_f32_e32 v91, v174, v91
	v_exp_f32_e32 v91, v91
	v_add_f32_e32 v13, 1.0, v13
	v_rcp_f32_e32 v13, v13
	v_fma_f32 v92, -v91, v91, 1.0
	v_max_f32_e32 v92, 0, v92
	v_sqrt_f32_e32 v95, v92
	v_add_f32_e32 v92, v170, v100
	v_mul_f32_e32 v92, 0xbfb8aa3b, v92
	v_exp_f32_e32 v92, v92
	v_pk_mul_f32 v[12:13], v[12:13], v[94:95]
	v_add_f32_e32 v95, v172, v97
	v_mul_f32_e32 v95, 0xbfb8aa3b, v95
	v_add_f32_e32 v92, 1.0, v92
	v_rcp_f32_e32 v92, v92
	v_add_f32_e32 v94, v172, v96
	v_exp_f32_e32 v95, v95
	v_mul_f32_e32 v94, 0xbfb8aa3b, v94
	v_mul_f32_e32 v92, v174, v92
	v_exp_f32_e32 v109, v92
	v_exp_f32_e32 v94, v94
	v_pk_mul_f32 v[12:13], v[12:13], v[138:139]
	v_add_f32_e32 v95, 1.0, v95
	v_rcp_f32_e32 v98, v95
	v_fma_f32 v95, v91, v12, v13
	v_fma_f32 v13, -v109, v109, 1.0
	v_add_f32_e32 v94, 1.0, v94
	v_max_f32_e32 v13, 0, v13
	v_rcp_f32_e32 v94, v94
	v_sqrt_f32_e32 v108, v13
	v_add_f32_e32 v92, v170, v101
	v_mul_f32_e32 v92, 0xbfb8aa3b, v92
	v_exp_f32_e32 v92, v92
	v_pk_mul_f32 v[96:97], v[94:95], v[108:109]
	v_exp_f32_e32 v94, v86
	v_fmac_f32_e32 v97, v96, v140
	v_exp_f32_e32 v96, v87
	v_add_f32_e32 v92, 1.0, v92
	v_fma_f32 v86, -v94, v94, 1.0
	v_max_f32_e32 v86, 0, v86
	v_fma_f32 v87, -v96, v96, 1.0
	v_max_f32_e32 v87, 0, v87
	v_sqrt_f32_e32 v86, v86
	v_sqrt_f32_e32 v87, v87
	v_rcp_f32_e32 v92, v92
	v_mov_b32_e32 v99, v97
	v_pk_mul_f32 v[82:83], v[82:83], v[86:87]
	s_nop 0
	v_pk_mul_f32 v[82:83], v[82:83], v[6:7]
	v_add_f32_e32 v6, v171, v88
	v_mul_f32_e32 v6, 0xbfb8aa3b, v6
	v_exp_f32_e32 v6, v6
	v_add_f32_e32 v7, v173, v84
	v_mul_f32_e32 v7, 0xbfb8aa3b, v7
	v_exp_f32_e32 v7, v7
	v_add_f32_e32 v6, 1.0, v6
	v_rcp_f32_e32 v6, v6
	v_mul_f32_e32 v92, v174, v92
	v_add_f32_e32 v7, 1.0, v7
	v_rcp_f32_e32 v84, v7
	v_mul_f32_e32 v6, v175, v6
	v_exp_f32_e32 v7, v6
	v_add_f32_e32 v6, v171, v89
	v_mul_f32_e32 v6, 0xbfb8aa3b, v6
	v_exp_f32_e32 v6, v6
	v_exp_f32_e32 v101, v92
	v_rcp_f32_e32 v88, v85
	v_fma_f32 v85, v96, v82, v83
	v_add_f32_e32 v6, 1.0, v6
	v_rcp_f32_e32 v6, v6
	v_fma_f32 v13, -v101, v101, 1.0
	v_max_f32_e32 v13, 0, v13
	v_sqrt_f32_e32 v100, v13
	v_mul_f32_e32 v6, v175, v6
	v_exp_f32_e32 v197, v6
	v_fma_f32 v6, -v7, v7, 1.0
	v_max_f32_e32 v6, 0, v6
	v_sqrt_f32_e32 v6, v6
	v_mul_f32_e32 v13, v91, v11
	v_mul_f32_e32 v83, v96, v94
	v_pk_mul_f32 v[98:99], v[98:99], v[100:101]
	v_pk_mul_f32 v[86:87], v[84:85], v[6:7]
	v_fma_f32 v6, -v197, v197, 1.0
	v_max_f32_e32 v6, 0, v6
	v_sqrt_f32_e32 v196, v6
	v_fmac_f32_e32 v87, v86, v8
	v_mov_b32_e32 v89, v87
	v_mul_f32_e32 v91, v109, v13
	v_pk_mul_f32 v[88:89], v[88:89], v[196:197]
	v_mul_f32_e32 v84, v7, v83
	v_fmac_f32_e32 v99, v98, v141
	v_mul_f32_e32 v92, v101, v91
	v_fmac_f32_e32 v89, v88, v9
	v_mul_f32_e32 v86, v197, v84
	ds_bpermute_b32 v138, v0, v92
	ds_bpermute_b32 v140, v0, v99
	ds_bpermute_b32 v139, v0, v86
	ds_bpermute_b32 v141, v0, v89
	ds_bpermute_b32 v188, v0, v92 offset:64
	ds_bpermute_b32 v190, v0, v99 offset:64
	ds_bpermute_b32 v189, v0, v86 offset:64
	ds_bpermute_b32 v191, v0, v89 offset:64
	ds_bpermute_b32 v192, v0, v92 offset:128
	ds_bpermute_b32 v194, v0, v99 offset:128
	ds_bpermute_b32 v193, v0, v86 offset:128
	ds_bpermute_b32 v195, v0, v89 offset:128
	s_waitcnt lgkmcnt(8)
; __device__ __forceinline__ float fsig2(float x) { return __builtin_amdgcn_rcpf(1.0f + __builtin_amdgcn_exp2f(-LOG2E * x)); }
; template <int PASS> __device__ __forceinline__ void lru_wave_item(LAS unsigned char* lds, LAS unsigned char* vw, int b, int c, int h, const MixP& p, int lane, float (&Hrun)[8], bool cont) {
;     ...
;         for (int n = 0; n < 8; ++n) {
;             const f32x4 aVn = __builtin_amdgcn_mfma_f32_16x16x32_bf16(af[n >> 1], idf[n & 1], (f32x4){0.f, 0.f, 0.f, 0.f}, 0, 0, 0);
;             float av[4], bxv[4];
; #pragma unroll
;             for (int j = 0; j < 4; ++j) {
;                 const float r = fsig2(aR[n][j] + pba[n]), ig = fsig2(aI[n][j] + pbx[n]);
;                 const float a = __builtin_amdgcn_exp2f(r * pk8[n]), mult = __builtin_amdgcn_sqrtf(fmaxf(1.0f - a * a, 0.f));
;                 av[j] = a; bxv[j] = mult * ig * aVn[j];
;             }
;             const float H0 = bxv[0], H1 = av[1] * H0 + bxv[1], H2 = av[2] * H1 + bxv[2], H3 = av[3] * H2 + bxv[3];
;             const float A0 = av[0], A1 = av[1] * A0, A2 = av[2] * A1, A3 = av[3] * A2;
;             float At[4], Ht[4];
; #pragma unroll
;             for (int q = 0; q < 4; ++q) { At[q] = __shfl(A3, fr + 16 * q); Ht[q] = __shfl(H3, fr + 16 * q); }
;             const float c0 = Hrun[n], c1 = At[0] * c0 + Ht[0], c2 = At[1] * c1 + Ht[1], c3 = At[2] * c2 + Ht[2], c4 = At[3] * c3 + Ht[3];
;             Hrun[n] = c4;
;             if (PASS == 1) Arun[n] *= (At[0] * At[1]) * (At[2] * At[3]);
;             if (PASS == 2) {
;                 const float cin = fq == 0 ? c0 : (fq == 1 ? c1 : (fq == 2 ? c2 : c3));
;                 aR[n][0] = H0 + A0 * cin; aR[n][1] = H1 + A1 * cin; aR[n][2] = H2 + A2 * cin; aR[n][3] = H3 + A3 * cin;
;             }
	v_pk_fma_f32 v[8:9], v[14:15], v[138:139], v[140:141]
	ds_bpermute_b32 v108, v0, v99 offset:192
	s_waitcnt lgkmcnt(5)
	v_pk_fma_f32 v[138:139], v[8:9], v[188:189], v[190:191]
	ds_bpermute_b32 v109, v0, v89 offset:192
	s_waitcnt lgkmcnt(2)
	v_pk_fma_f32 v[6:7], v[138:139], v[192:193], v[194:195]
	ds_bpermute_b32 v100, v0, v92 offset:192
	v_cndmask_b32_e64 v88, v6, v138, s[8:9]
	v_cndmask_b32_e64 v8, v88, v8, s[6:7]
	v_cndmask_b32_e64 v8, v8, v14, s[4:5]
	v_fmac_f32_e32 v12, v11, v8
	v_fmac_f32_e32 v95, v13, v8
	v_fmac_f32_e32 v97, v91, v8
	v_fmac_f32_e32 v99, v92, v8
	v_cndmask_b32_e64 v8, v7, v139, s[8:9]
	v_cndmask_b32_e64 v8, v8, v9, s[6:7]
	v_cndmask_b32_e64 v8, v8, v15, s[4:5]
	v_fmac_f32_e32 v82, v94, v8
	v_fmac_f32_e32 v85, v83, v8
	v_fmac_f32_e32 v87, v84, v8
	v_fmac_f32_e32 v89, v86, v8
	v_add_f32_e32 v8, v176, v78
	v_mul_f32_e32 v8, 0xbfb8aa3b, v8
	v_exp_f32_e32 v8, v8
	v_mfma_f32_16x16x32_bf16 v[138:141], v[2:5], v[18:21], 0
	ds_bpermute_b32 v101, v0, v86 offset:192
	v_add_f32_e32 v8, 1.0, v8
	v_rcp_f32_e32 v9, v8
	v_add_f32_e32 v8, v178, v74
	v_mul_f32_e32 v8, 0xbfb8aa3b, v8
	v_exp_f32_e32 v8, v8
	v_mul_f32_e32 v9, v180, v9
	v_exp_f32_e32 v11, v9
	v_mfma_f32_16x16x32_bf16 v[2:5], v[2:5], v[22:25], 0
	v_add_f32_e32 v8, 1.0, v8
	v_rcp_f32_e32 v8, v8
	v_fma_f32 v9, -v11, v11, 1.0
	v_max_f32_e32 v9, 0, v9
	v_sqrt_f32_e32 v14, v9
	v_add_f32_e32 v9, v176, v79
	v_mul_f32_e32 v9, 0xbfb8aa3b, v9
	v_exp_f32_e32 v9, v9
	s_waitcnt lgkmcnt(0)
	v_pk_fma_f32 v[6:7], v[6:7], v[100:101], v[108:109]
	v_add_f32_e32 v9, 1.0, v9
	v_rcp_f32_e32 v13, v9
	v_add_f32_e32 v9, v178, v75
	v_mul_f32_e32 v9, 0xbfb8aa3b, v9
	v_exp_f32_e32 v9, v9
	v_mul_f32_e32 v13, v180, v13
	v_exp_f32_e32 v13, v13
	v_add_f32_e32 v75, v178, v77
	v_add_f32_e32 v9, 1.0, v9
	v_rcp_f32_e32 v9, v9
	v_fma_f32 v15, -v13, v13, 1.0
	v_max_f32_e32 v15, 0, v15
	v_sqrt_f32_e32 v15, v15
	v_mul_f32_e32 v75, 0xbfb8aa3b, v75
	v_exp_f32_e32 v75, v75
	v_pk_mul_f32 v[8:9], v[8:9], v[14:15]
	s_nop 0
	v_pk_mul_f32 v[14:15], v[8:9], v[138:139]
	v_add_f32_e32 v8, v176, v80
	v_mul_f32_e32 v8, 0xbfb8aa3b, v8
	v_exp_f32_e32 v8, v8
	v_add_f32_e32 v9, v178, v76
	v_mul_f32_e32 v9, 0xbfb8aa3b, v9
	v_exp_f32_e32 v9, v9
	v_add_f32_e32 v8, 1.0, v8
	v_rcp_f32_e32 v8, v8
	v_add_f32_e32 v75, 1.0, v75
	v_add_f32_e32 v9, 1.0, v9
	v_rcp_f32_e32 v74, v9
	v_mul_f32_e32 v8, v180, v8
	v_exp_f32_e32 v9, v8
	v_add_f32_e32 v8, v176, v81
	v_mul_f32_e32 v8, 0xbfb8aa3b, v8
	v_exp_f32_e32 v8, v8
	v_rcp_f32_e32 v78, v75
	v_fma_f32 v75, v13, v14, v15
	v_mul_f32_e32 v13, v13, v11
	v_add_f32_e32 v8, 1.0, v8
	v_rcp_f32_e32 v8, v8
	v_mul_f32_e32 v15, v9, v13
	v_mul_f32_e32 v8, v180, v8
	v_exp_f32_e32 v81, v8
	v_fma_f32 v8, -v9, v9, 1.0
	v_max_f32_e32 v8, 0, v8
	v_sqrt_f32_e32 v8, v8
	s_nop 0
	v_pk_mul_f32 v[76:77], v[74:75], v[8:9]
	v_add_f32_e32 v9, v177, v70
	v_mul_f32_e32 v9, 0xbfb8aa3b, v9
	v_exp_f32_e32 v9, v9
	v_fmac_f32_e32 v77, v76, v140
	v_fma_f32 v8, -v81, v81, 1.0
	v_max_f32_e32 v8, 0, v8
	v_add_f32_e32 v9, 1.0, v9
	v_rcp_f32_e32 v9, v9
	v_sqrt_f32_e32 v80, v8
	v_mov_b32_e32 v79, v77
	v_mul_f32_e32 v74, v81, v15
	v_mul_f32_e32 v9, v181, v9
	v_exp_f32_e32 v76, v9
	v_pk_mul_f32 v[78:79], v[78:79], v[80:81]
	ds_bpermute_b32 v8, v0, v74
	v_fmac_f32_e32 v79, v78, v141
	v_fma_f32 v9, -v76, v76, 1.0
	v_max_f32_e32 v9, 0, v9
	v_sqrt_f32_e32 v70, v9
	v_add_f32_e32 v9, v177, v71
	v_mul_f32_e32 v9, 0xbfb8aa3b, v9
	v_exp_f32_e32 v9, v9
	ds_bpermute_b32 v80, v0, v79
	ds_bpermute_b32 v138, v0, v74 offset:64
	ds_bpermute_b32 v140, v0, v79 offset:64
	v_add_f32_e32 v9, 1.0, v9
	v_rcp_f32_e32 v9, v9
	ds_bpermute_b32 v188, v0, v74 offset:128
	ds_bpermute_b32 v190, v0, v79 offset:128
	ds_bpermute_b32 v192, v0, v74 offset:192
	v_mul_f32_e32 v9, v181, v9
	v_exp_f32_e32 v9, v9
	ds_bpermute_b32 v194, v0, v79 offset:192
	v_fma_f32 v71, -v9, v9, 1.0
	v_max_f32_e32 v71, 0, v71
	v_sqrt_f32_e32 v71, v71
	s_nop 0
	v_pk_mul_f32 v[66:67], v[66:67], v[70:71]
	s_nop 0
	v_pk_mul_f32 v[66:67], v[66:67], v[2:3]
	v_add_f32_e32 v2, v177, v72
	v_mul_f32_e32 v2, 0xbfb8aa3b, v2
	v_exp_f32_e32 v2, v2
	v_add_f32_e32 v3, v179, v68
	v_mul_f32_e32 v3, 0xbfb8aa3b, v3
	v_exp_f32_e32 v3, v3
	v_add_f32_e32 v2, 1.0, v2
	v_rcp_f32_e32 v2, v2
	v_rcp_f32_e32 v70, v69
	v_add_f32_e32 v3, 1.0, v3
	v_rcp_f32_e32 v68, v3
	v_mul_f32_e32 v2, v181, v2
	v_exp_f32_e32 v3, v2
	v_add_f32_e32 v2, v177, v73
	v_mul_f32_e32 v2, 0xbfb8aa3b, v2
	v_exp_f32_e32 v2, v2
	v_fma_f32 v69, v9, v66, v67
	v_mul_f32_e32 v67, v9, v76
	v_add_f32_e32 v2, 1.0, v2
	v_rcp_f32_e32 v2, v2
	s_nop 0
	v_mul_f32_e32 v2, v181, v2
	v_exp_f32_e32 v73, v2
	v_fma_f32 v2, -v3, v3, 1.0
	v_max_f32_e32 v2, 0, v2
	v_sqrt_f32_e32 v2, v2
	s_nop 0
	v_pk_mul_f32 v[196:197], v[68:69], v[2:3]
	v_fma_f32 v2, -v73, v73, 1.0
	v_max_f32_e32 v2, 0, v2
	v_sqrt_f32_e32 v72, v2
	v_fmac_f32_e32 v197, v196, v4
	v_mov_b32_e32 v71, v197
	v_mul_f32_e32 v68, v3, v67
	v_pk_mul_f32 v[70:71], v[70:71], v[72:73]
	v_pk_fma_f32 v[2:3], v[126:127], v[184:185], v[186:187]
	v_fmac_f32_e32 v71, v70, v5
	v_mul_f32_e32 v70, v73, v68
	ds_bpermute_b32 v9, v0, v70
	ds_bpermute_b32 v81, v0, v71
	ds_bpermute_b32 v139, v0, v70 offset:64
	ds_bpermute_b32 v141, v0, v71 offset:64
	ds_bpermute_b32 v189, v0, v70 offset:128
	ds_bpermute_b32 v191, v0, v71 offset:128
	s_waitcnt lgkmcnt(4)
	v_pk_fma_f32 v[72:73], v[16:17], v[8:9], v[80:81]
	ds_bpermute_b32 v193, v0, v70 offset:192
	s_waitcnt lgkmcnt(3)
	v_pk_fma_f32 v[80:81], v[72:73], v[138:139], v[140:141]
	ds_bpermute_b32 v195, v0, v71 offset:192
	s_waitcnt lgkmcnt(2)
; #define LAS __attribute__((address_space(3)))
; __device__ __forceinline__ unsigned cvt_pk_bf16(float lo, float hi) { unsigned r; asm volatile("v_cvt_pk_bf16_f32 %0, %1, %2" : "=v"(r) : "v"(lo), "v"(hi)); return r; }
; __device__ __forceinline__ float bflo(unsigned w) { return __uint_as_float(w << 16); }
; __device__ __forceinline__ float bfhi(unsigned w) { return __uint_as_float(w & 0xffff0000u); }
; __device__ __forceinline__ u32x4 pack8(const f32x4 a, const f32x4 b) { u32x4 w; w.x = cvt_pk_bf16(a[0], a[1]); w.y = cvt_pk_bf16(a[2], a[3]); w.z = cvt_pk_bf16(b[0], b[1]); w.w = cvt_pk_bf16(b[2], b[3]); return w; }
; template <int PASS> __device__ __forceinline__ void lru_wave_item(LAS unsigned char* lds, LAS unsigned char* vw, int b, int c, int h, const MixP& p, int lane, float (&Hrun)[8], bool cont) {
;     ...
;                 aR[n][0] = H0 + A0 * cin; aR[n][1] = H1 + A1 * cin; aR[n][2] = H2 + A2 * cin; aR[n][3] = H3 + A3 * cin;
;             }
;         }
;         if (PASS == 2) {
; #pragma unroll
;             for (int n = 0; n < 8; ++n)
; #pragma unroll
;                 for (int j = 0; j < 4; j += 2) { const unsigned w = cvt_pk_bf16(aR[n][j], aR[n][j + 1]);
;                     *(LAS unsigned short*)(vw + (4 * fq + j) * WROW + (16 * n + fr) * 2) = (unsigned short)(w & 0xffffu);
;                     *(LAS unsigned short*)(vw + (4 * fq + j + 1) * WROW + (16 * n + fr) * 2) = (unsigned short)(w >> 16); }
; #pragma unroll
;             for (int i = 0; i < 4; ++i) {
;                 const int t = fq + 4 * i; const size_t row = (size_t)(row0 + 16 * st + t);
;                 const u32x4 hh = *(const LAS u32x4*)(vw + t * WROW + cg * 16);
;                 const u32x4 g = *(const u32x4*)(p.P2 + row * P2W + h * 128 + cg * 8);
;                 const f32x4 o0 = (f32x4){bflo(hh.x) * bflo(g.x), bfhi(hh.x) * bfhi(g.x), bflo(hh.y) * bflo(g.y), bfhi(hh.y) * bfhi(g.y)};
;                 const f32x4 o1 = (f32x4){bflo(hh.z) * bflo(g.z), bfhi(hh.z) * bfhi(g.z), bflo(hh.w) * bflo(g.w), bfhi(hh.w) * bfhi(g.w)};
;                 *(u32x4*)(p.hl + row * LW + h * 128 + cg * 8) = pack8(o0, o1);
	v_pk_fma_f32 v[138:139], v[80:81], v[188:189], v[190:191]
	v_pk_fma_f32 v[4:5], v[106:107], v[116:117], v[128:129]
	v_cndmask_b32_e64 v0, v138, v80, s[8:9]
	v_cndmask_b32_e64 v0, v0, v72, s[6:7]
	v_cndmask_b32_e64 v0, v0, v16, s[4:5]
	v_fmac_f32_e32 v14, v11, v0
	v_fmac_f32_e32 v75, v13, v0
	v_fmac_f32_e32 v77, v15, v0
	v_fmac_f32_e32 v79, v74, v0
	v_cndmask_b32_e64 v0, v139, v81, s[8:9]
	v_cndmask_b32_e64 v0, v0, v73, s[6:7]
	v_cndmask_b32_e64 v0, v0, v17, s[4:5]
	v_fmac_f32_e32 v66, v76, v0
	v_fmac_f32_e32 v69, v67, v0
	v_fmac_f32_e32 v197, v68, v0
	v_fmac_f32_e32 v71, v70, v0
	v_cvt_pk_bf16_f32 v0, v130, v133
	ds_write_b16 v234, v0
	ds_write_b16_d16_hi v234, v0 offset:272
	v_cvt_pk_bf16_f32 v0, v135, v137
	ds_write_b16 v234, v0 offset:544
	ds_write_b16_d16_hi v234, v0 offset:816
	v_cvt_pk_bf16_f32 v0, v118, v121
	ds_write_b16 v234, v0 offset:32
	ds_write_b16_d16_hi v234, v0 offset:304
	v_cvt_pk_bf16_f32 v0, v123, v125
	ds_write_b16 v234, v0 offset:576
	ds_write_b16_d16_hi v234, v0 offset:848
	v_cvt_pk_bf16_f32 v0, v10, v111
	ds_write_b16 v234, v0 offset:64
	ds_write_b16_d16_hi v234, v0 offset:336
	v_cvt_pk_bf16_f32 v0, v113, v115
	ds_write_b16 v234, v0 offset:608
	ds_write_b16_d16_hi v234, v0 offset:880
	v_cvt_pk_bf16_f32 v0, v90, v93
	ds_write_b16 v234, v0 offset:96
	ds_write_b16_d16_hi v234, v0 offset:368
	v_cvt_pk_bf16_f32 v0, v103, v105
	ds_write_b16 v234, v0 offset:640
	ds_write_b16_d16_hi v234, v0 offset:912
	v_cvt_pk_bf16_f32 v0, v12, v95
	ds_write_b16 v234, v0 offset:128
	ds_write_b16_d16_hi v234, v0 offset:400
	v_cvt_pk_bf16_f32 v0, v97, v99
	ds_write_b16 v234, v0 offset:672
	ds_write_b16_d16_hi v234, v0 offset:944
	v_cvt_pk_bf16_f32 v0, v82, v85
	ds_write_b16 v234, v0 offset:160
	ds_write_b16_d16_hi v234, v0 offset:432
	v_cvt_pk_bf16_f32 v0, v87, v89
	ds_write_b16 v234, v0 offset:704
	ds_write_b16_d16_hi v234, v0 offset:976
	v_cvt_pk_bf16_f32 v0, v14, v75
	ds_write_b16 v234, v0 offset:192
	ds_write_b16_d16_hi v234, v0 offset:464
	v_cvt_pk_bf16_f32 v0, v77, v79
	ds_write_b16 v234, v0 offset:736
	ds_write_b16_d16_hi v234, v0 offset:1008
	v_cvt_pk_bf16_f32 v0, v66, v69
	ds_write_b16 v234, v0 offset:224
	ds_write_b16_d16_hi v234, v0 offset:496
	v_cvt_pk_bf16_f32 v0, v197, v71
	ds_write_b16 v234, v0 offset:768
	ds_write_b16_d16_hi v234, v0 offset:1040
	v_or_b32_e32 v0, s19, v203
	ds_read_b128 v[10:13], v235
	s_waitcnt lgkmcnt(14)
	v_pk_fma_f32 v[8:9], v[138:139], v[192:193], v[194:195]
	s_waitcnt lgkmcnt(0)
	v_lshlrev_b32_e32 v67, 16, v10
	v_and_b32_e32 v10, 0xffff0000, v10
	s_waitcnt vmcnt(11)
	v_lshlrev_b32_e32 v66, 16, v240
	v_and_b32_e32 v240, 0xffff0000, v240
	v_mul_f32_e32 v66, v66, v67
	v_mul_f32_e32 v10, v240, v10
	v_lshlrev_b32_e32 v240, 16, v241
	v_lshlrev_b32_e32 v67, 16, v11
	v_and_b32_e32 v241, 0xffff0000, v241
	v_and_b32_e32 v11, 0xffff0000, v11
	v_mul_f32_e32 v240, v240, v67
	v_mul_f32_e32 v11, v241, v11
	v_lshlrev_b32_e32 v241, 16, v242
	v_lshlrev_b32_e32 v67, 16, v12
	v_and_b32_e32 v242, 0xffff0000, v242
	v_and_b32_e32 v12, 0xffff0000, v12
	v_mul_f32_e32 v241, v241, v67
	v_mul_f32_e32 v12, v242, v12
	v_lshlrev_b32_e32 v242, 16, v243
	v_lshlrev_b32_e32 v67, 16, v13
	v_and_b32_e32 v243, 0xffff0000, v243
	v_and_b32_e32 v13, 0xffff0000, v13
	v_mul_f32_e32 v13, v243, v13
	v_cvt_pk_bf16_f32 v10, v66, v10
	v_cvt_pk_bf16_f32 v11, v240, v11
	v_cvt_pk_bf16_f32 v12, v241, v12
	v_mad_i64_i32 v[14:15], s[20:21], v0, s40, v[154:155]
	v_or_b32_e32 v0, s19, v225
	v_mul_f32_e32 v242, v242, v67
	v_cvt_pk_bf16_f32 v13, v242, v13
	global_store_dwordx4 v[14:15], v[10:13], off sc1
	ds_read_b128 v[10:13], v235 offset:1088
	s_waitcnt lgkmcnt(0)
; #define LAS __attribute__((address_space(3)))
; __device__ __forceinline__ float bflo(unsigned w) { return __uint_as_float(w << 16); }
; __device__ __forceinline__ float bfhi(unsigned w) { return __uint_as_float(w & 0xffff0000u); }
; __device__ __forceinline__ u32x4 pack8(const f32x4 a, const f32x4 b) { u32x4 w; w.x = cvt_pk_bf16(a[0], a[1]); w.y = cvt_pk_bf16(a[2], a[3]); w.z = cvt_pk_bf16(b[0], b[1]); w.w = cvt_pk_bf16(b[2], b[3]); return w; }
; template <int PASS> __device__ __forceinline__ void lru_wave_item(LAS unsigned char* lds, LAS unsigned char* vw, int b, int c, int h, const MixP& p, int lane, float (&Hrun)[8], bool cont) {
;     ...
;             for (int i = 0; i < 4; ++i) {
;                 const int t = fq + 4 * i; const size_t row = (size_t)(row0 + 16 * st + t);
;                 const u32x4 hh = *(const LAS u32x4*)(vw + t * WROW + cg * 16);
;                 const u32x4 g = *(const u32x4*)(p.P2 + row * P2W + h * 128 + cg * 8);
;                 const f32x4 o0 = (f32x4){bflo(hh.x) * bflo(g.x), bfhi(hh.x) * bfhi(g.x), bflo(hh.y) * bflo(g.y), bfhi(hh.y) * bfhi(g.y)};
;                 const f32x4 o1 = (f32x4){bflo(hh.z) * bflo(g.z), bfhi(hh.z) * bfhi(g.z), bflo(hh.w) * bflo(g.w), bfhi(hh.w) * bfhi(g.w)};
;                 *(u32x4*)(p.hl + row * LW + h * 128 + cg * 8) = pack8(o0, o1);
;             }
; template <int PASS> __device__ __forceinline__ void lru_pass(LAS unsigned char* lds, const MixP& p, const Args& a, int cv_layer, bf16_t* cv_slot, unsigned* cv_counter) {
;     ...
;             for (int j = jlo; j < jhi; ++j) lru_wave_item<PASS>(lds, vw, j / NCH, j % NCH, h, p, lane, Hrun, j > jlo && (j % NCH) != 0);
	v_lshlrev_b32_e32 v66, 16, v10
	v_and_b32_e32 v10, 0xffff0000, v10
	s_waitcnt vmcnt(11)
	v_lshlrev_b32_e32 v67, 16, v244
	v_and_b32_e32 v244, 0xffff0000, v244
	v_mul_f32_e32 v66, v67, v66
	v_mul_f32_e32 v10, v244, v10
	v_lshlrev_b32_e32 v244, 16, v11
	v_lshlrev_b32_e32 v67, 16, v245
	v_and_b32_e32 v245, 0xffff0000, v245
	v_and_b32_e32 v11, 0xffff0000, v11
	v_mul_f32_e32 v244, v67, v244
	v_mul_f32_e32 v11, v245, v11
	v_lshlrev_b32_e32 v245, 16, v12
	v_lshlrev_b32_e32 v67, 16, v246
	v_and_b32_e32 v246, 0xffff0000, v246
	v_and_b32_e32 v12, 0xffff0000, v12
	v_mul_f32_e32 v245, v67, v245
	v_mul_f32_e32 v12, v246, v12
	v_lshlrev_b32_e32 v246, 16, v13
	v_lshlrev_b32_e32 v67, 16, v247
	v_and_b32_e32 v247, 0xffff0000, v247
	v_and_b32_e32 v13, 0xffff0000, v13
	v_mul_f32_e32 v13, v247, v13
	v_cvt_pk_bf16_f32 v10, v66, v10
	v_cvt_pk_bf16_f32 v11, v244, v11
	v_cvt_pk_bf16_f32 v12, v245, v12
	v_mad_i64_i32 v[14:15], s[20:21], v0, s40, v[154:155]
	v_or_b32_e32 v0, s19, v226
	v_mul_f32_e32 v246, v67, v246
	v_cvt_pk_bf16_f32 v13, v246, v13
	global_store_dwordx4 v[14:15], v[10:13], off sc1
	ds_read_b128 v[10:13], v235 offset:2176
	s_waitcnt lgkmcnt(0)
	v_lshlrev_b32_e32 v66, 16, v10
	v_and_b32_e32 v10, 0xffff0000, v10
	s_waitcnt vmcnt(11)
	v_lshlrev_b32_e32 v67, 16, v248
	v_and_b32_e32 v248, 0xffff0000, v248
	v_mul_f32_e32 v66, v67, v66
	v_mul_f32_e32 v10, v248, v10
	v_lshlrev_b32_e32 v248, 16, v11
	v_lshlrev_b32_e32 v67, 16, v249
	v_and_b32_e32 v249, 0xffff0000, v249
	v_and_b32_e32 v11, 0xffff0000, v11
	v_mul_f32_e32 v248, v67, v248
	v_mul_f32_e32 v11, v249, v11
	v_lshlrev_b32_e32 v249, 16, v12
	v_lshlrev_b32_e32 v67, 16, v250
	v_and_b32_e32 v250, 0xffff0000, v250
	v_and_b32_e32 v12, 0xffff0000, v12
	v_mul_f32_e32 v249, v67, v249
	v_mul_f32_e32 v12, v250, v12
	v_lshlrev_b32_e32 v250, 16, v13
	v_lshlrev_b32_e32 v67, 16, v251
	v_and_b32_e32 v251, 0xffff0000, v251
	v_and_b32_e32 v13, 0xffff0000, v13
	v_mul_f32_e32 v13, v251, v13
	v_cvt_pk_bf16_f32 v10, v66, v10
	v_cvt_pk_bf16_f32 v11, v248, v11
	v_cvt_pk_bf16_f32 v12, v249, v12
	v_mad_i64_i32 v[14:15], s[20:21], v0, s40, v[154:155]
	v_or_b32_e32 v0, s19, v227
	v_mul_f32_e32 v250, v67, v250
	v_cvt_pk_bf16_f32 v13, v250, v13
	global_store_dwordx4 v[14:15], v[10:13], off sc1
	ds_read_b128 v[10:13], v235 offset:3264
	s_mov_b32 s19, 16
	s_waitcnt lgkmcnt(0)
	v_lshlrev_b32_e32 v66, 16, v10
	v_and_b32_e32 v10, 0xffff0000, v10
	s_waitcnt vmcnt(10)
	v_lshlrev_b32_e32 v67, 16, v206
	v_and_b32_e32 v206, 0xffff0000, v206
	v_mul_f32_e32 v66, v67, v66
	v_mul_f32_e32 v10, v206, v10
	v_lshlrev_b32_e32 v206, 16, v11
	v_lshlrev_b32_e32 v67, 16, v207
	v_and_b32_e32 v207, 0xffff0000, v207
	v_and_b32_e32 v11, 0xffff0000, v11
	v_mul_f32_e32 v206, v67, v206
	v_mul_f32_e32 v11, v207, v11
	v_lshlrev_b32_e32 v207, 16, v12
	v_lshlrev_b32_e32 v67, 16, v210
	v_and_b32_e32 v210, 0xffff0000, v210
	v_and_b32_e32 v12, 0xffff0000, v12
	v_mul_f32_e32 v207, v67, v207
	v_mul_f32_e32 v12, v210, v12
	v_lshlrev_b32_e32 v210, 16, v13
	v_lshlrev_b32_e32 v67, 16, v211
	v_and_b32_e32 v211, 0xffff0000, v211
	v_and_b32_e32 v13, 0xffff0000, v13
	v_mul_f32_e32 v13, v211, v13
	v_mul_f32_e32 v210, v67, v210
	v_cvt_pk_bf16_f32 v10, v66, v10
	v_cvt_pk_bf16_f32 v11, v206, v11
	v_cvt_pk_bf16_f32 v12, v207, v12
	v_cvt_pk_bf16_f32 v13, v210, v13
	v_mad_i64_i32 v[14:15], s[20:21], v0, s40, v[154:155]
	global_store_dwordx4 v[14:15], v[10:13], off sc1
	v_mov_b64_e32 v[16:17], v[8:9]
	v_mov_b64_e32 v[14:15], v[6:7]
	v_mov_b64_e32 v[12:13], v[4:5]
	v_mov_b64_e32 v[10:11], v[2:3]
	s_cbranch_vccnz .LBB0_818
	s_add_i32 s1, s1, 1
	s_cmp_ge_i32 s1, s10
	s_cbranch_scc0 .LBB0_811
	s_branch .LBB0_797

; #define PG8_STAGE(bufoff, gbase, voff) do { _Pragma("unroll") for (int _i = 0; _i < 2; ++_i) \
;         __builtin_amdgcn_global_load_lds((const unsigned*)((const char*)(gbase) + (voff)[_i]), (PG8_LAS unsigned*)(lds + (bufoff) + ldsw + _i * 8192), 16, 0, 0); } while (0)
; #define PG8_LDA(dst, b, h) do { _Pragma("unroll") for (int m = 0; m < 4; ++m) _Pragma("unroll") for (int k = 0; k < 2; ++k) dst[m][k] = *(const PG8_LAS bf16x8*)(lds + PG8_SA(b, h) + aoff + m * 2048 + k * 1024); } while (0)
; #define PG8_LDB(dst, b, h) do { _Pragma("unroll") for (int n = 0; n < 2; ++n) _Pragma("unroll") for (int k = 0; k < 2; ++k) dst[n][k] = *(const PG8_LAS bf16x8*)(lds + PG8_SB(b, h) + boff + n * 2048 + k * 1024); } while (0)
; #define PG8_MMA(ai, bj, At, Bt) do { __builtin_amdgcn_s_setprio(1); _Pragma("unroll") for (int m = 0; m < 4; ++m) _Pragma("unroll") for (int n = 0; n < 2; ++n) _Pragma("unroll") for (int k = 0; k < 2; ++k) \
;         acc[ai][bj][m][n] = __builtin_amdgcn_mfma_f32_16x16x32_bf16(Bt[n][k], At[m][k], acc[ai][bj][m][n], 0, 0, 0); __builtin_amdgcn_s_setprio(0); } while (0)
; #define PG8_WAIT_V(n) asm volatile("s_waitcnt vmcnt(" #n ")" ::: "memory")
; #define PG8_BAR __builtin_amdgcn_s_barrier()
; template <class Epi, class Sched, bool ALIGN_EPI = false, bool SP2 = false>
; __device__ __forceinline__ void gemm_phase(PG8_LAS unsigned char* lds, const Gemm g, const Sched& S, const Epi& E) {
;     ...
;         for (int t = 0; t < nt; t += 2) {
;             const bool last = (t == nt - 2);
;             const char* a1 = cA + (size_t)(t + 1) * kstep;
;             const char* a2 = last ? nA : cA + (size_t)(t + 2) * kstep; const char* b2 = last ? nB : cB + (size_t)(t + 2) * kstep;
;             const char* a3 = a2 + kstep; const char* b3 = b2 + kstep;
;             if (last && has_next) S.a_ready(nxt);
;             if constexpr (SP2) {
;             PG8_LDB(B0, 0, 0); PG8_LDB(B1, 0, 1); PG8_SCHED; PG8_LDA(At, 0, 0); PG8_STAGE(PG8_SA(1, 1), a1 + hstep, voffA);
;             PG8_WAIT_V(8); PG8_WAIT_L(0); PG8_BAR; PG8_MMA(0, 0, At, B0); PG8_MMA(0, 1, At, B1); PG8_BAR; PG8_SCHED;
;             PG8_LDA(At, 0, 1); PG8_STAGE(PG8_SB(0, 0), b2, voffB); PG8_STAGE(PG8_SB(0, 1), b2 + hstep, voffB); PG8_STAGE(PG8_SA(0, 0), a2, voffA);
;             PG8_WAIT_V(8); PG8_WAIT_L(0); PG8_BAR; PG8_MMA(1, 0, At, B0); PG8_MMA(1, 1, At, B1); PG8_BAR; PG8_SCHED;
.LBB0_891:
	s_add_u32 s18, s16, 0xfffe0080
	s_addc_u32 s19, s17, -1
	s_add_i32 s46, 0, 0x10000
	s_cmp_eq_u32 s45, 4
	s_cselect_b32 s21, s9, s19
	s_cselect_b32 s20, s41, s18
	v_add_u32_e32 v148, s46, v151
	s_cselect_b32 s19, s7, s44
	s_cselect_b32 s18, s42, s43
	s_add_i32 s48, 0, 0x14000
	ds_read_b128 v[138:141], v148
	ds_read_b128 v[144:147], v148 offset:1024
	ds_read_b128 v[154:157], v148 offset:2048
	ds_read_b128 v[158:161], v148 offset:3072
	v_add_u32_e32 v148, s48, v151
	ds_read_b128 v[162:165], v148
	ds_read_b128 v[166:169], v148 offset:1024
	ds_read_b128 v[170:173], v148 offset:2048
	ds_read_b128 v[174:177], v148 offset:3072
	v_lshl_add_u64 v[148:149], s[16:17], 0, v[136:137]
	s_add_i32 m0, s27, 0xc000
	ds_read_b128 v[178:181], v153
	ds_read_b128 v[182:185], v153 offset:1024
	ds_read_b128 v[186:189], v153 offset:2048
	ds_read_b128 v[190:193], v153 offset:3072
	ds_read_b128 v[194:197], v153 offset:4096
	ds_read_b128 v[198:201], v153 offset:5120
	ds_read_b128 v[202:205], v153 offset:6144
	ds_read_b128 v[224:227], v153 offset:7168
	global_load_lds_dwordx4 v[148:149], off
	v_lshl_add_u64 v[148:149], s[16:17], 0, v[142:143]
	s_add_i32 m0, s27, 0xe000
	s_nop 0
	global_load_lds_dwordx4 v[148:149], off
	s_waitcnt vmcnt(8)
	s_waitcnt lgkmcnt(0)
	s_setprio 1
	s_barrier
	v_mfma_f32_16x16x32_bf16 v[126:129], v[138:141], v[178:181], v[126:129]
	v_mfma_f32_16x16x32_bf16 v[122:125], v[154:157], v[178:181], v[122:125]
	v_mfma_f32_16x16x32_bf16 v[110:113], v[138:141], v[186:189], v[110:113]
	v_mfma_f32_16x16x32_bf16 v[106:109], v[154:157], v[186:189], v[106:109]
	v_mfma_f32_16x16x32_bf16 v[94:97], v[138:141], v[194:197], v[94:97]
	v_mfma_f32_16x16x32_bf16 v[90:93], v[154:157], v[194:197], v[90:93]
	v_mfma_f32_16x16x32_bf16 v[78:81], v[138:141], v[202:205], v[78:81]
	v_mfma_f32_16x16x32_bf16 v[74:77], v[154:157], v[202:205], v[74:77]
	v_mfma_f32_16x16x32_bf16 v[126:129], v[144:147], v[182:185], v[126:129]
	v_mfma_f32_16x16x32_bf16 v[122:125], v[158:161], v[182:185], v[122:125]
	v_mfma_f32_16x16x32_bf16 v[110:113], v[144:147], v[190:193], v[110:113]
	v_mfma_f32_16x16x32_bf16 v[106:109], v[158:161], v[190:193], v[106:109]
	v_mfma_f32_16x16x32_bf16 v[94:97], v[144:147], v[198:201], v[94:97]
	v_mfma_f32_16x16x32_bf16 v[90:93], v[158:161], v[198:201], v[90:93]
	v_mfma_f32_16x16x32_bf16 v[78:81], v[144:147], v[224:227], v[78:81]
	v_mfma_f32_16x16x32_bf16 v[74:77], v[158:161], v[224:227], v[74:77]
	v_mfma_f32_16x16x32_bf16 v[118:121], v[162:165], v[178:181], v[118:121]
	v_mfma_f32_16x16x32_bf16 v[114:117], v[170:173], v[178:181], v[114:117]
	v_mfma_f32_16x16x32_bf16 v[102:105], v[162:165], v[186:189], v[102:105]
	v_mfma_f32_16x16x32_bf16 v[98:101], v[170:173], v[186:189], v[98:101]
	v_mfma_f32_16x16x32_bf16 v[86:89], v[162:165], v[194:197], v[86:89]
	v_mfma_f32_16x16x32_bf16 v[82:85], v[170:173], v[194:197], v[82:85]
	v_mfma_f32_16x16x32_bf16 v[70:73], v[162:165], v[202:205], v[70:73]
	v_mfma_f32_16x16x32_bf16 v[66:69], v[170:173], v[202:205], v[66:69]
	v_mfma_f32_16x16x32_bf16 v[118:121], v[166:169], v[182:185], v[118:121]
	v_mfma_f32_16x16x32_bf16 v[114:117], v[174:177], v[182:185], v[114:117]
	v_mfma_f32_16x16x32_bf16 v[102:105], v[166:169], v[190:193], v[102:105]
	v_mfma_f32_16x16x32_bf16 v[98:101], v[174:177], v[190:193], v[98:101]
	v_mfma_f32_16x16x32_bf16 v[86:89], v[166:169], v[198:201], v[86:89]
	v_mfma_f32_16x16x32_bf16 v[82:85], v[174:177], v[198:201], v[82:85]
	v_mfma_f32_16x16x32_bf16 v[70:73], v[166:169], v[224:227], v[70:73]
	v_mfma_f32_16x16x32_bf16 v[66:69], v[174:177], v[224:227], v[66:69]
	s_barrier
	s_setprio 0
	s_add_i32 s46, s46, s26
	v_lshl_add_u64 v[148:149], s[18:19], 0, v[0:1]
	s_mov_b32 m0, s46
	ds_read_b128 v[178:181], v153 offset:16384
	ds_read_b128 v[182:185], v153 offset:17408
	ds_read_b128 v[186:189], v153 offset:18432
	ds_read_b128 v[190:193], v153 offset:19456
	ds_read_b128 v[194:197], v153 offset:20480
	ds_read_b128 v[198:201], v153 offset:21504
	ds_read_b128 v[202:205], v153 offset:22528
	ds_read_b128 v[224:227], v153 offset:23552
	global_load_lds_dwordx4 v[148:149], off
	s_add_i32 m0, s46, 0x2000
	s_add_u32 s46, s18, 0x20000
	v_lshl_add_u64 v[228:229], s[18:19], 0, v[134:135]
	s_addc_u32 s47, s19, 0
	s_add_i32 s48, s48, s26
	global_load_lds_dwordx4 v[228:229], off
	v_lshl_add_u64 v[230:231], s[46:47], 0, v[0:1]
	s_mov_b32 m0, s48
	v_lshl_add_u64 v[232:233], s[20:21], 0, v[132:133]
	global_load_lds_dwordx4 v[230:231], off
	v_lshl_add_u64 v[230:231], s[46:47], 0, v[134:135]
	s_add_i32 m0, s48, 0x2000
	s_nop 0
	global_load_lds_dwordx4 v[230:231], off
	v_lshl_add_u64 v[230:231], s[20:21], 0, v[130:131]
	s_mov_b32 m0, s27
	s_nop 0
	global_load_lds_dwordx4 v[230:231], off
	s_mov_b32 m0, s28
	s_nop 0
	global_load_lds_dwordx4 v[232:233], off
	s_waitcnt vmcnt(8)
	s_waitcnt lgkmcnt(0)
	s_setprio 1
	s_barrier
; #define PG8_STAGE(bufoff, gbase, voff) do { _Pragma("unroll") for (int _i = 0; _i < 2; ++_i) \
;         __builtin_amdgcn_global_load_lds((const unsigned*)((const char*)(gbase) + (voff)[_i]), (PG8_LAS unsigned*)(lds + (bufoff) + ldsw + _i * 8192), 16, 0, 0); } while (0)
; #define PG8_LDA(dst, b, h) do { _Pragma("unroll") for (int m = 0; m < 4; ++m) _Pragma("unroll") for (int k = 0; k < 2; ++k) dst[m][k] = *(const PG8_LAS bf16x8*)(lds + PG8_SA(b, h) + aoff + m * 2048 + k * 1024); } while (0)
; #define PG8_LDB(dst, b, h) do { _Pragma("unroll") for (int n = 0; n < 2; ++n) _Pragma("unroll") for (int k = 0; k < 2; ++k) dst[n][k] = *(const PG8_LAS bf16x8*)(lds + PG8_SB(b, h) + boff + n * 2048 + k * 1024); } while (0)
; #define PG8_MMA(ai, bj, At, Bt) do { __builtin_amdgcn_s_setprio(1); _Pragma("unroll") for (int m = 0; m < 4; ++m) _Pragma("unroll") for (int n = 0; n < 2; ++n) _Pragma("unroll") for (int k = 0; k < 2; ++k) \
;         acc[ai][bj][m][n] = __builtin_amdgcn_mfma_f32_16x16x32_bf16(Bt[n][k], At[m][k], acc[ai][bj][m][n], 0, 0, 0); __builtin_amdgcn_s_setprio(0); } while (0)
; #define PG8_WAIT_V(n) asm volatile("s_waitcnt vmcnt(" #n ")" ::: "memory")
; #define PG8_WAIT_L(n) asm volatile("s_waitcnt lgkmcnt(" #n ")" ::: "memory")
; #define PG8_BAR __builtin_amdgcn_s_barrier()
; #define PG8_SCHED __builtin_amdgcn_sched_barrier(0)
; template <class Epi, class Sched, bool ALIGN_EPI = false, bool SP2 = false>
; __device__ __forceinline__ void gemm_phase(PG8_LAS unsigned char* lds, const Gemm g, const Sched& S, const Epi& E) {
;     ...
;             PG8_LDA(At, 0, 1); PG8_STAGE(PG8_SB(0, 0), b2, voffB); PG8_STAGE(PG8_SB(0, 1), b2 + hstep, voffB); PG8_STAGE(PG8_SA(0, 0), a2, voffA);
;             PG8_WAIT_V(8); PG8_WAIT_L(0); PG8_BAR; PG8_MMA(1, 0, At, B0); PG8_MMA(1, 1, At, B1); PG8_BAR; PG8_SCHED;
;             PG8_LDB(B0, 1, 0); PG8_LDB(B1, 1, 1); PG8_SCHED; PG8_LDA(At, 1, 0); PG8_STAGE(PG8_SA(0, 1), a2 + hstep, voffA);
;             PG8_WAIT_V(8); PG8_WAIT_L(0); PG8_BAR; PG8_MMA(0, 0, At, B0); PG8_MMA(0, 1, At, B1); PG8_BAR; PG8_SCHED;
	v_mfma_f32_16x16x32_bf16 v[62:65], v[138:141], v[178:181], v[62:65]
	v_mfma_f32_16x16x32_bf16 v[58:61], v[154:157], v[178:181], v[58:61]
	v_mfma_f32_16x16x32_bf16 v[46:49], v[138:141], v[186:189], v[46:49]
	v_mfma_f32_16x16x32_bf16 v[42:45], v[154:157], v[186:189], v[42:45]
	v_mfma_f32_16x16x32_bf16 v[30:33], v[138:141], v[194:197], v[30:33]
	v_mfma_f32_16x16x32_bf16 v[26:29], v[154:157], v[194:197], v[26:29]
	v_mfma_f32_16x16x32_bf16 v[14:17], v[138:141], v[202:205], v[14:17]
	v_mfma_f32_16x16x32_bf16 v[10:13], v[154:157], v[202:205], v[10:13]
	v_mfma_f32_16x16x32_bf16 v[62:65], v[144:147], v[182:185], v[62:65]
	v_mfma_f32_16x16x32_bf16 v[58:61], v[158:161], v[182:185], v[58:61]
	v_mfma_f32_16x16x32_bf16 v[46:49], v[144:147], v[190:193], v[46:49]
	v_mfma_f32_16x16x32_bf16 v[42:45], v[158:161], v[190:193], v[42:45]
	v_mfma_f32_16x16x32_bf16 v[30:33], v[144:147], v[198:201], v[30:33]
	v_mfma_f32_16x16x32_bf16 v[26:29], v[158:161], v[198:201], v[26:29]
	v_mfma_f32_16x16x32_bf16 v[14:17], v[144:147], v[224:227], v[14:17]
	v_mfma_f32_16x16x32_bf16 v[10:13], v[158:161], v[224:227], v[10:13]
	v_mfma_f32_16x16x32_bf16 v[54:57], v[162:165], v[178:181], v[54:57]
	v_mfma_f32_16x16x32_bf16 v[50:53], v[170:173], v[178:181], v[50:53]
	v_mfma_f32_16x16x32_bf16 v[38:41], v[162:165], v[186:189], v[38:41]
	v_mfma_f32_16x16x32_bf16 v[34:37], v[170:173], v[186:189], v[34:37]
	v_mfma_f32_16x16x32_bf16 v[22:25], v[162:165], v[194:197], v[22:25]
	v_mfma_f32_16x16x32_bf16 v[18:21], v[170:173], v[194:197], v[18:21]
	v_mfma_f32_16x16x32_bf16 v[6:9], v[162:165], v[202:205], v[6:9]
	v_mfma_f32_16x16x32_bf16 v[2:5], v[170:173], v[202:205], v[2:5]
	v_mfma_f32_16x16x32_bf16 v[54:57], v[166:169], v[182:185], v[54:57]
	v_mfma_f32_16x16x32_bf16 v[50:53], v[174:177], v[182:185], v[50:53]
	v_mfma_f32_16x16x32_bf16 v[38:41], v[166:169], v[190:193], v[38:41]
	v_mfma_f32_16x16x32_bf16 v[34:37], v[174:177], v[190:193], v[34:37]
	v_mfma_f32_16x16x32_bf16 v[22:25], v[166:169], v[198:201], v[22:25]
	v_mfma_f32_16x16x32_bf16 v[18:21], v[174:177], v[198:201], v[18:21]
	v_mfma_f32_16x16x32_bf16 v[6:9], v[166:169], v[224:227], v[6:9]
	v_mfma_f32_16x16x32_bf16 v[2:5], v[174:177], v[224:227], v[2:5]
	s_barrier
	s_setprio 0
	s_add_i32 s46, 0, 0x18000
	s_add_i32 s47, 0, 0x1c000
	v_add_u32_e32 v158, s46, v151
	v_add_u32_e32 v174, s47, v151
	ds_read_b128 v[138:141], v158
	ds_read_b128 v[144:147], v158 offset:1024
	ds_read_b128 v[154:157], v158 offset:2048
	ds_read_b128 v[158:161], v158 offset:3072
	ds_read_b128 v[162:165], v174
	ds_read_b128 v[166:169], v174 offset:1024
	ds_read_b128 v[170:173], v174 offset:2048
	ds_read_b128 v[174:177], v174 offset:3072
	s_add_u32 s20, s20, 0x20000
	s_addc_u32 s21, s21, 0
	s_mov_b32 m0, s29
	v_lshl_add_u64 v[234:235], s[20:21], 0, v[130:131]
	ds_read_b128 v[178:181], v153 offset:32768
	ds_read_b128 v[182:185], v153 offset:33792
	ds_read_b128 v[186:189], v153 offset:34816
	ds_read_b128 v[190:193], v153 offset:35840
	ds_read_b128 v[194:197], v153 offset:36864
	ds_read_b128 v[198:201], v153 offset:37888
	ds_read_b128 v[202:205], v153 offset:38912
	ds_read_b128 v[224:227], v153 offset:39936
	global_load_lds_dwordx4 v[234:235], off
	v_lshl_add_u64 v[234:235], s[20:21], 0, v[132:133]
	s_mov_b32 m0, s30
	s_nop 0
	global_load_lds_dwordx4 v[234:235], off
	s_waitcnt vmcnt(8)
	s_waitcnt lgkmcnt(0)
	s_setprio 1
	s_barrier
	v_mfma_f32_16x16x32_bf16 v[126:129], v[138:141], v[178:181], v[126:129]
	v_mfma_f32_16x16x32_bf16 v[122:125], v[154:157], v[178:181], v[122:125]
	v_mfma_f32_16x16x32_bf16 v[110:113], v[138:141], v[186:189], v[110:113]
	v_mfma_f32_16x16x32_bf16 v[106:109], v[154:157], v[186:189], v[106:109]
	v_mfma_f32_16x16x32_bf16 v[94:97], v[138:141], v[194:197], v[94:97]
	v_mfma_f32_16x16x32_bf16 v[90:93], v[154:157], v[194:197], v[90:93]
	v_mfma_f32_16x16x32_bf16 v[78:81], v[138:141], v[202:205], v[78:81]
	v_mfma_f32_16x16x32_bf16 v[74:77], v[154:157], v[202:205], v[74:77]
	v_mfma_f32_16x16x32_bf16 v[126:129], v[144:147], v[182:185], v[126:129]
	v_mfma_f32_16x16x32_bf16 v[122:125], v[158:161], v[182:185], v[122:125]
	v_mfma_f32_16x16x32_bf16 v[110:113], v[144:147], v[190:193], v[110:113]
	v_mfma_f32_16x16x32_bf16 v[106:109], v[158:161], v[190:193], v[106:109]
	v_mfma_f32_16x16x32_bf16 v[94:97], v[144:147], v[198:201], v[94:97]
	v_mfma_f32_16x16x32_bf16 v[90:93], v[158:161], v[198:201], v[90:93]
	v_mfma_f32_16x16x32_bf16 v[78:81], v[144:147], v[224:227], v[78:81]
	v_mfma_f32_16x16x32_bf16 v[74:77], v[158:161], v[224:227], v[74:77]
	v_mfma_f32_16x16x32_bf16 v[118:121], v[162:165], v[178:181], v[118:121]
	v_mfma_f32_16x16x32_bf16 v[114:117], v[170:173], v[178:181], v[114:117]
	v_mfma_f32_16x16x32_bf16 v[102:105], v[162:165], v[186:189], v[102:105]
	v_mfma_f32_16x16x32_bf16 v[98:101], v[170:173], v[186:189], v[98:101]
	v_mfma_f32_16x16x32_bf16 v[86:89], v[162:165], v[194:197], v[86:89]
	v_mfma_f32_16x16x32_bf16 v[82:85], v[170:173], v[194:197], v[82:85]
	v_mfma_f32_16x16x32_bf16 v[70:73], v[162:165], v[202:205], v[70:73]
	v_mfma_f32_16x16x32_bf16 v[66:69], v[170:173], v[202:205], v[66:69]
	v_mfma_f32_16x16x32_bf16 v[118:121], v[166:169], v[182:185], v[118:121]
	v_mfma_f32_16x16x32_bf16 v[114:117], v[174:177], v[182:185], v[114:117]
	v_mfma_f32_16x16x32_bf16 v[102:105], v[166:169], v[190:193], v[102:105]
	v_mfma_f32_16x16x32_bf16 v[98:101], v[174:177], v[190:193], v[98:101]
	v_mfma_f32_16x16x32_bf16 v[86:89], v[166:169], v[198:201], v[86:89]
	v_mfma_f32_16x16x32_bf16 v[82:85], v[174:177], v[198:201], v[82:85]
	v_mfma_f32_16x16x32_bf16 v[70:73], v[166:169], v[224:227], v[70:73]
	v_mfma_f32_16x16x32_bf16 v[66:69], v[174:177], v[224:227], v[66:69]
	s_barrier
; #define PG8_STAGE(bufoff, gbase, voff) do { _Pragma("unroll") for (int _i = 0; _i < 2; ++_i) \
;         __builtin_amdgcn_global_load_lds((const unsigned*)((const char*)(gbase) + (voff)[_i]), (PG8_LAS unsigned*)(lds + (bufoff) + ldsw + _i * 8192), 16, 0, 0); } while (0)
; #define PG8_LDA(dst, b, h) do { _Pragma("unroll") for (int m = 0; m < 4; ++m) _Pragma("unroll") for (int k = 0; k < 2; ++k) dst[m][k] = *(const PG8_LAS bf16x8*)(lds + PG8_SA(b, h) + aoff + m * 2048 + k * 1024); } while (0)
; #define PG8_MMA(ai, bj, At, Bt) do { __builtin_amdgcn_s_setprio(1); _Pragma("unroll") for (int m = 0; m < 4; ++m) _Pragma("unroll") for (int n = 0; n < 2; ++n) _Pragma("unroll") for (int k = 0; k < 2; ++k) \
;         acc[ai][bj][m][n] = __builtin_amdgcn_mfma_f32_16x16x32_bf16(Bt[n][k], At[m][k], acc[ai][bj][m][n], 0, 0, 0); __builtin_amdgcn_s_setprio(0); } while (0)
; #define PG8_WAIT_V(n) asm volatile("s_waitcnt vmcnt(" #n ")" ::: "memory")
; #define PG8_WAIT_L(n) asm volatile("s_waitcnt lgkmcnt(" #n ")" ::: "memory")
; #define PG8_BAR __builtin_amdgcn_s_barrier()
; #define PG8_SCHED __builtin_amdgcn_sched_barrier(0)
; template <class Epi, class Sched, bool ALIGN_EPI = false, bool SP2 = false>
; __device__ __forceinline__ void gemm_phase(PG8_LAS unsigned char* lds, const Gemm g, const Sched& S, const Epi& E) {
;     ...
;             PG8_LDA(At, 1, 1); PG8_STAGE(PG8_SB(1, 0), b3, voffB); PG8_STAGE(PG8_SB(1, 1), b3 + hstep, voffB); PG8_STAGE(PG8_SA(1, 0), a3, voffA);
;             PG8_WAIT_V(8); PG8_WAIT_L(0); PG8_BAR; PG8_MMA(1, 0, At, B0); PG8_MMA(1, 1, At, B1); PG8_BAR; PG8_SCHED;
;     __device__ __forceinline__ void operator()(const f32x4 (&acc)[2][2][4][2], const Unit& u, int wr, int wc, int fr, int fq) const {
;         const int row0 = u.pm * 256 + wr * 64 + fr, col0 = u.pn * 256 + wc * 32 + 8 * fq;
; #pragma unroll
;         for (int ai = 0; ai < 2; ++ai)
; #pragma unroll
;             for (int m = 0; m < 4; ++m) {
;                 const int row = row0 + ai * 128 + m * 16;
; #pragma unroll
;                 for (int bj = 0; bj < 2; ++bj) {
;                     const int c = col0 + bj * 128;
;                     const u32x4 g = *(const u32x4*)(G + (size_t)row * P2W + c);
	s_setprio 0
	s_add_i32 s20, s46, s26
	v_lshl_add_u64 v[148:149], v[148:149], 0, s[86:87]
	s_mov_b32 m0, s20
	ds_read_b128 v[178:181], v153 offset:49152
	ds_read_b128 v[182:185], v153 offset:50176
	ds_read_b128 v[186:189], v153 offset:51200
	ds_read_b128 v[190:193], v153 offset:52224
	ds_read_b128 v[194:197], v153 offset:53248
	ds_read_b128 v[198:201], v153 offset:54272
	ds_read_b128 v[202:205], v153 offset:55296
	ds_read_b128 v[224:227], v153 offset:56320
	global_load_lds_dwordx4 v[148:149], off
	s_add_i32 m0, s20, 0x2000
	s_add_u32 s18, s18, 0x20080
	v_lshl_add_u64 v[148:149], v[228:229], 0, s[86:87]
	s_addc_u32 s19, s19, 0
	s_add_i32 s20, s47, s26
	global_load_lds_dwordx4 v[148:149], off
	v_lshl_add_u64 v[148:149], s[18:19], 0, v[0:1]
	s_mov_b32 m0, s20
	s_nop 0
	global_load_lds_dwordx4 v[148:149], off
	v_lshl_add_u64 v[148:149], s[18:19], 0, v[134:135]
	s_add_i32 m0, s20, 0x2000
	s_nop 0
	global_load_lds_dwordx4 v[148:149], off
	v_lshl_add_u64 v[148:149], v[230:231], 0, s[86:87]
	s_mov_b32 m0, s31
	s_nop 0
	global_load_lds_dwordx4 v[148:149], off
	v_lshl_add_u64 v[148:149], v[232:233], 0, s[86:87]
	s_mov_b32 m0, s38
	s_nop 0
	global_load_lds_dwordx4 v[148:149], off
	s_waitcnt vmcnt(8)
	s_waitcnt lgkmcnt(0)
	s_setprio 1
	s_barrier
	v_mfma_f32_16x16x32_bf16 v[62:65], v[138:141], v[178:181], v[62:65]
	v_mfma_f32_16x16x32_bf16 v[58:61], v[154:157], v[178:181], v[58:61]
	v_mfma_f32_16x16x32_bf16 v[46:49], v[138:141], v[186:189], v[46:49]
	v_mfma_f32_16x16x32_bf16 v[42:45], v[154:157], v[186:189], v[42:45]
	v_mfma_f32_16x16x32_bf16 v[30:33], v[138:141], v[194:197], v[30:33]
	v_mfma_f32_16x16x32_bf16 v[26:29], v[154:157], v[194:197], v[26:29]
	v_mfma_f32_16x16x32_bf16 v[14:17], v[138:141], v[202:205], v[14:17]
	v_mfma_f32_16x16x32_bf16 v[10:13], v[154:157], v[202:205], v[10:13]
	v_mfma_f32_16x16x32_bf16 v[62:65], v[144:147], v[182:185], v[62:65]
	v_mfma_f32_16x16x32_bf16 v[58:61], v[158:161], v[182:185], v[58:61]
	v_mfma_f32_16x16x32_bf16 v[46:49], v[144:147], v[190:193], v[46:49]
	v_mfma_f32_16x16x32_bf16 v[42:45], v[158:161], v[190:193], v[42:45]
	v_mfma_f32_16x16x32_bf16 v[30:33], v[144:147], v[198:201], v[30:33]
	v_mfma_f32_16x16x32_bf16 v[26:29], v[158:161], v[198:201], v[26:29]
	v_mfma_f32_16x16x32_bf16 v[14:17], v[144:147], v[224:227], v[14:17]
	v_mfma_f32_16x16x32_bf16 v[10:13], v[158:161], v[224:227], v[10:13]
	v_mfma_f32_16x16x32_bf16 v[54:57], v[162:165], v[178:181], v[54:57]
	v_mfma_f32_16x16x32_bf16 v[50:53], v[170:173], v[178:181], v[50:53]
	v_mfma_f32_16x16x32_bf16 v[38:41], v[162:165], v[186:189], v[38:41]
	v_mfma_f32_16x16x32_bf16 v[34:37], v[170:173], v[186:189], v[34:37]
	v_mfma_f32_16x16x32_bf16 v[22:25], v[162:165], v[194:197], v[22:25]
	v_mfma_f32_16x16x32_bf16 v[18:21], v[170:173], v[194:197], v[18:21]
	v_mfma_f32_16x16x32_bf16 v[6:9], v[162:165], v[202:205], v[6:9]
	v_mfma_f32_16x16x32_bf16 v[2:5], v[170:173], v[202:205], v[2:5]
	v_mfma_f32_16x16x32_bf16 v[54:57], v[166:169], v[182:185], v[54:57]
	v_mfma_f32_16x16x32_bf16 v[50:53], v[174:177], v[182:185], v[50:53]
	v_mfma_f32_16x16x32_bf16 v[38:41], v[166:169], v[190:193], v[38:41]
	v_mfma_f32_16x16x32_bf16 v[34:37], v[174:177], v[190:193], v[34:37]
	v_mfma_f32_16x16x32_bf16 v[22:25], v[166:169], v[198:201], v[22:25]
	v_mfma_f32_16x16x32_bf16 v[18:21], v[174:177], v[198:201], v[18:21]
	v_mfma_f32_16x16x32_bf16 v[6:9], v[166:169], v[224:227], v[6:9]
	v_mfma_f32_16x16x32_bf16 v[2:5], v[174:177], v[224:227], v[2:5]
	s_barrier
	s_setprio 0
	s_add_i32 s45, s45, 2
	s_add_u32 s16, s16, 0x100
	s_addc_u32 s17, s17, 0
	s_add_u32 s43, s43, 0x100
	s_addc_u32 s44, s44, 0
	s_cmp_gt_u32 s45, 5
	s_cbranch_scc0 .LBB0_891
	v_lshl_add_u32 v140, s14, 8, v150
	v_lshl_or_b32 v141, s15, 8, v152
	v_mul_lo_u32 v138, v140, s83
	v_lshlrev_b32_e32 v139, 11, v140
	v_lshl_add_u32 v138, v141, 1, v138
	v_lshl_add_u32 v139, v141, 1, v139
	global_load_dwordx4 v[144:147], v138, s[74:75] nt
	global_load_dwordx4 v[156:159], v138, s[74:75] offset:256 nt
	v_add_u32_e32 v140, 0x1a000, v138
	global_load_dwordx4 v[160:163], v140, s[74:75] nt
	global_load_dwordx4 v[164:167], v140, s[74:75] offset:256 nt
	v_add_u32_e32 v140, 0x34000, v138
	global_load_dwordx4 v[168:171], v140, s[74:75] nt
	global_load_dwordx4 v[172:175], v140, s[74:75] offset:256 nt
	v_add_u32_e32 v140, 0x4e000, v138
	global_load_dwordx4 v[176:179], v140, s[74:75] nt
	global_load_dwordx4 v[180:183], v140, s[74:75] offset:256 nt
	v_add_u32_e32 v140, 0xd0000, v138
	global_load_dwordx4 v[184:187], v140, s[74:75] nt
	global_load_dwordx4 v[188:191], v140, s[74:75] offset:256 nt
	v_add_u32_e32 v140, 0xea000, v138
	global_load_dwordx4 v[192:195], v140, s[74:75] nt
	global_load_dwordx4 v[196:199], v140, s[74:75] offset:256 nt
	v_add_u32_e32 v140, 0x104000, v138
	global_load_dwordx4 v[200:203], v140, s[74:75] nt
	global_load_dwordx4 v[224:227], v140, s[74:75] offset:256 nt
	v_add_u32_e32 v140, 0x11e000, v138
	global_load_dwordx4 v[228:231], v140, s[74:75] nt
	global_load_dwordx4 v[232:235], v140, s[74:75] offset:256 nt
	s_and_b64 vcc, exec, s[4:5]
	s_cbranch_vccz .LBB0_894
	s_barrier

; #define PG8_STAGE(bufoff, gbase, voff) do { _Pragma("unroll") for (int _i = 0; _i < 2; ++_i) \
;         __builtin_amdgcn_global_load_lds((const unsigned*)((const char*)(gbase) + (voff)[_i]), (PG8_LAS unsigned*)(lds + (bufoff) + ldsw + _i * 8192), 16, 0, 0); } while (0)
; #define PG8_LDA(dst, b, h) do { _Pragma("unroll") for (int m = 0; m < 4; ++m) _Pragma("unroll") for (int k = 0; k < 2; ++k) dst[m][k] = *(const PG8_LAS bf16x8*)(lds + PG8_SA(b, h) + aoff + m * 2048 + k * 1024); } while (0)
; #define PG8_LDB(dst, b, h) do { _Pragma("unroll") for (int n = 0; n < 2; ++n) _Pragma("unroll") for (int k = 0; k < 2; ++k) dst[n][k] = *(const PG8_LAS bf16x8*)(lds + PG8_SB(b, h) + boff + n * 2048 + k * 1024); } while (0)
; #define PG8_MMA(ai, bj, At, Bt) do { __builtin_amdgcn_s_setprio(1); _Pragma("unroll") for (int m = 0; m < 4; ++m) _Pragma("unroll") for (int n = 0; n < 2; ++n) _Pragma("unroll") for (int k = 0; k < 2; ++k) \
;         acc[ai][bj][m][n] = __builtin_amdgcn_mfma_f32_16x16x32_bf16(Bt[n][k], At[m][k], acc[ai][bj][m][n], 0, 0, 0); __builtin_amdgcn_s_setprio(0); } while (0)
; #define PG8_WAIT_V(n) asm volatile("s_waitcnt vmcnt(" #n ")" ::: "memory")
; #define PG8_BAR __builtin_amdgcn_s_barrier()
; template <class Epi, class Sched, bool ALIGN_EPI = false, bool SP2 = false>
; __device__ __forceinline__ void gemm_phase(PG8_LAS unsigned char* lds, const Gemm g, const Sched& S, const Epi& E) {
;     ...
;         for (int t = 0; t < nt; t += 2) {
;             const bool last = (t == nt - 2);
;             const char* a1 = cA + (size_t)(t + 1) * kstep;
;             const char* a2 = last ? nA : cA + (size_t)(t + 2) * kstep; const char* b2 = last ? nB : cB + (size_t)(t + 2) * kstep;
;             const char* a3 = a2 + kstep; const char* b3 = b2 + kstep;
;             if (last && has_next) S.a_ready(nxt);
;             if constexpr (SP2) {
;             PG8_LDB(B0, 0, 0); PG8_LDB(B1, 0, 1); PG8_SCHED; PG8_LDA(At, 0, 0); PG8_STAGE(PG8_SA(1, 1), a1 + hstep, voffA);
;             PG8_WAIT_V(8); PG8_WAIT_L(0); PG8_BAR; PG8_MMA(0, 0, At, B0); PG8_MMA(0, 1, At, B1); PG8_BAR; PG8_SCHED;
;             PG8_LDA(At, 0, 1); PG8_STAGE(PG8_SB(0, 0), b2, voffB); PG8_STAGE(PG8_SB(0, 1), b2 + hstep, voffB); PG8_STAGE(PG8_SA(0, 0), a2, voffA);
;             PG8_WAIT_V(8); PG8_WAIT_L(0); PG8_BAR; PG8_MMA(1, 0, At, B0); PG8_MMA(1, 1, At, B1); PG8_BAR; PG8_SCHED;
.LBB0_919:
	s_add_u32 s12, s10, 0x100
	s_addc_u32 s13, s11, 0
	s_add_i32 s44, 0, 0x10000
	s_cmp_eq_u32 s43, 16
	s_cselect_b32 s17, s5, s13
	s_cselect_b32 s16, s4, s12
	v_add_u32_e32 v148, s44, v151
	s_cselect_b32 s15, s9, s42
	s_cselect_b32 s14, s8, s41
	s_add_i32 s45, 0, 0x14000
	ds_read_b128 v[138:141], v148
	ds_read_b128 v[144:147], v148 offset:1024
	ds_read_b128 v[154:157], v148 offset:2048
	ds_read_b128 v[158:161], v148 offset:3072
	v_add_u32_e32 v148, s45, v151
	ds_read_b128 v[162:165], v148
	ds_read_b128 v[166:169], v148 offset:1024
	ds_read_b128 v[170:173], v148 offset:2048
	ds_read_b128 v[174:177], v148 offset:3072
	v_lshl_add_u64 v[148:149], s[10:11], 0, v[136:137]
	s_add_i32 m0, s23, 0xc000
	ds_read_b128 v[178:181], v153
	ds_read_b128 v[182:185], v153 offset:1024
	ds_read_b128 v[186:189], v153 offset:2048
	ds_read_b128 v[190:193], v153 offset:3072
	ds_read_b128 v[194:197], v153 offset:4096
	ds_read_b128 v[198:201], v153 offset:5120
	ds_read_b128 v[202:205], v153 offset:6144
	ds_read_b128 v[224:227], v153 offset:7168
	global_load_lds_dwordx4 v[148:149], off
	v_lshl_add_u64 v[148:149], s[10:11], 0, v[142:143]
	s_add_i32 m0, s23, 0xe000
	s_nop 0
	global_load_lds_dwordx4 v[148:149], off
	s_waitcnt vmcnt(8)
	s_waitcnt lgkmcnt(0)
	s_setprio 1
	s_barrier
	v_mfma_f32_16x16x32_bf16 v[126:129], v[138:141], v[178:181], v[126:129]
	v_mfma_f32_16x16x32_bf16 v[122:125], v[154:157], v[178:181], v[122:125]
	v_mfma_f32_16x16x32_bf16 v[110:113], v[138:141], v[186:189], v[110:113]
	v_mfma_f32_16x16x32_bf16 v[106:109], v[154:157], v[186:189], v[106:109]
	v_mfma_f32_16x16x32_bf16 v[94:97], v[138:141], v[194:197], v[94:97]
	v_mfma_f32_16x16x32_bf16 v[90:93], v[154:157], v[194:197], v[90:93]
	v_mfma_f32_16x16x32_bf16 v[78:81], v[138:141], v[202:205], v[78:81]
	v_mfma_f32_16x16x32_bf16 v[74:77], v[154:157], v[202:205], v[74:77]
	v_mfma_f32_16x16x32_bf16 v[126:129], v[144:147], v[182:185], v[126:129]
	v_mfma_f32_16x16x32_bf16 v[122:125], v[158:161], v[182:185], v[122:125]
	v_mfma_f32_16x16x32_bf16 v[110:113], v[144:147], v[190:193], v[110:113]
	v_mfma_f32_16x16x32_bf16 v[106:109], v[158:161], v[190:193], v[106:109]
	v_mfma_f32_16x16x32_bf16 v[94:97], v[144:147], v[198:201], v[94:97]
	v_mfma_f32_16x16x32_bf16 v[90:93], v[158:161], v[198:201], v[90:93]
	v_mfma_f32_16x16x32_bf16 v[78:81], v[144:147], v[224:227], v[78:81]
	v_mfma_f32_16x16x32_bf16 v[74:77], v[158:161], v[224:227], v[74:77]
	v_mfma_f32_16x16x32_bf16 v[118:121], v[162:165], v[178:181], v[118:121]
	v_mfma_f32_16x16x32_bf16 v[114:117], v[170:173], v[178:181], v[114:117]
	v_mfma_f32_16x16x32_bf16 v[102:105], v[162:165], v[186:189], v[102:105]
	v_mfma_f32_16x16x32_bf16 v[98:101], v[170:173], v[186:189], v[98:101]
	v_mfma_f32_16x16x32_bf16 v[86:89], v[162:165], v[194:197], v[86:89]
	v_mfma_f32_16x16x32_bf16 v[82:85], v[170:173], v[194:197], v[82:85]
	v_mfma_f32_16x16x32_bf16 v[70:73], v[162:165], v[202:205], v[70:73]
	v_mfma_f32_16x16x32_bf16 v[66:69], v[170:173], v[202:205], v[66:69]
	v_mfma_f32_16x16x32_bf16 v[118:121], v[166:169], v[182:185], v[118:121]
	v_mfma_f32_16x16x32_bf16 v[114:117], v[174:177], v[182:185], v[114:117]
	v_mfma_f32_16x16x32_bf16 v[102:105], v[166:169], v[190:193], v[102:105]
	v_mfma_f32_16x16x32_bf16 v[98:101], v[174:177], v[190:193], v[98:101]
	v_mfma_f32_16x16x32_bf16 v[86:89], v[166:169], v[198:201], v[86:89]
	v_mfma_f32_16x16x32_bf16 v[82:85], v[174:177], v[198:201], v[82:85]
	v_mfma_f32_16x16x32_bf16 v[70:73], v[166:169], v[224:227], v[70:73]
	v_mfma_f32_16x16x32_bf16 v[66:69], v[174:177], v[224:227], v[66:69]
	s_barrier
	s_setprio 0
	s_add_i32 s10, s44, s20
	v_lshl_add_u64 v[148:149], s[14:15], 0, v[0:1]
	s_mov_b32 m0, s10
	ds_read_b128 v[178:181], v153 offset:16384
	ds_read_b128 v[182:185], v153 offset:17408
	ds_read_b128 v[186:189], v153 offset:18432
	ds_read_b128 v[190:193], v153 offset:19456
	ds_read_b128 v[194:197], v153 offset:20480
	ds_read_b128 v[198:201], v153 offset:21504
	ds_read_b128 v[202:205], v153 offset:22528
	ds_read_b128 v[224:227], v153 offset:23552
	global_load_lds_dwordx4 v[148:149], off
	s_add_i32 m0, s10, 0x2000
	s_add_u32 s10, s14, 0x50000
	v_lshl_add_u64 v[228:229], s[14:15], 0, v[134:135]
	s_addc_u32 s11, s15, 0
	s_add_i32 s44, s45, s20
	global_load_lds_dwordx4 v[228:229], off
	v_lshl_add_u64 v[230:231], s[10:11], 0, v[0:1]
	s_mov_b32 m0, s44
	v_lshl_add_u64 v[232:233], s[16:17], 0, v[132:133]
	global_load_lds_dwordx4 v[230:231], off
	v_lshl_add_u64 v[230:231], s[10:11], 0, v[134:135]
	s_add_i32 m0, s44, 0x2000
	s_nop 0
	global_load_lds_dwordx4 v[230:231], off
	v_lshl_add_u64 v[230:231], s[16:17], 0, v[130:131]
	s_mov_b32 m0, s23
	s_nop 0
	global_load_lds_dwordx4 v[230:231], off
	s_mov_b32 m0, s24
	s_nop 0
	global_load_lds_dwordx4 v[232:233], off
	s_waitcnt vmcnt(8)
	s_waitcnt lgkmcnt(0)
	s_setprio 1
	s_barrier
; #define PG8_STAGE(bufoff, gbase, voff) do { _Pragma("unroll") for (int _i = 0; _i < 2; ++_i) \
;         __builtin_amdgcn_global_load_lds((const unsigned*)((const char*)(gbase) + (voff)[_i]), (PG8_LAS unsigned*)(lds + (bufoff) + ldsw + _i * 8192), 16, 0, 0); } while (0)
; #define PG8_LDA(dst, b, h) do { _Pragma("unroll") for (int m = 0; m < 4; ++m) _Pragma("unroll") for (int k = 0; k < 2; ++k) dst[m][k] = *(const PG8_LAS bf16x8*)(lds + PG8_SA(b, h) + aoff + m * 2048 + k * 1024); } while (0)
; #define PG8_LDB(dst, b, h) do { _Pragma("unroll") for (int n = 0; n < 2; ++n) _Pragma("unroll") for (int k = 0; k < 2; ++k) dst[n][k] = *(const PG8_LAS bf16x8*)(lds + PG8_SB(b, h) + boff + n * 2048 + k * 1024); } while (0)
; #define PG8_MMA(ai, bj, At, Bt) do { __builtin_amdgcn_s_setprio(1); _Pragma("unroll") for (int m = 0; m < 4; ++m) _Pragma("unroll") for (int n = 0; n < 2; ++n) _Pragma("unroll") for (int k = 0; k < 2; ++k) \
;         acc[ai][bj][m][n] = __builtin_amdgcn_mfma_f32_16x16x32_bf16(Bt[n][k], At[m][k], acc[ai][bj][m][n], 0, 0, 0); __builtin_amdgcn_s_setprio(0); } while (0)
; #define PG8_WAIT_V(n) asm volatile("s_waitcnt vmcnt(" #n ")" ::: "memory")
; #define PG8_WAIT_L(n) asm volatile("s_waitcnt lgkmcnt(" #n ")" ::: "memory")
; #define PG8_BAR __builtin_amdgcn_s_barrier()
; #define PG8_SCHED __builtin_amdgcn_sched_barrier(0)
; template <class Epi, class Sched, bool ALIGN_EPI = false, bool SP2 = false>
; __device__ __forceinline__ void gemm_phase(PG8_LAS unsigned char* lds, const Gemm g, const Sched& S, const Epi& E) {
;     ...
;             PG8_LDA(At, 0, 1); PG8_STAGE(PG8_SB(0, 0), b2, voffB); PG8_STAGE(PG8_SB(0, 1), b2 + hstep, voffB); PG8_STAGE(PG8_SA(0, 0), a2, voffA);
;             PG8_WAIT_V(8); PG8_WAIT_L(0); PG8_BAR; PG8_MMA(1, 0, At, B0); PG8_MMA(1, 1, At, B1); PG8_BAR; PG8_SCHED;
;             PG8_LDB(B0, 1, 0); PG8_LDB(B1, 1, 1); PG8_SCHED; PG8_LDA(At, 1, 0); PG8_STAGE(PG8_SA(0, 1), a2 + hstep, voffA);
;             PG8_WAIT_V(8); PG8_WAIT_L(0); PG8_BAR; PG8_MMA(0, 0, At, B0); PG8_MMA(0, 1, At, B1); PG8_BAR; PG8_SCHED;
	v_mfma_f32_16x16x32_bf16 v[62:65], v[138:141], v[178:181], v[62:65]
	v_mfma_f32_16x16x32_bf16 v[58:61], v[154:157], v[178:181], v[58:61]
	v_mfma_f32_16x16x32_bf16 v[46:49], v[138:141], v[186:189], v[46:49]
	v_mfma_f32_16x16x32_bf16 v[42:45], v[154:157], v[186:189], v[42:45]
	v_mfma_f32_16x16x32_bf16 v[30:33], v[138:141], v[194:197], v[30:33]
	v_mfma_f32_16x16x32_bf16 v[26:29], v[154:157], v[194:197], v[26:29]
	v_mfma_f32_16x16x32_bf16 v[14:17], v[138:141], v[202:205], v[14:17]
	v_mfma_f32_16x16x32_bf16 v[10:13], v[154:157], v[202:205], v[10:13]
	v_mfma_f32_16x16x32_bf16 v[62:65], v[144:147], v[182:185], v[62:65]
	v_mfma_f32_16x16x32_bf16 v[58:61], v[158:161], v[182:185], v[58:61]
	v_mfma_f32_16x16x32_bf16 v[46:49], v[144:147], v[190:193], v[46:49]
	v_mfma_f32_16x16x32_bf16 v[42:45], v[158:161], v[190:193], v[42:45]
	v_mfma_f32_16x16x32_bf16 v[30:33], v[144:147], v[198:201], v[30:33]
	v_mfma_f32_16x16x32_bf16 v[26:29], v[158:161], v[198:201], v[26:29]
	v_mfma_f32_16x16x32_bf16 v[14:17], v[144:147], v[224:227], v[14:17]
	v_mfma_f32_16x16x32_bf16 v[10:13], v[158:161], v[224:227], v[10:13]
	v_mfma_f32_16x16x32_bf16 v[54:57], v[162:165], v[178:181], v[54:57]
	v_mfma_f32_16x16x32_bf16 v[50:53], v[170:173], v[178:181], v[50:53]
	v_mfma_f32_16x16x32_bf16 v[38:41], v[162:165], v[186:189], v[38:41]
	v_mfma_f32_16x16x32_bf16 v[34:37], v[170:173], v[186:189], v[34:37]
	v_mfma_f32_16x16x32_bf16 v[22:25], v[162:165], v[194:197], v[22:25]
	v_mfma_f32_16x16x32_bf16 v[18:21], v[170:173], v[194:197], v[18:21]
	v_mfma_f32_16x16x32_bf16 v[6:9], v[162:165], v[202:205], v[6:9]
	v_mfma_f32_16x16x32_bf16 v[2:5], v[170:173], v[202:205], v[2:5]
	v_mfma_f32_16x16x32_bf16 v[54:57], v[166:169], v[182:185], v[54:57]
	v_mfma_f32_16x16x32_bf16 v[50:53], v[174:177], v[182:185], v[50:53]
	v_mfma_f32_16x16x32_bf16 v[38:41], v[166:169], v[190:193], v[38:41]
	v_mfma_f32_16x16x32_bf16 v[34:37], v[174:177], v[190:193], v[34:37]
	v_mfma_f32_16x16x32_bf16 v[22:25], v[166:169], v[198:201], v[22:25]
	v_mfma_f32_16x16x32_bf16 v[18:21], v[174:177], v[198:201], v[18:21]
	v_mfma_f32_16x16x32_bf16 v[6:9], v[166:169], v[224:227], v[6:9]
	v_mfma_f32_16x16x32_bf16 v[2:5], v[174:177], v[224:227], v[2:5]
	s_barrier
	s_setprio 0
	s_add_i32 s44, 0, 0x18000
	s_add_i32 s45, 0, 0x1c000
	v_add_u32_e32 v158, s44, v151
	v_add_u32_e32 v174, s45, v151
	ds_read_b128 v[138:141], v158
	ds_read_b128 v[144:147], v158 offset:1024
	ds_read_b128 v[154:157], v158 offset:2048
	ds_read_b128 v[158:161], v158 offset:3072
	ds_read_b128 v[162:165], v174
	ds_read_b128 v[166:169], v174 offset:1024
	ds_read_b128 v[170:173], v174 offset:2048
	ds_read_b128 v[174:177], v174 offset:3072
	s_add_u32 s10, s16, 0x50000
	s_addc_u32 s11, s17, 0
	s_mov_b32 m0, s25
	v_lshl_add_u64 v[234:235], s[10:11], 0, v[130:131]
	ds_read_b128 v[178:181], v153 offset:32768
	ds_read_b128 v[182:185], v153 offset:33792
	ds_read_b128 v[186:189], v153 offset:34816
	ds_read_b128 v[190:193], v153 offset:35840
	ds_read_b128 v[194:197], v153 offset:36864
	ds_read_b128 v[198:201], v153 offset:37888
	ds_read_b128 v[202:205], v153 offset:38912
	ds_read_b128 v[224:227], v153 offset:39936
	global_load_lds_dwordx4 v[234:235], off
	v_lshl_add_u64 v[234:235], s[10:11], 0, v[132:133]
	s_mov_b32 m0, s26
	s_nop 0
	global_load_lds_dwordx4 v[234:235], off
	s_waitcnt vmcnt(8)
	s_waitcnt lgkmcnt(0)
	s_setprio 1
	s_barrier
	v_mfma_f32_16x16x32_bf16 v[126:129], v[138:141], v[178:181], v[126:129]
	v_mfma_f32_16x16x32_bf16 v[122:125], v[154:157], v[178:181], v[122:125]
	v_mfma_f32_16x16x32_bf16 v[110:113], v[138:141], v[186:189], v[110:113]
	v_mfma_f32_16x16x32_bf16 v[106:109], v[154:157], v[186:189], v[106:109]
	v_mfma_f32_16x16x32_bf16 v[94:97], v[138:141], v[194:197], v[94:97]
	v_mfma_f32_16x16x32_bf16 v[90:93], v[154:157], v[194:197], v[90:93]
	v_mfma_f32_16x16x32_bf16 v[78:81], v[138:141], v[202:205], v[78:81]
	v_mfma_f32_16x16x32_bf16 v[74:77], v[154:157], v[202:205], v[74:77]
	v_mfma_f32_16x16x32_bf16 v[126:129], v[144:147], v[182:185], v[126:129]
	v_mfma_f32_16x16x32_bf16 v[122:125], v[158:161], v[182:185], v[122:125]
	v_mfma_f32_16x16x32_bf16 v[110:113], v[144:147], v[190:193], v[110:113]
	v_mfma_f32_16x16x32_bf16 v[106:109], v[158:161], v[190:193], v[106:109]
	v_mfma_f32_16x16x32_bf16 v[94:97], v[144:147], v[198:201], v[94:97]
	v_mfma_f32_16x16x32_bf16 v[90:93], v[158:161], v[198:201], v[90:93]
	v_mfma_f32_16x16x32_bf16 v[78:81], v[144:147], v[224:227], v[78:81]
	v_mfma_f32_16x16x32_bf16 v[74:77], v[158:161], v[224:227], v[74:77]
	v_mfma_f32_16x16x32_bf16 v[118:121], v[162:165], v[178:181], v[118:121]
	v_mfma_f32_16x16x32_bf16 v[114:117], v[170:173], v[178:181], v[114:117]
	v_mfma_f32_16x16x32_bf16 v[102:105], v[162:165], v[186:189], v[102:105]
	v_mfma_f32_16x16x32_bf16 v[98:101], v[170:173], v[186:189], v[98:101]
	v_mfma_f32_16x16x32_bf16 v[86:89], v[162:165], v[194:197], v[86:89]
	v_mfma_f32_16x16x32_bf16 v[82:85], v[170:173], v[194:197], v[82:85]
	v_mfma_f32_16x16x32_bf16 v[70:73], v[162:165], v[202:205], v[70:73]
	v_mfma_f32_16x16x32_bf16 v[66:69], v[170:173], v[202:205], v[66:69]
	v_mfma_f32_16x16x32_bf16 v[118:121], v[166:169], v[182:185], v[118:121]
	v_mfma_f32_16x16x32_bf16 v[114:117], v[174:177], v[182:185], v[114:117]
	v_mfma_f32_16x16x32_bf16 v[102:105], v[166:169], v[190:193], v[102:105]
	v_mfma_f32_16x16x32_bf16 v[98:101], v[174:177], v[190:193], v[98:101]
	v_mfma_f32_16x16x32_bf16 v[86:89], v[166:169], v[198:201], v[86:89]
	v_mfma_f32_16x16x32_bf16 v[82:85], v[174:177], v[198:201], v[82:85]
	v_mfma_f32_16x16x32_bf16 v[70:73], v[166:169], v[224:227], v[70:73]
	v_mfma_f32_16x16x32_bf16 v[66:69], v[174:177], v[224:227], v[66:69]
	s_barrier
; #define PG8_STAGE(bufoff, gbase, voff) do { _Pragma("unroll") for (int _i = 0; _i < 2; ++_i) \
;         __builtin_amdgcn_global_load_lds((const unsigned*)((const char*)(gbase) + (voff)[_i]), (PG8_LAS unsigned*)(lds + (bufoff) + ldsw + _i * 8192), 16, 0, 0); } while (0)
; #define PG8_LDA(dst, b, h) do { _Pragma("unroll") for (int m = 0; m < 4; ++m) _Pragma("unroll") for (int k = 0; k < 2; ++k) dst[m][k] = *(const PG8_LAS bf16x8*)(lds + PG8_SA(b, h) + aoff + m * 2048 + k * 1024); } while (0)
; #define PG8_MMA(ai, bj, At, Bt) do { __builtin_amdgcn_s_setprio(1); _Pragma("unroll") for (int m = 0; m < 4; ++m) _Pragma("unroll") for (int n = 0; n < 2; ++n) _Pragma("unroll") for (int k = 0; k < 2; ++k) \
;         acc[ai][bj][m][n] = __builtin_amdgcn_mfma_f32_16x16x32_bf16(Bt[n][k], At[m][k], acc[ai][bj][m][n], 0, 0, 0); __builtin_amdgcn_s_setprio(0); } while (0)
; #define PG8_WAIT_V(n) asm volatile("s_waitcnt vmcnt(" #n ")" ::: "memory")
; #define PG8_WAIT_L(n) asm volatile("s_waitcnt lgkmcnt(" #n ")" ::: "memory")
; #define PG8_BAR __builtin_amdgcn_s_barrier()
; #define PG8_SCHED __builtin_amdgcn_sched_barrier(0)
; template <class Epi, class Sched, bool ALIGN_EPI = false, bool SP2 = false>
; __device__ __forceinline__ void gemm_phase(PG8_LAS unsigned char* lds, const Gemm g, const Sched& S, const Epi& E) {
;     ...
;             PG8_LDA(At, 1, 1); PG8_STAGE(PG8_SB(1, 0), b3, voffB); PG8_STAGE(PG8_SB(1, 1), b3 + hstep, voffB); PG8_STAGE(PG8_SA(1, 0), a3, voffA);
;             PG8_WAIT_V(8); PG8_WAIT_L(0); PG8_BAR; PG8_MMA(1, 0, At, B0); PG8_MMA(1, 1, At, B1); PG8_BAR; PG8_SCHED;
;     __device__ __forceinline__ void operator()(const f32x4 (&acc)[2][2][4][2], const Unit& u, int wr, int wc, int fr, int fq) const {
;         const int row0 = u.pm * 256 + wr * 64 + fr, col0 = u.pn * 256 + wc * 32 + 8 * fq;
; #pragma unroll
;         for (int ai = 0; ai < 2; ++ai)
; #pragma unroll
;             for (int m = 0; m < 4; ++m) {
;                 const int row = row0 + ai * 128 + m * 16;
; #pragma unroll
;                 for (int bj = 0; bj < 2; ++bj) {
;                     const int c = col0 + bj * 128;
;                     const u32x4 g = *(const u32x4*)(G + (size_t)row * P2W + c);
;                     const u32x4 t = *(const u32x4*)(T + (size_t)row * D + c);
	s_setprio 0
	s_add_i32 s10, s44, s20
	v_lshl_add_u64 v[148:149], v[148:149], 0, s[86:87]
	s_mov_b32 m0, s10
	ds_read_b128 v[178:181], v153 offset:49152
	ds_read_b128 v[182:185], v153 offset:50176
	ds_read_b128 v[186:189], v153 offset:51200
	ds_read_b128 v[190:193], v153 offset:52224
	ds_read_b128 v[194:197], v153 offset:53248
	ds_read_b128 v[198:201], v153 offset:54272
	ds_read_b128 v[202:205], v153 offset:55296
	ds_read_b128 v[224:227], v153 offset:56320
	global_load_lds_dwordx4 v[148:149], off
	s_add_i32 m0, s10, 0x2000
	s_add_u32 s10, s14, 0x50080
	v_lshl_add_u64 v[148:149], v[228:229], 0, s[86:87]
	s_addc_u32 s11, s15, 0
	s_add_i32 s14, s45, s20
	global_load_lds_dwordx4 v[148:149], off
	v_lshl_add_u64 v[148:149], s[10:11], 0, v[0:1]
	s_mov_b32 m0, s14
	s_nop 0
	global_load_lds_dwordx4 v[148:149], off
	v_lshl_add_u64 v[148:149], s[10:11], 0, v[134:135]
	s_add_i32 m0, s14, 0x2000
	s_nop 0
	global_load_lds_dwordx4 v[148:149], off
	v_lshl_add_u64 v[148:149], v[230:231], 0, s[86:87]
	s_mov_b32 m0, s27
	s_nop 0
	global_load_lds_dwordx4 v[148:149], off
	v_lshl_add_u64 v[148:149], v[232:233], 0, s[86:87]
	s_mov_b32 m0, s28
	s_nop 0
	global_load_lds_dwordx4 v[148:149], off
	s_waitcnt vmcnt(8)
	s_waitcnt lgkmcnt(0)
	s_setprio 1
	s_barrier
	v_mfma_f32_16x16x32_bf16 v[62:65], v[138:141], v[178:181], v[62:65]
	v_mfma_f32_16x16x32_bf16 v[58:61], v[154:157], v[178:181], v[58:61]
	v_mfma_f32_16x16x32_bf16 v[46:49], v[138:141], v[186:189], v[46:49]
	v_mfma_f32_16x16x32_bf16 v[42:45], v[154:157], v[186:189], v[42:45]
	v_mfma_f32_16x16x32_bf16 v[30:33], v[138:141], v[194:197], v[30:33]
	v_mfma_f32_16x16x32_bf16 v[26:29], v[154:157], v[194:197], v[26:29]
	v_mfma_f32_16x16x32_bf16 v[14:17], v[138:141], v[202:205], v[14:17]
	v_mfma_f32_16x16x32_bf16 v[10:13], v[154:157], v[202:205], v[10:13]
	v_mfma_f32_16x16x32_bf16 v[62:65], v[144:147], v[182:185], v[62:65]
	v_mfma_f32_16x16x32_bf16 v[58:61], v[158:161], v[182:185], v[58:61]
	v_mfma_f32_16x16x32_bf16 v[46:49], v[144:147], v[190:193], v[46:49]
	v_mfma_f32_16x16x32_bf16 v[42:45], v[158:161], v[190:193], v[42:45]
	v_mfma_f32_16x16x32_bf16 v[30:33], v[144:147], v[198:201], v[30:33]
	v_mfma_f32_16x16x32_bf16 v[26:29], v[158:161], v[198:201], v[26:29]
	v_mfma_f32_16x16x32_bf16 v[14:17], v[144:147], v[224:227], v[14:17]
	v_mfma_f32_16x16x32_bf16 v[10:13], v[158:161], v[224:227], v[10:13]
	v_mfma_f32_16x16x32_bf16 v[54:57], v[162:165], v[178:181], v[54:57]
	v_mfma_f32_16x16x32_bf16 v[50:53], v[170:173], v[178:181], v[50:53]
	v_mfma_f32_16x16x32_bf16 v[38:41], v[162:165], v[186:189], v[38:41]
	v_mfma_f32_16x16x32_bf16 v[34:37], v[170:173], v[186:189], v[34:37]
	v_mfma_f32_16x16x32_bf16 v[22:25], v[162:165], v[194:197], v[22:25]
	v_mfma_f32_16x16x32_bf16 v[18:21], v[170:173], v[194:197], v[18:21]
	v_mfma_f32_16x16x32_bf16 v[6:9], v[162:165], v[202:205], v[6:9]
	v_mfma_f32_16x16x32_bf16 v[2:5], v[170:173], v[202:205], v[2:5]
	v_mfma_f32_16x16x32_bf16 v[54:57], v[166:169], v[182:185], v[54:57]
	v_mfma_f32_16x16x32_bf16 v[50:53], v[174:177], v[182:185], v[50:53]
	v_mfma_f32_16x16x32_bf16 v[38:41], v[166:169], v[190:193], v[38:41]
	v_mfma_f32_16x16x32_bf16 v[34:37], v[174:177], v[190:193], v[34:37]
	v_mfma_f32_16x16x32_bf16 v[22:25], v[166:169], v[198:201], v[22:25]
	v_mfma_f32_16x16x32_bf16 v[18:21], v[174:177], v[198:201], v[18:21]
	v_mfma_f32_16x16x32_bf16 v[6:9], v[166:169], v[224:227], v[6:9]
	v_mfma_f32_16x16x32_bf16 v[2:5], v[174:177], v[224:227], v[2:5]
	s_barrier
	s_setprio 0
	s_add_i32 s43, s43, 2
	s_add_u32 s41, s41, 0x100
	s_addc_u32 s42, s42, 0
	s_cmp_gt_u32 s43, 17
	s_mov_b64 s[10:11], s[12:13]
	s_cbranch_scc0 .LBB0_919
	v_lshl_add_u32 v140, s38, 8, v150
	v_lshl_or_b32 v141, s39, 8, v152
	v_mul_lo_u32 v138, v140, s83
	v_lshlrev_b32_e32 v139, 11, v140
	v_lshl_add_u32 v138, v141, 1, v138
	v_lshl_add_u32 v139, v141, 1, v139
	global_load_dwordx4 v[144:147], v138, s[72:73] nt
	global_load_dwordx4 v[156:159], v139, s[36:37]
	global_load_dwordx4 v[160:163], v138, s[72:73] offset:256 nt
	global_load_dwordx4 v[164:167], v139, s[36:37] offset:256
	v_add_u32_e32 v140, 0x1a000, v138
	v_add_u32_e32 v141, 0x8000, v139
	global_load_dwordx4 v[168:171], v140, s[72:73] nt
	global_load_dwordx4 v[172:175], v141, s[36:37]
	global_load_dwordx4 v[176:179], v140, s[72:73] offset:256 nt
	global_load_dwordx4 v[180:183], v141, s[36:37] offset:256
	v_add_u32_e32 v140, 0x34000, v138
	v_add_u32_e32 v141, 0x10000, v139
	global_load_dwordx4 v[184:187], v140, s[72:73] nt
	global_load_dwordx4 v[188:191], v141, s[36:37]
	global_load_dwordx4 v[192:195], v140, s[72:73] offset:256 nt
	global_load_dwordx4 v[196:199], v141, s[36:37] offset:256
	v_add_u32_e32 v140, 0x4e000, v138
	v_add_u32_e32 v141, 0x18000, v139
	global_load_dwordx4 v[200:203], v140, s[72:73] nt
	global_load_dwordx4 v[224:227], v141, s[36:37]
	global_load_dwordx4 v[228:231], v140, s[72:73] offset:256 nt
	global_load_dwordx4 v[232:235], v141, s[36:37] offset:256
	s_and_b64 vcc, exec, s[6:7]
	s_cbranch_vccz .LBB0_922
	s_barrier
; __device__ __forceinline__ float bflo(unsigned w) { return __uint_as_float(w << 16); }
; __device__ __forceinline__ float bfhi(unsigned w) { return __uint_as_float(w & 0xffff0000u); }
; __device__ __forceinline__ u32x4 pack8(const f32x4 a, const f32x4 b) { u32x4 w; w.x = cvt_pk_bf16(a[0], a[1]); w.y = cvt_pk_bf16(a[2], a[3]); w.z = cvt_pk_bf16(b[0], b[1]); w.w = cvt_pk_bf16(b[2], b[3]); return w; }
;     __device__ __forceinline__ void operator()(const f32x4 (&acc)[2][2][4][2], const Unit& u, int wr, int wc, int fr, int fq) const {
;         const int row0 = u.pm * 256 + wr * 64 + fr, col0 = u.pn * 256 + wc * 32 + 8 * fq;
; #pragma unroll
;         for (int ai = 0; ai < 2; ++ai)
; #pragma unroll
;             for (int m = 0; m < 4; ++m) {
;                 const int row = row0 + ai * 128 + m * 16;
; #pragma unroll
;                 for (int bj = 0; bj < 2; ++bj) {
;                     const int c = col0 + bj * 128;
;                     const u32x4 g = *(const u32x4*)(G + (size_t)row * P2W + c);
;                     const u32x4 t = *(const u32x4*)(T + (size_t)row * D + c);
;                     f32x4 o0 = acc[ai][bj][m][0], o1 = acc[ai][bj][m][1];
;                     o0[0] = o0[0] * bflo(g.x) + bflo(t.x); o0[1] = o0[1] * bfhi(g.x) + bfhi(t.x); o0[2] = o0[2] * bflo(g.y) + bflo(t.y); o0[3] = o0[3] * bfhi(g.y) + bfhi(t.y);
;                     o1[0] = o1[0] * bflo(g.z) + bflo(t.z); o1[1] = o1[1] * bfhi(g.z) + bfhi(t.z); o1[2] = o1[2] * bflo(g.w) + bflo(t.w); o1[3] = o1[3] * bfhi(g.w) + bfhi(t.w);
;                     *(u32x4*)(O + (size_t)row * D + c) = pack8(o0, o1);
.LBB0_922:
	s_waitcnt vmcnt(14)
	v_lshlrev_b32_e32 v148, 16, v144
	v_and_b32_e32 v149, 0xffff0000, v144
	v_lshlrev_b32_e32 v154, 16, v156
	v_and_b32_e32 v155, 0xffff0000, v156
	v_pk_fma_f32 v[126:127], v[126:127], v[148:149], v[154:155]
	v_lshlrev_b32_e32 v148, 16, v145
	v_and_b32_e32 v149, 0xffff0000, v145
	v_lshlrev_b32_e32 v154, 16, v157
	v_and_b32_e32 v155, 0xffff0000, v157
	v_pk_fma_f32 v[128:129], v[128:129], v[148:149], v[154:155]
	v_lshlrev_b32_e32 v148, 16, v146
	v_and_b32_e32 v149, 0xffff0000, v146
	v_lshlrev_b32_e32 v154, 16, v158
	v_and_b32_e32 v155, 0xffff0000, v158
	v_pk_fma_f32 v[122:123], v[122:123], v[148:149], v[154:155]
	v_lshlrev_b32_e32 v148, 16, v147
	v_and_b32_e32 v149, 0xffff0000, v147
	v_lshlrev_b32_e32 v154, 16, v159
	v_and_b32_e32 v155, 0xffff0000, v159
	v_pk_fma_f32 v[124:125], v[124:125], v[148:149], v[154:155]
	v_cvt_pk_bf16_f32 v144, v126, v127
	v_cvt_pk_bf16_f32 v145, v128, v129
	v_cvt_pk_bf16_f32 v146, v122, v123
	v_cvt_pk_bf16_f32 v147, v124, v125
	global_store_dwordx4 v139, v[144:147], s[84:85]
	s_waitcnt vmcnt(13)
	v_lshlrev_b32_e32 v148, 16, v160
	v_and_b32_e32 v149, 0xffff0000, v160
	v_lshlrev_b32_e32 v154, 16, v164
	v_and_b32_e32 v155, 0xffff0000, v164
	v_pk_fma_f32 v[118:119], v[118:119], v[148:149], v[154:155]
	v_lshlrev_b32_e32 v148, 16, v161
	v_and_b32_e32 v149, 0xffff0000, v161
	v_lshlrev_b32_e32 v154, 16, v165
	v_and_b32_e32 v155, 0xffff0000, v165
	v_pk_fma_f32 v[120:121], v[120:121], v[148:149], v[154:155]
	v_lshlrev_b32_e32 v148, 16, v162
	v_and_b32_e32 v149, 0xffff0000, v162
	v_lshlrev_b32_e32 v154, 16, v166
	v_and_b32_e32 v155, 0xffff0000, v166
	v_pk_fma_f32 v[114:115], v[114:115], v[148:149], v[154:155]
	v_lshlrev_b32_e32 v148, 16, v163
	v_and_b32_e32 v149, 0xffff0000, v163
	v_lshlrev_b32_e32 v154, 16, v167
	v_and_b32_e32 v155, 0xffff0000, v167
	v_pk_fma_f32 v[116:117], v[116:117], v[148:149], v[154:155]
	v_cvt_pk_bf16_f32 v160, v118, v119
	v_cvt_pk_bf16_f32 v161, v120, v121
	v_cvt_pk_bf16_f32 v162, v114, v115
	v_cvt_pk_bf16_f32 v163, v116, v117
	global_store_dwordx4 v139, v[160:163], s[84:85] offset:256
	s_nop 1
	v_add_u32_e32 v140, 0xd0000, v138
	v_add_u32_e32 v141, 0x40000, v139
	global_load_dwordx4 v[144:147], v140, s[72:73] nt
	global_load_dwordx4 v[156:159], v141, s[36:37]
	global_load_dwordx4 v[160:163], v140, s[72:73] offset:256 nt
	global_load_dwordx4 v[164:167], v141, s[36:37] offset:256
	v_add_u32_e32 v141, 0x8000, v139
	s_waitcnt vmcnt(16)
	v_lshlrev_b32_e32 v148, 16, v168
	v_and_b32_e32 v149, 0xffff0000, v168
	v_lshlrev_b32_e32 v154, 16, v172
	v_and_b32_e32 v155, 0xffff0000, v172
	v_pk_fma_f32 v[110:111], v[110:111], v[148:149], v[154:155]
	v_lshlrev_b32_e32 v148, 16, v169
	v_and_b32_e32 v149, 0xffff0000, v169
	v_lshlrev_b32_e32 v154, 16, v173
	v_and_b32_e32 v155, 0xffff0000, v173
	v_pk_fma_f32 v[112:113], v[112:113], v[148:149], v[154:155]
	v_lshlrev_b32_e32 v148, 16, v170
	v_and_b32_e32 v149, 0xffff0000, v170
	v_lshlrev_b32_e32 v154, 16, v174
	v_and_b32_e32 v155, 0xffff0000, v174
	v_pk_fma_f32 v[106:107], v[106:107], v[148:149], v[154:155]
	v_lshlrev_b32_e32 v148, 16, v171
	v_and_b32_e32 v149, 0xffff0000, v171
	v_lshlrev_b32_e32 v154, 16, v175
	v_and_b32_e32 v155, 0xffff0000, v175
	v_pk_fma_f32 v[108:109], v[108:109], v[148:149], v[154:155]
	v_cvt_pk_bf16_f32 v168, v110, v111
	v_cvt_pk_bf16_f32 v169, v112, v113
	v_cvt_pk_bf16_f32 v170, v106, v107
	v_cvt_pk_bf16_f32 v171, v108, v109
	global_store_dwordx4 v141, v[168:171], s[84:85]
	s_waitcnt vmcnt(15)
	v_lshlrev_b32_e32 v148, 16, v176
	v_and_b32_e32 v149, 0xffff0000, v176
	v_lshlrev_b32_e32 v154, 16, v180
	v_and_b32_e32 v155, 0xffff0000, v180
	v_pk_fma_f32 v[102:103], v[102:103], v[148:149], v[154:155]
	v_lshlrev_b32_e32 v148, 16, v177
	v_and_b32_e32 v149, 0xffff0000, v177
	v_lshlrev_b32_e32 v154, 16, v181
	v_and_b32_e32 v155, 0xffff0000, v181
	v_pk_fma_f32 v[104:105], v[104:105], v[148:149], v[154:155]
	v_lshlrev_b32_e32 v148, 16, v178
	v_and_b32_e32 v149, 0xffff0000, v178
	v_lshlrev_b32_e32 v154, 16, v182
	v_and_b32_e32 v155, 0xffff0000, v182
	v_pk_fma_f32 v[98:99], v[98:99], v[148:149], v[154:155]
	v_lshlrev_b32_e32 v148, 16, v179
	v_and_b32_e32 v149, 0xffff0000, v179
	v_lshlrev_b32_e32 v154, 16, v183
	v_and_b32_e32 v155, 0xffff0000, v183
	v_pk_fma_f32 v[100:101], v[100:101], v[148:149], v[154:155]
	v_cvt_pk_bf16_f32 v176, v102, v103
	v_cvt_pk_bf16_f32 v177, v104, v105
	v_cvt_pk_bf16_f32 v178, v98, v99
	v_cvt_pk_bf16_f32 v179, v100, v101
	global_store_dwordx4 v141, v[176:179], s[84:85] offset:256
	s_nop 1
	v_add_u32_e32 v140, 0xea000, v138
	v_add_u32_e32 v141, 0x48000, v139
	global_load_dwordx4 v[168:171], v140, s[72:73] nt
	global_load_dwordx4 v[172:175], v141, s[36:37]
	global_load_dwordx4 v[176:179], v140, s[72:73] offset:256 nt
	global_load_dwordx4 v[180:183], v141, s[36:37] offset:256
	v_add_u32_e32 v141, 0x10000, v139
	s_waitcnt vmcnt(18)
	v_lshlrev_b32_e32 v148, 16, v184
	v_and_b32_e32 v149, 0xffff0000, v184
	v_lshlrev_b32_e32 v154, 16, v188
	v_and_b32_e32 v155, 0xffff0000, v188
	v_pk_fma_f32 v[94:95], v[94:95], v[148:149], v[154:155]
	v_lshlrev_b32_e32 v148, 16, v185
	v_and_b32_e32 v149, 0xffff0000, v185
	v_lshlrev_b32_e32 v154, 16, v189
	v_and_b32_e32 v155, 0xffff0000, v189
	v_pk_fma_f32 v[96:97], v[96:97], v[148:149], v[154:155]
	v_lshlrev_b32_e32 v148, 16, v186
	v_and_b32_e32 v149, 0xffff0000, v186
	v_lshlrev_b32_e32 v154, 16, v190
	v_and_b32_e32 v155, 0xffff0000, v190
	v_pk_fma_f32 v[90:91], v[90:91], v[148:149], v[154:155]
	v_lshlrev_b32_e32 v148, 16, v187
	v_and_b32_e32 v149, 0xffff0000, v187
	v_lshlrev_b32_e32 v154, 16, v191
	v_and_b32_e32 v155, 0xffff0000, v191
	v_pk_fma_f32 v[92:93], v[92:93], v[148:149], v[154:155]
	v_cvt_pk_bf16_f32 v184, v94, v95
	v_cvt_pk_bf16_f32 v185, v96, v97
	v_cvt_pk_bf16_f32 v186, v90, v91
	v_cvt_pk_bf16_f32 v187, v92, v93
	global_store_dwordx4 v141, v[184:187], s[84:85]
	s_waitcnt vmcnt(17)
; __device__ __forceinline__ float bflo(unsigned w) { return __uint_as_float(w << 16); }
; __device__ __forceinline__ float bfhi(unsigned w) { return __uint_as_float(w & 0xffff0000u); }
; __device__ __forceinline__ u32x4 pack8(const f32x4 a, const f32x4 b) { u32x4 w; w.x = cvt_pk_bf16(a[0], a[1]); w.y = cvt_pk_bf16(a[2], a[3]); w.z = cvt_pk_bf16(b[0], b[1]); w.w = cvt_pk_bf16(b[2], b[3]); return w; }
;     __device__ __forceinline__ void operator()(const f32x4 (&acc)[2][2][4][2], const Unit& u, int wr, int wc, int fr, int fq) const {
;         const int row0 = u.pm * 256 + wr * 64 + fr, col0 = u.pn * 256 + wc * 32 + 8 * fq;
; #pragma unroll
;         for (int ai = 0; ai < 2; ++ai)
; #pragma unroll
;             for (int m = 0; m < 4; ++m) {
;                 const int row = row0 + ai * 128 + m * 16;
; #pragma unroll
;                 for (int bj = 0; bj < 2; ++bj) {
;                     const int c = col0 + bj * 128;
;                     const u32x4 g = *(const u32x4*)(G + (size_t)row * P2W + c);
;                     const u32x4 t = *(const u32x4*)(T + (size_t)row * D + c);
;                     f32x4 o0 = acc[ai][bj][m][0], o1 = acc[ai][bj][m][1];
;                     o0[0] = o0[0] * bflo(g.x) + bflo(t.x); o0[1] = o0[1] * bfhi(g.x) + bfhi(t.x); o0[2] = o0[2] * bflo(g.y) + bflo(t.y); o0[3] = o0[3] * bfhi(g.y) + bfhi(t.y);
;                     o1[0] = o1[0] * bflo(g.z) + bflo(t.z); o1[1] = o1[1] * bfhi(g.z) + bfhi(t.z); o1[2] = o1[2] * bflo(g.w) + bflo(t.w); o1[3] = o1[3] * bfhi(g.w) + bfhi(t.w);
;                     *(u32x4*)(O + (size_t)row * D + c) = pack8(o0, o1);
	v_lshlrev_b32_e32 v148, 16, v192
	v_and_b32_e32 v149, 0xffff0000, v192
	v_lshlrev_b32_e32 v154, 16, v196
	v_and_b32_e32 v155, 0xffff0000, v196
	v_pk_fma_f32 v[86:87], v[86:87], v[148:149], v[154:155]
	v_lshlrev_b32_e32 v148, 16, v193
	v_and_b32_e32 v149, 0xffff0000, v193
	v_lshlrev_b32_e32 v154, 16, v197
	v_and_b32_e32 v155, 0xffff0000, v197
	v_pk_fma_f32 v[88:89], v[88:89], v[148:149], v[154:155]
	v_lshlrev_b32_e32 v148, 16, v194
	v_and_b32_e32 v149, 0xffff0000, v194
	v_lshlrev_b32_e32 v154, 16, v198
	v_and_b32_e32 v155, 0xffff0000, v198
	v_pk_fma_f32 v[82:83], v[82:83], v[148:149], v[154:155]
	v_lshlrev_b32_e32 v148, 16, v195
	v_and_b32_e32 v149, 0xffff0000, v195
	v_lshlrev_b32_e32 v154, 16, v199
	v_and_b32_e32 v155, 0xffff0000, v199
	v_pk_fma_f32 v[84:85], v[84:85], v[148:149], v[154:155]
	v_cvt_pk_bf16_f32 v192, v86, v87
	v_cvt_pk_bf16_f32 v193, v88, v89
	v_cvt_pk_bf16_f32 v194, v82, v83
	v_cvt_pk_bf16_f32 v195, v84, v85
	global_store_dwordx4 v141, v[192:195], s[84:85] offset:256
	s_nop 1
	v_add_u32_e32 v140, 0x104000, v138
	v_add_u32_e32 v141, 0x50000, v139
	global_load_dwordx4 v[184:187], v140, s[72:73] nt
	global_load_dwordx4 v[188:191], v141, s[36:37]
	global_load_dwordx4 v[192:195], v140, s[72:73] offset:256 nt
	global_load_dwordx4 v[196:199], v141, s[36:37] offset:256
	v_add_u32_e32 v141, 0x18000, v139
	s_waitcnt vmcnt(20)
	v_lshlrev_b32_e32 v148, 16, v200
	v_and_b32_e32 v149, 0xffff0000, v200
	v_lshlrev_b32_e32 v154, 16, v224
	v_and_b32_e32 v155, 0xffff0000, v224
	v_pk_fma_f32 v[78:79], v[78:79], v[148:149], v[154:155]
	v_lshlrev_b32_e32 v148, 16, v201
	v_and_b32_e32 v149, 0xffff0000, v201
	v_lshlrev_b32_e32 v154, 16, v225
	v_and_b32_e32 v155, 0xffff0000, v225
	v_pk_fma_f32 v[80:81], v[80:81], v[148:149], v[154:155]
	v_lshlrev_b32_e32 v148, 16, v202
	v_and_b32_e32 v149, 0xffff0000, v202
	v_lshlrev_b32_e32 v154, 16, v226
	v_and_b32_e32 v155, 0xffff0000, v226
	v_pk_fma_f32 v[74:75], v[74:75], v[148:149], v[154:155]
	v_lshlrev_b32_e32 v148, 16, v203
	v_and_b32_e32 v149, 0xffff0000, v203
	v_lshlrev_b32_e32 v154, 16, v227
	v_and_b32_e32 v155, 0xffff0000, v227
	v_pk_fma_f32 v[76:77], v[76:77], v[148:149], v[154:155]
	v_cvt_pk_bf16_f32 v200, v78, v79
	v_cvt_pk_bf16_f32 v201, v80, v81
	v_cvt_pk_bf16_f32 v202, v74, v75
	v_cvt_pk_bf16_f32 v203, v76, v77
	global_store_dwordx4 v141, v[200:203], s[84:85]
	s_waitcnt vmcnt(19)
	v_lshlrev_b32_e32 v148, 16, v228
	v_and_b32_e32 v149, 0xffff0000, v228
	v_lshlrev_b32_e32 v154, 16, v232
	v_and_b32_e32 v155, 0xffff0000, v232
	v_pk_fma_f32 v[70:71], v[70:71], v[148:149], v[154:155]
	v_lshlrev_b32_e32 v148, 16, v229
	v_and_b32_e32 v149, 0xffff0000, v229
	v_lshlrev_b32_e32 v154, 16, v233
	v_and_b32_e32 v155, 0xffff0000, v233
	v_pk_fma_f32 v[72:73], v[72:73], v[148:149], v[154:155]
	v_lshlrev_b32_e32 v148, 16, v230
	v_and_b32_e32 v149, 0xffff0000, v230
	v_lshlrev_b32_e32 v154, 16, v234
	v_and_b32_e32 v155, 0xffff0000, v234
	v_pk_fma_f32 v[66:67], v[66:67], v[148:149], v[154:155]
	v_lshlrev_b32_e32 v148, 16, v231
	v_and_b32_e32 v149, 0xffff0000, v231
	v_lshlrev_b32_e32 v154, 16, v235
	v_and_b32_e32 v155, 0xffff0000, v235
	v_pk_fma_f32 v[68:69], v[68:69], v[148:149], v[154:155]
	v_cvt_pk_bf16_f32 v228, v70, v71
	v_cvt_pk_bf16_f32 v229, v72, v73
	v_cvt_pk_bf16_f32 v230, v66, v67
	v_cvt_pk_bf16_f32 v231, v68, v69
	global_store_dwordx4 v141, v[228:231], s[84:85] offset:256
	s_nop 1
	v_add_u32_e32 v140, 0x11e000, v138
	v_add_u32_e32 v141, 0x58000, v139
	global_load_dwordx4 v[200:203], v140, s[72:73] nt
	global_load_dwordx4 v[224:227], v141, s[36:37]
	global_load_dwordx4 v[228:231], v140, s[72:73] offset:256 nt
	global_load_dwordx4 v[232:235], v141, s[36:37] offset:256
	v_add_u32_e32 v141, 0x40000, v139
	s_waitcnt vmcnt(20)
	v_lshlrev_b32_e32 v148, 16, v144
	v_and_b32_e32 v149, 0xffff0000, v144
	v_lshlrev_b32_e32 v154, 16, v156
	v_and_b32_e32 v155, 0xffff0000, v156
	v_pk_fma_f32 v[62:63], v[62:63], v[148:149], v[154:155]
	v_lshlrev_b32_e32 v148, 16, v145
	v_and_b32_e32 v149, 0xffff0000, v145
	v_lshlrev_b32_e32 v154, 16, v157
	v_and_b32_e32 v155, 0xffff0000, v157
	v_pk_fma_f32 v[64:65], v[64:65], v[148:149], v[154:155]
	v_lshlrev_b32_e32 v148, 16, v146
	v_and_b32_e32 v149, 0xffff0000, v146
	v_lshlrev_b32_e32 v154, 16, v158
	v_and_b32_e32 v155, 0xffff0000, v158
	v_pk_fma_f32 v[58:59], v[58:59], v[148:149], v[154:155]
	v_lshlrev_b32_e32 v148, 16, v147
	v_and_b32_e32 v149, 0xffff0000, v147
	v_lshlrev_b32_e32 v154, 16, v159
	v_and_b32_e32 v155, 0xffff0000, v159
	v_pk_fma_f32 v[60:61], v[60:61], v[148:149], v[154:155]
	v_cvt_pk_bf16_f32 v144, v62, v63
	v_cvt_pk_bf16_f32 v145, v64, v65
	v_cvt_pk_bf16_f32 v146, v58, v59
	v_cvt_pk_bf16_f32 v147, v60, v61
	global_store_dwordx4 v141, v[144:147], s[84:85]
	s_waitcnt vmcnt(19)
	v_lshlrev_b32_e32 v148, 16, v160
	v_and_b32_e32 v149, 0xffff0000, v160
	v_lshlrev_b32_e32 v154, 16, v164
	v_and_b32_e32 v155, 0xffff0000, v164
	v_pk_fma_f32 v[54:55], v[54:55], v[148:149], v[154:155]
	v_lshlrev_b32_e32 v148, 16, v161
	v_and_b32_e32 v149, 0xffff0000, v161
	v_lshlrev_b32_e32 v154, 16, v165
	v_and_b32_e32 v155, 0xffff0000, v165
	v_pk_fma_f32 v[56:57], v[56:57], v[148:149], v[154:155]
	v_lshlrev_b32_e32 v148, 16, v162
	v_and_b32_e32 v149, 0xffff0000, v162
	v_lshlrev_b32_e32 v154, 16, v166
	v_and_b32_e32 v155, 0xffff0000, v166
	v_pk_fma_f32 v[50:51], v[50:51], v[148:149], v[154:155]
	v_lshlrev_b32_e32 v148, 16, v163
	v_and_b32_e32 v149, 0xffff0000, v163
	v_lshlrev_b32_e32 v154, 16, v167
	v_and_b32_e32 v155, 0xffff0000, v167
	v_pk_fma_f32 v[52:53], v[52:53], v[148:149], v[154:155]
	v_cvt_pk_bf16_f32 v160, v54, v55
	v_cvt_pk_bf16_f32 v161, v56, v57
	v_cvt_pk_bf16_f32 v162, v50, v51
	v_cvt_pk_bf16_f32 v163, v52, v53
	global_store_dwordx4 v141, v[160:163], s[84:85] offset:256
	v_add_u32_e32 v141, 0x48000, v139
	s_waitcnt vmcnt(16)
; #define PG8_BAR __builtin_amdgcn_s_barrier()
; __device__ __forceinline__ float bflo(unsigned w) { return __uint_as_float(w << 16); }
; __device__ __forceinline__ float bfhi(unsigned w) { return __uint_as_float(w & 0xffff0000u); }
; __device__ __forceinline__ u32x4 pack8(const f32x4 a, const f32x4 b) { u32x4 w; w.x = cvt_pk_bf16(a[0], a[1]); w.y = cvt_pk_bf16(a[2], a[3]); w.z = cvt_pk_bf16(b[0], b[1]); w.w = cvt_pk_bf16(b[2], b[3]); return w; }
; template <class Epi, class Sched, bool ALIGN_EPI = false, bool SP2 = false>
; __device__ __forceinline__ void gemm_phase(PG8_LAS unsigned char* lds, const Gemm g, const Sched& S, const Epi& E) {
;     ...
;         if constexpr (ALIGN_EPI) { if (wr == 0) PG8_BAR; }
;         if constexpr (!Epi::AFTER_DRAIN) { E(acc, cur, wr, wc, fr, fq); S.done(cur); }
;         if (!has_next) break;
;     __device__ __forceinline__ void operator()(const f32x4 (&acc)[2][2][4][2], const Unit& u, int wr, int wc, int fr, int fq) const {
;     ...
;                 const int row = row0 + ai * 128 + m * 16;
; #pragma unroll
;                 for (int bj = 0; bj < 2; ++bj) {
;                     const int c = col0 + bj * 128;
;                     const u32x4 g = *(const u32x4*)(G + (size_t)row * P2W + c);
;                     const u32x4 t = *(const u32x4*)(T + (size_t)row * D + c);
;                     f32x4 o0 = acc[ai][bj][m][0], o1 = acc[ai][bj][m][1];
;                     o0[0] = o0[0] * bflo(g.x) + bflo(t.x); o0[1] = o0[1] * bfhi(g.x) + bfhi(t.x); o0[2] = o0[2] * bflo(g.y) + bflo(t.y); o0[3] = o0[3] * bfhi(g.y) + bfhi(t.y);
;                     o1[0] = o1[0] * bflo(g.z) + bflo(t.z); o1[1] = o1[1] * bfhi(g.z) + bfhi(t.z); o1[2] = o1[2] * bflo(g.w) + bflo(t.w); o1[3] = o1[3] * bfhi(g.w) + bfhi(t.w);
;                     *(u32x4*)(O + (size_t)row * D + c) = pack8(o0, o1);
	v_lshlrev_b32_e32 v148, 16, v168
	v_and_b32_e32 v149, 0xffff0000, v168
	v_lshlrev_b32_e32 v154, 16, v172
	v_and_b32_e32 v155, 0xffff0000, v172
	v_pk_fma_f32 v[46:47], v[46:47], v[148:149], v[154:155]
	v_lshlrev_b32_e32 v148, 16, v169
	v_and_b32_e32 v149, 0xffff0000, v169
	v_lshlrev_b32_e32 v154, 16, v173
	v_and_b32_e32 v155, 0xffff0000, v173
	v_pk_fma_f32 v[48:49], v[48:49], v[148:149], v[154:155]
	v_lshlrev_b32_e32 v148, 16, v170
	v_and_b32_e32 v149, 0xffff0000, v170
	v_lshlrev_b32_e32 v154, 16, v174
	v_and_b32_e32 v155, 0xffff0000, v174
	v_pk_fma_f32 v[42:43], v[42:43], v[148:149], v[154:155]
	v_lshlrev_b32_e32 v148, 16, v171
	v_and_b32_e32 v149, 0xffff0000, v171
	v_lshlrev_b32_e32 v154, 16, v175
	v_and_b32_e32 v155, 0xffff0000, v175
	v_pk_fma_f32 v[44:45], v[44:45], v[148:149], v[154:155]
	v_cvt_pk_bf16_f32 v168, v46, v47
	v_cvt_pk_bf16_f32 v169, v48, v49
	v_cvt_pk_bf16_f32 v170, v42, v43
	v_cvt_pk_bf16_f32 v171, v44, v45
	global_store_dwordx4 v141, v[168:171], s[84:85]
	s_waitcnt vmcnt(15)
	v_lshlrev_b32_e32 v148, 16, v176
	v_and_b32_e32 v149, 0xffff0000, v176
	v_lshlrev_b32_e32 v154, 16, v180
	v_and_b32_e32 v155, 0xffff0000, v180
	v_pk_fma_f32 v[38:39], v[38:39], v[148:149], v[154:155]
	v_lshlrev_b32_e32 v148, 16, v177
	v_and_b32_e32 v149, 0xffff0000, v177
	v_lshlrev_b32_e32 v154, 16, v181
	v_and_b32_e32 v155, 0xffff0000, v181
	v_pk_fma_f32 v[40:41], v[40:41], v[148:149], v[154:155]
	v_lshlrev_b32_e32 v148, 16, v178
	v_and_b32_e32 v149, 0xffff0000, v178
	v_lshlrev_b32_e32 v154, 16, v182
	v_and_b32_e32 v155, 0xffff0000, v182
	v_pk_fma_f32 v[34:35], v[34:35], v[148:149], v[154:155]
	v_lshlrev_b32_e32 v148, 16, v179
	v_and_b32_e32 v149, 0xffff0000, v179
	v_lshlrev_b32_e32 v154, 16, v183
	v_and_b32_e32 v155, 0xffff0000, v183
	v_pk_fma_f32 v[36:37], v[36:37], v[148:149], v[154:155]
	v_cvt_pk_bf16_f32 v176, v38, v39
	v_cvt_pk_bf16_f32 v177, v40, v41
	v_cvt_pk_bf16_f32 v178, v34, v35
	v_cvt_pk_bf16_f32 v179, v36, v37
	global_store_dwordx4 v141, v[176:179], s[84:85] offset:256
	v_add_u32_e32 v141, 0x50000, v139
	s_waitcnt vmcnt(12)
	v_lshlrev_b32_e32 v148, 16, v184
	v_and_b32_e32 v149, 0xffff0000, v184
	v_lshlrev_b32_e32 v154, 16, v188
	v_and_b32_e32 v155, 0xffff0000, v188
	v_pk_fma_f32 v[30:31], v[30:31], v[148:149], v[154:155]
	v_lshlrev_b32_e32 v148, 16, v185
	v_and_b32_e32 v149, 0xffff0000, v185
	v_lshlrev_b32_e32 v154, 16, v189
	v_and_b32_e32 v155, 0xffff0000, v189
	v_pk_fma_f32 v[32:33], v[32:33], v[148:149], v[154:155]
	v_lshlrev_b32_e32 v148, 16, v186
	v_and_b32_e32 v149, 0xffff0000, v186
	v_lshlrev_b32_e32 v154, 16, v190
	v_and_b32_e32 v155, 0xffff0000, v190
	v_pk_fma_f32 v[26:27], v[26:27], v[148:149], v[154:155]
	v_lshlrev_b32_e32 v148, 16, v187
	v_and_b32_e32 v149, 0xffff0000, v187
	v_lshlrev_b32_e32 v154, 16, v191
	v_and_b32_e32 v155, 0xffff0000, v191
	v_pk_fma_f32 v[28:29], v[28:29], v[148:149], v[154:155]
	v_cvt_pk_bf16_f32 v184, v30, v31
	v_cvt_pk_bf16_f32 v185, v32, v33
	v_cvt_pk_bf16_f32 v186, v26, v27
	v_cvt_pk_bf16_f32 v187, v28, v29
	global_store_dwordx4 v141, v[184:187], s[84:85]
	s_waitcnt vmcnt(11)
	v_lshlrev_b32_e32 v148, 16, v192
	v_and_b32_e32 v149, 0xffff0000, v192
	v_lshlrev_b32_e32 v154, 16, v196
	v_and_b32_e32 v155, 0xffff0000, v196
	v_pk_fma_f32 v[22:23], v[22:23], v[148:149], v[154:155]
	v_lshlrev_b32_e32 v148, 16, v193
	v_and_b32_e32 v149, 0xffff0000, v193
	v_lshlrev_b32_e32 v154, 16, v197
	v_and_b32_e32 v155, 0xffff0000, v197
	v_pk_fma_f32 v[24:25], v[24:25], v[148:149], v[154:155]
	v_lshlrev_b32_e32 v148, 16, v194
	v_and_b32_e32 v149, 0xffff0000, v194
	v_lshlrev_b32_e32 v154, 16, v198
	v_and_b32_e32 v155, 0xffff0000, v198
	v_pk_fma_f32 v[18:19], v[18:19], v[148:149], v[154:155]
	v_lshlrev_b32_e32 v148, 16, v195
	v_and_b32_e32 v149, 0xffff0000, v195
	v_lshlrev_b32_e32 v154, 16, v199
	v_and_b32_e32 v155, 0xffff0000, v199
	v_pk_fma_f32 v[20:21], v[20:21], v[148:149], v[154:155]
	v_cvt_pk_bf16_f32 v192, v22, v23
	v_cvt_pk_bf16_f32 v193, v24, v25
	v_cvt_pk_bf16_f32 v194, v18, v19
	v_cvt_pk_bf16_f32 v195, v20, v21
	global_store_dwordx4 v141, v[192:195], s[84:85] offset:256
	v_add_u32_e32 v141, 0x58000, v139
	s_waitcnt vmcnt(8)
	v_lshlrev_b32_e32 v148, 16, v200
	v_and_b32_e32 v149, 0xffff0000, v200
	v_lshlrev_b32_e32 v154, 16, v224
	v_and_b32_e32 v155, 0xffff0000, v224
	v_pk_fma_f32 v[14:15], v[14:15], v[148:149], v[154:155]
	v_lshlrev_b32_e32 v148, 16, v201
	v_and_b32_e32 v149, 0xffff0000, v201
	v_lshlrev_b32_e32 v154, 16, v225
	v_and_b32_e32 v155, 0xffff0000, v225
	v_pk_fma_f32 v[16:17], v[16:17], v[148:149], v[154:155]
	v_lshlrev_b32_e32 v148, 16, v202
	v_and_b32_e32 v149, 0xffff0000, v202
	v_lshlrev_b32_e32 v154, 16, v226
	v_and_b32_e32 v155, 0xffff0000, v226
	v_pk_fma_f32 v[10:11], v[10:11], v[148:149], v[154:155]
	v_lshlrev_b32_e32 v148, 16, v203
	v_and_b32_e32 v149, 0xffff0000, v203
	v_lshlrev_b32_e32 v154, 16, v227
	v_and_b32_e32 v155, 0xffff0000, v227
	v_pk_fma_f32 v[12:13], v[12:13], v[148:149], v[154:155]
	v_cvt_pk_bf16_f32 v200, v14, v15
	v_cvt_pk_bf16_f32 v201, v16, v17
	v_cvt_pk_bf16_f32 v202, v10, v11
	v_cvt_pk_bf16_f32 v203, v12, v13
	global_store_dwordx4 v141, v[200:203], s[84:85]
	s_waitcnt vmcnt(7)
	v_lshlrev_b32_e32 v148, 16, v228
	v_and_b32_e32 v149, 0xffff0000, v228
	v_lshlrev_b32_e32 v154, 16, v232
	v_and_b32_e32 v155, 0xffff0000, v232
	v_pk_fma_f32 v[6:7], v[6:7], v[148:149], v[154:155]
	v_lshlrev_b32_e32 v148, 16, v229
	v_and_b32_e32 v149, 0xffff0000, v229
	v_lshlrev_b32_e32 v154, 16, v233
	v_and_b32_e32 v155, 0xffff0000, v233
	v_pk_fma_f32 v[8:9], v[8:9], v[148:149], v[154:155]
	v_lshlrev_b32_e32 v148, 16, v230
	v_and_b32_e32 v149, 0xffff0000, v230
	v_lshlrev_b32_e32 v154, 16, v234
	v_and_b32_e32 v155, 0xffff0000, v234
	v_pk_fma_f32 v[2:3], v[2:3], v[148:149], v[154:155]
	v_lshlrev_b32_e32 v148, 16, v231
	v_and_b32_e32 v149, 0xffff0000, v231
	v_lshlrev_b32_e32 v154, 16, v235
	v_and_b32_e32 v155, 0xffff0000, v235
	v_pk_fma_f32 v[4:5], v[4:5], v[148:149], v[154:155]
	v_cvt_pk_bf16_f32 v228, v6, v7
	v_cvt_pk_bf16_f32 v229, v8, v9
	v_cvt_pk_bf16_f32 v230, v2, v3
	v_cvt_pk_bf16_f32 v231, v4, v5
	global_store_dwordx4 v141, v[228:231], s[84:85] offset:256
	s_mov_b64 s[10:11], -1
	s_and_b64 vcc, exec, s[2:3]
	s_cbranch_vccnz .LBB0_907
	s_andn2_b64 vcc, exec, s[0:1]
	s_cbranch_vccnz .LBB0_906
	s_barrier
	s_branch .LBB0_906
